# k7: mixer chains C1 software-pipelined (all 3), hgrn state update batched, side-unit state loads after row loads, unit end waits moved
# speedup vs baseline: 1.0071x; 1.0071x over previous
; template <int TYPE>
; __device__ __forceinline__ void mix_sg_unit(Frame& F, int b, int h, int mode  , const float* rot) {
;     ...
;     f32x4 S[8]; f32x4 nacc = {0.f, 0.f, 0.f, 0.f}; float m0 = 0.f;
; #pragma unroll
;     for (int mt = 0; mt < 8; ++mt) S[mt] = (f32x4){0.f, 0.f, 0.f, 0.f};
;     if (!prompt) {
;         const float* Sin = (TYPE == 0 ? F.in[2] : F.in[5]) + (size_t)(b * 4 + h) * 16384;
; #pragma unroll
;         for (int mt = 0; mt < 8; ++mt)
; #pragma unroll
;             for (int r = 0; r < 4; ++r) S[mt][r] = __builtin_nontemporal_load(Sin + (16 * mt + 4 * q + r) * 128 + 16 * w + r16);
;         if (TYPE == 0) {
; #pragma unroll
;             for (int r = 0; r < 4; ++r) nacc[r] = F.in[3][(size_t)(b * 4 + h) * 128 + 16 * w + 4 * q + r];
;             m0 = F.in[4][b * 4 + h];
;         }
;     }
;     const float lgam = (TYPE != 1) ? 0.f : h == 0 ? -0.031748698314580298f : h == 1 ? -0.015748356968139168f : h == 2 ? -0.0078431774610258928f : -0.0039138993211363287f;
.LBB0_720:
	s_cmpk_lt_i32 s43, 0x400
	s_cselect_b64 s[0:1], -1, 0
	v_cndmask_b32_e64 v0, 0, 1, s[0:1]
	s_add_i32 s0, s43, 0xfffffc00
	s_lshr_b32 s34, s0, 2
	s_ashr_i32 s35, s43, 9
	s_cmpk_gt_i32 s43, 0x3ff
	s_cselect_b64 s[0:1], -1, 0
	s_and_b64 s[28:29], s[0:1], exec
	s_cselect_b32 s28, 3, 0x1ff
	s_cselect_b32 s29, s34, s35
	s_and_b32 s56, s28, s43
	s_cmp_lg_u32 s29, 0
	v_cmp_ne_u32_e64 s[28:29], 1, v0
	s_cbranch_scc0 .LBB0_726
	v_mov_b32_e32 v16, 0
	s_lshr_b32 s57, s56, 2
	s_and_b32 s58, s43, 3
	s_and_b64 vcc, exec, s[28:29]
	v_mov_b32_e32 v17, v16
	v_mov_b32_e32 v18, v16
	v_mov_b32_e32 v19, v16
	s_waitcnt vmcnt(1)
	v_mov_b32_e32 v12, v16
	v_mov_b32_e32 v13, v16
	v_mov_b32_e32 v14, v16
	v_mov_b32_e32 v15, v16
	v_mov_b32_e32 v20, v16
	v_mov_b32_e32 v21, v16
	v_mov_b32_e32 v22, v16
	v_mov_b32_e32 v23, v16
	v_mov_b32_e32 v24, v16
	v_mov_b32_e32 v25, v16
	v_mov_b32_e32 v26, v16
	v_mov_b32_e32 v27, v16
	v_mov_b32_e32 v36, v16
	v_mov_b32_e32 v37, v16
	v_mov_b32_e32 v38, v16
	v_mov_b32_e32 v39, v16
	v_mov_b32_e32 v28, v16
	v_mov_b32_e32 v29, v16
	v_mov_b32_e32 v30, v16
	v_mov_b32_e32 v31, v16
	v_mov_b32_e32 v32, v16
	v_mov_b32_e32 v33, v16
	v_mov_b32_e32 v34, v16
	v_mov_b32_e32 v35, v16
	v_mov_b32_e32 v40, v16
	v_mov_b32_e32 v41, v16
	v_mov_b32_e32 v42, v16
	v_mov_b32_e32 v43, v16
	s_cbranch_vccnz .LBB0_723
.LBB0_723:
	s_cmp_lt_i32 s58, 1
	v_mov_b32_e32 v0, 0xbd020aec
	s_cbranch_scc1 .LBB0_729
	s_cmp_eq_u32 s58, 1
	s_cbranch_scc1 .LBB0_727
	s_cmp_eq_u32 s58, 2
	s_cselect_b64 vcc, -1, 0
	v_cndmask_b32_e32 v0, v217, v218, vcc
	s_cbranch_execz .LBB0_728
	s_branch .LBB0_729

; template <int TYPE>
; __device__ __forceinline__ void mix_sg_unit(Frame& F, int b, int h, int mode  , const float* rot) {
;     ...
;     if (!prompt) {
;         const float* Sin = (TYPE == 0 ? F.in[2] : F.in[5]) + (size_t)(b * 4 + h) * 16384;
; #pragma unroll
;         for (int mt = 0; mt < 8; ++mt)
; #pragma unroll
;             for (int r = 0; r < 4; ++r) S[mt][r] = __builtin_nontemporal_load(Sin + (16 * mt + 4 * q + r) * 128 + 16 * w + r16);
;     ...
;     const int zvo = tk * 8192 + (qcol + 16 * p) * 2;
.LBB0_731:
	s_or_b64 exec, exec, s[34:35]
	s_lshl_b32 s34, s57, 15
	s_or_b32 s36, s34, 0x4000000
	s_and_b64 s[34:35], s[0:1], exec
	s_cselect_b32 s34, 0x4400000, s36
	s_lshl_b32 s34, s34, 1
	v_readlane_b32 s4, v252, 59
	v_readlane_b32 s8, v253, 37
	s_add_u32 s8, s4, s34
	v_readlane_b32 s4, v252, 60
	v_or_b32_e32 v1, s59, v64
	s_addc_u32 s37, s4, 0
	v_readlane_b32 s4, v254, 22
	v_lshl_or_b32 v1, v1, 1, v90
	v_readlane_b32 s9, v253, 38
	v_readlane_b32 s10, v253, 39
	s_and_b64 s[34:35], s[0:1], exec
	v_readlane_b32 s6, v254, 24
	v_readlane_b32 s11, v253, 40
	s_cselect_b32 s10, 0x20000, s6
	s_and_b32 s9, s37, 0xffff
	v_add_u32_e32 v1, 0x1000, v1
	s_nop 1
	buffer_load_dwordx4 v[4:7], v1, s[8:11], 0 offen
	buffer_load_dwordx4 v[8:11], v1, s[8:11], 0 offen offset:16
	buffer_load_dwordx4 v[44:47], v1, s[8:11], 0 offen offset:1024
	buffer_load_dwordx4 v[48:51], v1, s[8:11], 0 offen offset:1040
	buffer_load_dwordx4 v[52:55], v1, s[8:11], 0 offen offset:2048
	buffer_load_dwordx4 v[56:59], v1, s[8:11], 0 offen offset:2064
	s_cmpk_lt_i32 s43, 0x400
	s_cbranch_scc0 .Lsur_noload
	s_lshl_b32 s98, s58, 16
	s_lshl_b32 s99, s57, 18
	s_or_b32 s98, s99, s98
	s_mov_b32 s99, 0
	v_lshl_add_u64 v[126:127], v[72:73], 0, s[98:99]
	s_mov_b32 s98, 0x2000
	global_load_dword v16, v[126:127], off nt
	global_load_dword v17, v[126:127], off offset:512 nt
	global_load_dword v18, v[126:127], off offset:1024 nt
	global_load_dword v19, v[126:127], off offset:1536 nt
	v_lshl_add_u64 v[126:127], v[126:127], 0, s[98:99]
	global_load_dword v12, v[126:127], off nt
	global_load_dword v13, v[126:127], off offset:512 nt
	global_load_dword v14, v[126:127], off offset:1024 nt
	global_load_dword v15, v[126:127], off offset:1536 nt
	v_lshl_add_u64 v[126:127], v[126:127], 0, s[98:99]
	global_load_dword v20, v[126:127], off nt
	global_load_dword v21, v[126:127], off offset:512 nt
	global_load_dword v22, v[126:127], off offset:1024 nt
	global_load_dword v23, v[126:127], off offset:1536 nt
	v_lshl_add_u64 v[126:127], v[126:127], 0, s[98:99]
	global_load_dword v24, v[126:127], off nt
	global_load_dword v25, v[126:127], off offset:512 nt
	global_load_dword v26, v[126:127], off offset:1024 nt
	global_load_dword v27, v[126:127], off offset:1536 nt
	v_lshl_add_u64 v[126:127], v[126:127], 0, s[98:99]
	global_load_dword v36, v[126:127], off nt
	global_load_dword v37, v[126:127], off offset:512 nt
	global_load_dword v38, v[126:127], off offset:1024 nt
	global_load_dword v39, v[126:127], off offset:1536 nt
	v_lshl_add_u64 v[126:127], v[126:127], 0, s[98:99]
	global_load_dword v28, v[126:127], off nt
	global_load_dword v29, v[126:127], off offset:512 nt
	global_load_dword v30, v[126:127], off offset:1024 nt
	global_load_dword v31, v[126:127], off offset:1536 nt
	v_lshl_add_u64 v[126:127], v[126:127], 0, s[98:99]
	global_load_dword v32, v[126:127], off nt
	global_load_dword v33, v[126:127], off offset:512 nt
	global_load_dword v34, v[126:127], off offset:1024 nt
	global_load_dword v35, v[126:127], off offset:1536 nt
	v_lshl_add_u64 v[126:127], v[126:127], 0, s[98:99]
	global_load_dword v40, v[126:127], off nt
	global_load_dword v41, v[126:127], off offset:512 nt
	global_load_dword v42, v[126:127], off offset:1024 nt
	global_load_dword v43, v[126:127], off offset:1536 nt
	s_branch .Lsur_loaded

; #define LAS __attribute__((address_space(3)))
; __device__ __forceinline__ float logsigmoidf_(float x) { return fminf(x, 0.f) - __logf(1.f + __expf(-fabsf(x))); }
; template <int TYPE>
; __device__ __forceinline__ void mix_sg_unit(Frame& F, int b, int h, int mode  , const float* rot) {
;     ...
;             *(LAS u32x4*)(L + MX_V + tk * MX_PITCH + 32 * p) = pa[4]; *(LAS u32x4*)(L + MX_V + tk * MX_PITCH + 32 * p + 16) = pa[5];
;             {
;                 const int c0 = (MX_POS4(16 * p)) * 2;
; #pragma unroll
;                 for (int g = 0; g < 4; ++g) {
;                     *(LAS u32x2*)(L + MX_Q + tk * MX_PITCH + c0 + 16 * g) = (u32x2){pa[g >> 1][2 * (g & 1)], pa[g >> 1][2 * (g & 1) + 1]};
;                     *(LAS u32x2*)(L + MX_K + tk * MX_PITCH + c0 + 16 * g) = (u32x2){pa[2 + (g >> 1)][2 * (g & 1)], pa[2 + (g >> 1)][2 * (g & 1) + 1]};
;                 }
;             }
;         }
;         if (w == 0) {
;             const bool valid = lane < ntok;
;             float li = -1e30f, lf = 0.f;
;             if (TYPE == 0) { if (valid) { li = pli + bias_i; lf = logsigmoidf_(plf + bias_f); } } else { if (valid) { li = 0.f; lf = lgam; } }
;             const float bb = row_prefix_sum(lf);
;             const float y = li - bb;
;             const float am = row_prefix_max(y);
;             const float a = bb + am;
;             const float B0 = rdlane(bb, 15), B1 = rdlane(bb, 31), B2 = rdlane(bb, 47), B3 = rdlane(bb, 63);
;             float M1 = 0.f, M2 = 0.f, M3 = 0.f, M4 = 0.f;
;             if (TYPE == 0) { const float A0 = rdlane(a, 15), A1 = rdlane(a, 31), A2 = rdlane(a, 47), A3 = rdlane(a, 63);
;                 M1 = fmaxf(B0 + m0, A0); M2 = fmaxf(B1 + M1, A1); M3 = fmaxf(B2 + M2, A2); M4 = fmaxf(B3 + M3, A3); }
;             const float m0q = q == 0 ? m0 : q == 1 ? M1 : q == 2 ? M2 : M3;
;             const float mnq = q == 0 ? M1 : q == 1 ? M2 : q == 2 ? M3 : M4;
;             const float b15 = q == 0 ? B0 : q == 1 ? B1 : q == 2 ? B2 : B3;
;             const float m = (TYPE == 0) ? fmaxf(bb + m0q, a) : 0.f;
;             SC[lane] = bb - m; SC[64 + lane] = y + LNKS; SC[128 + lane] = __expf(bb + m0q - m);
;             SC[192 + lane] = __expf(y + LNKS + b15 - mnq); SC[256 + lane] = __expf(-m);
;             if (r16 == 0) SC[320 + q] = __expf(b15 + m0q - mnq);
;             m0 = (nmc == 4) ? M4 : M1;
;         }
.Lsur_loaded:
	v_add_u32_e32 v2, v91, v66
	v_readlane_b32 s7, v254, 25
	s_and_b64 s[34:35], s[0:1], exec
	s_mov_b32 s7, s11
	s_cselect_b32 s60, 16, 8
	s_andn2_b64 vcc, exec, s[50:51]
	v_readlane_b32 s5, v254, 23
	s_waitcnt vmcnt(33)
	ds_write_b128 v2, v[52:55] offset:52224
	s_waitcnt vmcnt(32)
	ds_write_b128 v2, v[56:59] offset:52240
	v_add_u32_e32 v2, v91, v92
	ds_write2_b64 v2, v[4:5], v[6:7] offset1:2
	v_add_u32_e32 v4, 0x4000, v2
	ds_write2_b64 v4, v[44:45], v[46:47] offset0:128 offset1:130
	ds_write2_b64 v2, v[8:9], v[10:11] offset0:4 offset1:6
	ds_write2_b64 v4, v[48:49], v[50:51] offset0:132 offset1:134
	s_cbranch_vccnz .LBB0_735
	v_cmp_gt_u32_e32 vcc, s60, v190
	s_nop 1
	v_cndmask_b32_e32 v0, 0, v0, vcc
	v_cndmask_b32_e64 v2, v219, 0, vcc
	s_nop 0
	v_add_f32_dpp v0, v0, v0 row_shr:1 row_mask:0xf bank_mask:0xf bound_ctrl:1
	s_nop 1
	v_add_f32_dpp v0, v0, v0 row_shr:2 row_mask:0xf bank_mask:0xf bound_ctrl:1
	s_nop 1
	v_add_f32_dpp v0, v0, v0 row_shr:4 row_mask:0xf bank_mask:0xf bound_ctrl:1
	s_nop 1
	v_add_f32_dpp v4, v0, v0 row_shr:8 row_mask:0xf bank_mask:0xf bound_ctrl:1
	v_sub_f32_e32 v2, v2, v4
	v_readlane_b32 s36, v4, 47
	v_readlane_b32 s37, v4, 63
	v_readlane_b32 s35, v4, 31
	v_mov_b32_e32 v5, s36
	v_mov_b32_e32 v0, s37
	v_readlane_b32 s34, v4, 15
	v_cndmask_b32_e64 v0, v0, v5, s[84:85]
	v_mov_b32_e32 v5, s35
	v_cndmask_b32_e64 v0, v0, v5, s[96:97]
	v_mov_b32_e32 v5, s34
	v_cndmask_b32_e64 v0, v0, v5, s[20:21]
	v_add_f32_e32 v2, 0xc01b43d5, v2
	ds_write2st64_b32 v104, v4, v2 offset1:1
	v_add_f32_e32 v4, 0, v4
	v_add_f32_e32 v2, v2, v0
	v_mul_f32_e32 v4, 0x3fb8aa3b, v4
	v_mul_f32_e32 v2, 0x3fb8aa3b, v2
	v_exp_f32_e32 v4, v4
	v_exp_f32_e32 v2, v2
	ds_write2st64_b32 v104, v4, v2 offset0:2 offset1:3
	ds_write_b32 v104, v212 offset:1024
	s_and_saveexec_b64 s[34:35], s[72:73]
	s_cbranch_execz .LBB0_734
	v_add_f32_e32 v0, 0, v0
	v_mul_f32_e32 v0, 0x3fb8aa3b, v0
	v_exp_f32_e32 v0, v0
	ds_write_b32 v105, v0 offset:1280

; #define LAS __attribute__((address_space(3)))
; template <int TYPE, int NMC>
; __device__ __forceinline__ void sg_chain(LAS unsigned char* L, LAS float* SC, f32x4 (&S)[8], f32x4& nacc, int w, int r16, int q) {
;     ...
;         {
;             const LAS unsigned char* Qb = L + MX_Q + 16 * mc * MX_PITCH; const LAS unsigned char* Kb = L + MX_K + 16 * mc * MX_PITCH; const LAS unsigned char* Vb = L + MX_V + 16 * mc * MX_PITCH;
;             f32x4 g0 = {0.f, 0.f, 0.f, 0.f}, g1 = {0.f, 0.f, 0.f, 0.f};
; #pragma unroll
;             for (int ks = 0; ks < 4; ++ks) {
;                 const bf16x8 kf = ld8(Kb + r16 * MX_PITCH + (32 * ks + 8 * q) * 2), qf = ld8(Qb + r16 * MX_PITCH + (32 * ks + 8 * q) * 2);
;                 if (ks & 1) g1 = MFMA16(kf, qf, g1); else g0 = MFMA16(kf, qf, g0);
;             }
;             const f32x4 g = g0 + g1;
;             const float xi = SC[mc * 16 + r16]; const f32x4 y4 = *(const LAS f32x4*)(SC + 64 + mc * 16 + 4 * q);
;             f32x4 P;
; #pragma unroll
;             for (int r = 0; r < 4; ++r) P[r] = (4 * q + r <= r16) ? g[r] * __expf(xi + y4[r]) : 0.f;
;             if (TYPE == 0) { float ps = (P[0] + P[1]) + (P[2] + P[3]); ps += __shfl_xor(ps, 16); ps += __shfl_xor(ps, 32); if (w == 0 && q == 0) DI[16 * mc + r16] = ps; }
;             const u32x2 vt = tr16(Vb + (4 * q + (r16 >> 2)) * MX_PITCH + (16 * w + 4 * (r16 & 3)) * 2);
;             oo[mc] = mfma16k16((u32x2){pkbf(P[0], P[1]), pkbf(P[2], P[3])}, vt, oo[mc]);
;         }
;         if (mc == 1 || TYPE == 1) __builtin_amdgcn_sched_barrier(0);
;     }
; #pragma unroll
;     for (int mc = 0; mc < NMC; ++mc) {
;         {
;             const LAS unsigned char* Qb = L + MX_Q + 16 * mc * MX_PITCH; const LAS unsigned char* Kb = L + MX_K + 16 * mc * MX_PITCH;
;             const u32x2 vt = tr16(L + MX_V + 16 * mc * MX_PITCH + (4 * q + (r16 >> 2)) * MX_PITCH + (16 * w + 4 * (r16 & 3)) * 2);
;             f32x4 o2a = {0.f, 0.f, 0.f, 0.f}, o2b = {0.f, 0.f, 0.f, 0.f};
; #pragma unroll
;             for (int ks = 0; ks < 4; ++ks) {
; template <int TYPE>
; __device__ __forceinline__ void mix_sg_unit(Frame& F, int b, int h, int mode  , const float* rot) {
;     ...
;         __syncthreads();
;         MSTAMP(2);
;         if (sc + 1 < nsc) SG_LOAD(sc + 1);
;         { const __amdgpu_buffer_rsrc_t rz = Z_RSRC(ZROW(F, row0, 0), ntok); pg[0] = Z_LD(rz, zvo + 3072); pg[1] = Z_LD(rz, zvo + 3088); }
.LBB0_735:
	s_lshl_b32 s34, s57, 3
	s_or_b32 s36, s34, 0x4000
	s_and_b64 s[34:35], s[0:1], exec
	s_cselect_b32 s61, 0x4400, s36
	s_lshl_b32 s34, s61, 13
	v_readlane_b32 s4, v252, 59
	s_add_u32 s8, s4, s34
	v_readlane_b32 s4, v252, 60
	s_addc_u32 s34, s4, 0
	s_mov_b32 s11, s7
	s_lshl_b32 s10, s60, 13
	s_and_b32 s9, s34, 0xffff
	s_waitcnt lgkmcnt(0)
	s_barrier
	buffer_load_dwordx4 v[8:11], v1, s[8:11], 0 offen offset:3072
	buffer_load_dwordx4 v[4:7], v1, s[8:11], 0 offen offset:3088
	v_add_u32_e32 v76, v94, v95
	ds_read_b32 v2, v106
	ds_read_b128 v[44:47], v76
	ds_read_b128 v[48:51], v76 offset:17408
	s_waitcnt lgkmcnt(0)
	v_mfma_f32_16x16x32_bf16 v[44:47], v[48:51], v[44:47], 0
	ds_read_b128 v[48:51], v76 offset:64
	ds_read_b128 v[52:55], v76 offset:17472
	v_writelane_b32 v253, s4, 37
	s_waitcnt lgkmcnt(0)
	v_mfma_f32_16x16x32_bf16 v[48:51], v[52:55], v[48:51], 0
	ds_read_b128 v[52:55], v76 offset:128
	ds_read_b128 v[56:59], v76 offset:17536
	v_writelane_b32 v253, s5, 38
	v_writelane_b32 v253, s6, 39
	s_waitcnt lgkmcnt(0)
	v_mfma_f32_16x16x32_bf16 v[44:47], v[56:59], v[52:55], v[44:47]
	ds_read_b128 v[52:55], v76 offset:192
	ds_read_b128 v[56:59], v76 offset:17600
	v_writelane_b32 v253, s7, 40
	s_waitcnt lgkmcnt(0)
	v_mfma_f32_16x16x32_bf16 v[48:51], v[56:59], v[52:55], v[48:51]
	s_nop 7
	v_pk_add_f32 v[0:1], v[46:47], v[50:51]
	v_pk_add_f32 v[48:49], v[44:45], v[48:49]
	ds_read_b128 v[44:47], v107
	s_waitcnt lgkmcnt(0)
	v_add_f32_e32 v46, v2, v46
	v_mul_f32_e32 v46, 0x3fb8aa3b, v46
	v_exp_f32_e32 v46, v46
	v_add_f32_e32 v44, v2, v44
	v_add_f32_e32 v45, v2, v45
	v_mul_f32_e32 v44, 0x3fb8aa3b, v44
	v_mul_f32_e32 v0, v0, v46
	v_cndmask_b32_e64 v77, v0, 0, s[68:69]
	v_add_f32_e32 v0, v2, v47
	v_mul_f32_e32 v0, 0x3fb8aa3b, v0
	v_exp_f32_e32 v0, v0
	v_mul_f32_e32 v45, 0x3fb8aa3b, v45
	v_exp_f32_e32 v44, v44
	v_exp_f32_e32 v45, v45
	v_mul_f32_e32 v0, v1, v0
	v_cndmask_b32_e64 v78, v0, 0, s[70:71]
	v_add_u32_e32 v0, v97, v98
	ds_read_b64_tr_b16 v[0:1], v0 offset:52224
	v_mul_f32_e32 v44, v48, v44
	v_mul_f32_e32 v45, v49, v45
	v_cndmask_b32_e64 v44, v44, 0, s[64:65]
	v_cndmask_b32_e64 v45, 0, v45, s[66:67]
	v_add_u32_e32 v2, v96, v99
	ds_read_b64_tr_b16 v[46:47], v2 offset:52224
	ds_read_b128 v[52:55], v76
	ds_read_b128 v[56:59], v76 offset:64
	ds_read_b128 v[60:63], v76 offset:128
	s_waitcnt vmcnt(2)
	v_cvt_pk_bf16_f32 v48, v16, v17
	v_cvt_pk_bf16_f32 v49, v18, v19
	v_cvt_pk_bf16_f32 v50, v12, v13
	v_cvt_pk_bf16_f32 v51, v14, v15
	v_mov_b32_e32 v2, v3
	s_waitcnt lgkmcnt(2)
	v_mfma_f32_16x16x32_bf16 v[48:51], v[52:55], v[48:51], 0
	v_cvt_pk_bf16_f32 v52, v20, v21
	v_cvt_pk_bf16_f32 v53, v22, v23
	v_cvt_pk_bf16_f32 v54, v24, v25
	v_cvt_pk_bf16_f32 v55, v26, v27
	s_waitcnt lgkmcnt(1)
	s_nop 0
	v_mfma_f32_16x16x32_bf16 v[52:55], v[56:59], v[52:55], 0
	v_cvt_pk_bf16_f32 v56, v36, v37
	v_cvt_pk_bf16_f32 v57, v38, v39
	v_cvt_pk_bf16_f32 v58, v28, v29
	v_cvt_pk_bf16_f32 v59, v30, v31
	s_waitcnt lgkmcnt(0)
	s_nop 0
	v_mfma_f32_16x16x32_bf16 v[48:51], v[60:63], v[56:59], v[48:51]
	ds_read_b128 v[60:63], v76 offset:192
	v_cvt_pk_bf16_f32 v56, v32, v33
	v_cvt_pk_bf16_f32 v57, v34, v35
	v_cvt_pk_bf16_f32 v58, v40, v41
	v_cvt_pk_bf16_f32 v59, v42, v43
	s_waitcnt lgkmcnt(0)
	s_nop 0
	v_mfma_f32_16x16x32_bf16 v[52:55], v[60:63], v[56:59], v[52:55]
	v_cvt_pk_bf16_f32 v57, v77, v78
	v_cvt_pk_bf16_f32 v56, v44, v45
	v_mov_b32_e32 v58, v3
	v_mov_b32_e32 v59, v3
	ds_read_b128 v[60:63], v109
	s_nop 2
	v_pk_add_f32 v[52:53], v[48:49], v[52:53]
	v_mfma_f32_16x16x32_bf16 v[56:59], v[56:59], v[0:3], 0
	v_add_f32_e64 v0, v50, v54
	v_add_f32_e64 v1, v51, v55
	ds_read_b128 v[48:51], v108
	v_add_u32_e32 v45, v101, v102
	v_mov_b32_e32 v2, s62
	s_waitcnt lgkmcnt(1)
	s_nop 1
	v_fma_f32 v0, v0, v62, v58
	v_fmac_f32_e32 v59, v1, v63
	v_add_u32_e32 v1, 0x400, v45
	ds_read_b32 v44, v2
	v_fma_f32 v2, v52, v60, v56
	v_fma_f32 v52, v53, v61, v57
	ds_write2_b32 v1, v0, v59 offset0:8 offset1:140
	v_lshlrev_b32_e32 v0, 16, v46
	v_and_b32_e32 v1, 0xffff0000, v46
	v_lshlrev_b32_e32 v46, 16, v47
	v_and_b32_e32 v47, 0xffff0000, v47
	ds_write2_b32 v45, v2, v52 offset1:132
	s_waitcnt lgkmcnt(3)
	v_pk_mul_f32 v[0:1], v[48:49], v[0:1]
	v_pk_mul_f32 v[46:47], v[50:51], v[46:47]
	v_add_u32_e32 v45, v96, v100
	v_mov_b32_e32 v48, v3
	v_mov_b32_e32 v49, v3
	v_cvt_pk_bf16_f32 v0, v0, v1
	v_cvt_pk_bf16_f32 v1, v46, v47
	ds_read_b64_tr_b16 v[46:47], v45 offset:17408
	ds_read_b64_tr_b16 v[50:51], v45 offset:17416
	v_mov_b32_e32 v2, v3
	s_waitcnt lgkmcnt(4)
	v_pk_mul_f32 v[18:19], v[18:19], v[44:45] op_sel_hi:[1,0]
	v_pk_mul_f32 v[16:17], v[16:17], v[44:45] op_sel_hi:[1,0]
	v_pk_mul_f32 v[22:23], v[22:23], v[44:45] op_sel_hi:[1,0]
	v_pk_mul_f32 v[20:21], v[20:21], v[44:45] op_sel_hi:[1,0]
	s_waitcnt lgkmcnt(1)
	v_mfma_f32_16x16x32_bf16 v[16:19], v[46:49], v[0:3], v[16:19]
	ds_read_b64_tr_b16 v[46:47], v45 offset:17472
	v_pk_mul_f32 v[26:27], v[26:27], v[44:45] op_sel_hi:[1,0]
	v_pk_mul_f32 v[24:25], v[24:25], v[44:45] op_sel_hi:[1,0]
	s_waitcnt lgkmcnt(0)
	v_mfma_f32_16x16x32_bf16 v[20:23], v[46:49], v[0:3], v[20:23]
	ds_read_b64_tr_b16 v[46:47], v45 offset:17480
	v_pk_mul_f32 v[38:39], v[38:39], v[44:45] op_sel_hi:[1,0]
	v_pk_mul_f32 v[36:37], v[36:37], v[44:45] op_sel_hi:[1,0]
	s_waitcnt lgkmcnt(0)
	v_mfma_f32_16x16x32_bf16 v[24:27], v[46:49], v[0:3], v[24:27]
	ds_read_b64_tr_b16 v[46:47], v45 offset:17536
	v_pk_mul_f32 v[30:31], v[30:31], v[44:45] op_sel_hi:[1,0]
	v_pk_mul_f32 v[28:29], v[28:29], v[44:45] op_sel_hi:[1,0]
	s_waitcnt lgkmcnt(0)
	v_mfma_f32_16x16x32_bf16 v[36:39], v[46:49], v[0:3], v[36:39]
	ds_read_b64_tr_b16 v[46:47], v45 offset:17544
	v_pk_mul_f32 v[34:35], v[34:35], v[44:45] op_sel_hi:[1,0]
	v_pk_mul_f32 v[32:33], v[32:33], v[44:45] op_sel_hi:[1,0]
	s_waitcnt lgkmcnt(0)
	v_mfma_f32_16x16x32_bf16 v[28:31], v[46:49], v[0:3], v[28:31]
	ds_read_b64_tr_b16 v[46:47], v45 offset:17600
	v_mov_b32_e32 v52, v3
	v_mov_b32_e32 v53, v3
	s_waitcnt lgkmcnt(0)
	v_mfma_f32_16x16x32_bf16 v[32:35], v[46:49], v[0:3], v[32:35]
	ds_read_b64_tr_b16 v[46:47], v45 offset:17608
	v_pk_mul_f32 v[14:15], v[14:15], v[44:45] op_sel_hi:[1,0]
	v_pk_mul_f32 v[12:13], v[12:13], v[44:45] op_sel_hi:[1,0]
	v_pk_mul_f32 v[42:43], v[42:43], v[44:45] op_sel_hi:[1,0]
	v_pk_mul_f32 v[40:41], v[40:41], v[44:45] op_sel_hi:[1,0]
	v_mfma_f32_16x16x32_bf16 v[12:15], v[50:53], v[0:3], v[12:15]
	s_waitcnt lgkmcnt(0)
	s_barrier
; #define LAS __attribute__((address_space(3)))
; #define MSTAMP(id) do { if (blockIdx.x == PROBE_BLOCK && tid == 0) { const unsigned long long t_now_ = __builtin_amdgcn_s_memrealtime(); volatile LAS unsigned long long* a_ = (volatile LAS unsigned long long*)(F.lds + 139264 + 128) + 48 + (id); *a_ = *a_ + (t_now_ - t_last_); t_last_ = t_now_; } } while (0)
; #define MSTAMP(id) do { } while (0)
; template <int TYPE>
; __device__ __forceinline__ void mix_sg_unit(Frame& F, int b, int h, int mode  , const float* rot) {
;     ...
;         __syncthreads();
;         MSTAMP(6);
;         {
;             const bool valid = tk < ntok; const int row = row0 + (valid ? tk : 0);
;             f32x4 o[4];
; #pragma unroll
;             for (int c = 0; c < 4; ++c) o[c] = *(const LAS f32x4*)(OB + tk * MX_OP + 16 * p + 4 * c);
;             if (tk >= 16 * nmc) {
; #pragma unroll
;                 for (int c = 0; c < 4; ++c) o[c] = (f32x4){0.f, 0.f, 0.f, 0.f}; }
	s_waitcnt vmcnt(0)
	v_mfma_f32_16x16x32_bf16 v[40:43], v[46:49], v[0:3], v[40:43]
	ds_read_b128 v[56:59], v93
	ds_read_b128 v[52:55], v93 offset:16
	ds_read_b128 v[48:51], v93 offset:32
	ds_read_b128 v[44:47], v93 offset:48
	s_and_saveexec_b64 s[34:35], s[24:25]
	s_cbranch_execz .LBB0_737
	s_waitcnt lgkmcnt(2)
	v_mov_b32_e32 v52, 0
	v_mov_b32_e32 v53, v52
	v_mov_b32_e32 v54, v52
	v_mov_b32_e32 v55, v52
	v_mov_b32_e32 v56, v52
	v_mov_b32_e32 v57, v52
	v_mov_b32_e32 v58, v52
	v_mov_b32_e32 v59, v52
	s_waitcnt lgkmcnt(1)
	v_mov_b32_e32 v48, v52
	v_mov_b32_e32 v49, v52
	v_mov_b32_e32 v50, v52
	v_mov_b32_e32 v51, v52
	s_waitcnt lgkmcnt(0)
	v_mov_b32_e32 v44, v52
	v_mov_b32_e32 v45, v52
	v_mov_b32_e32 v46, v52
	v_mov_b32_e32 v47, v52

; template <int TYPE>
; __device__ __forceinline__ void mix_sg_unit(Frame& F, int b, int h, int mode  , const float* rot) {
;     ...
;     __syncthreads();
;     if (mode != 2) {
;         int l2 = F.lane; asm volatile("" : "+v"(l2)); const int r16 = l2 & 15, q = l2 >> 4;
;         float* So = F.out + (TYPE == 0 ? (prompt ? O_CP : O_CS) : (prompt ? O_RP : O_RS)) + (size_t)(b * 4 + h) * 16384;
; #pragma unroll
;         for (int mt = 0; mt < 8; ++mt)
; #pragma unroll
;             for (int r = 0; r < 4; ++r) __builtin_nontemporal_store(S[mt][r], So + (16 * mt + 4 * q + r) * 128 + 16 * w + r16);
.LBB0_739:
	s_or_b64 exec, exec, s[34:35]
	s_and_b64 vcc, exec, s[28:29]
	s_barrier
	s_cbranch_vccnz .LBB0_741
	s_lshl_b32 s34, s58, 16
	s_lshl_b32 s35, s57, 18
	v_mov_b32_e32 v4, v190
	s_or_b32 s34, s35, s34
	s_add_u32 s34, s41, s34
	v_and_b32_e32 v0, 15, v4
	s_addc_u32 s35, s44, 0
	v_lshlrev_b32_e32 v2, 2, v0
	v_lshl_add_u64 v[0:1], s[34:35], 0, v[2:3]
	v_lshlrev_b32_e32 v2, 5, v4
	v_and_b32_e32 v4, 0xfffffe00, v2
	v_ashrrev_i32_e32 v5, 31, v4
	v_lshl_add_u64 v[6:7], v[4:5], 2, v[0:1]
	global_store_dword v[6:7], v16, off nt
	global_store_dword v[6:7], v17, off offset:512 nt
	global_store_dword v[6:7], v18, off offset:1024 nt
	global_store_dword v[6:7], v19, off offset:1536 nt
	v_add_u32_e32 v6, 0x800, v4
	v_ashrrev_i32_e32 v7, 31, v6
	v_lshl_add_u64 v[6:7], v[6:7], 2, v[0:1]
	global_store_dword v[6:7], v12, off nt
	v_add_u32_e32 v6, 0x880, v4
	v_ashrrev_i32_e32 v7, 31, v6
	v_lshl_add_u64 v[6:7], v[6:7], 2, v[0:1]
	global_store_dword v[6:7], v13, off nt
	v_add_u32_e32 v6, 0x900, v4
	v_ashrrev_i32_e32 v7, 31, v6
	v_lshl_add_u64 v[6:7], v[6:7], 2, v[0:1]
	global_store_dword v[6:7], v14, off nt
	v_add_u32_e32 v6, 0x980, v4
	v_ashrrev_i32_e32 v7, 31, v6
	v_lshl_add_u64 v[6:7], v[6:7], 2, v[0:1]
	global_store_dword v[6:7], v15, off nt
	v_add_u32_e32 v6, 0x1000, v4
	v_ashrrev_i32_e32 v7, 31, v6
	v_lshl_add_u64 v[6:7], v[6:7], 2, v[0:1]
	global_store_dword v[6:7], v20, off nt
	v_add_u32_e32 v6, 0x1080, v4
	v_ashrrev_i32_e32 v7, 31, v6
	v_lshl_add_u64 v[6:7], v[6:7], 2, v[0:1]
	global_store_dword v[6:7], v21, off nt
	v_add_u32_e32 v6, 0x1100, v4
	v_ashrrev_i32_e32 v7, 31, v6
	v_lshl_add_u64 v[6:7], v[6:7], 2, v[0:1]
	global_store_dword v[6:7], v22, off nt
	v_add_u32_e32 v6, 0x1180, v4
	v_ashrrev_i32_e32 v7, 31, v6
	v_lshl_add_u64 v[6:7], v[6:7], 2, v[0:1]
	global_store_dword v[6:7], v23, off nt
	v_add_u32_e32 v6, 0x1800, v4
	v_ashrrev_i32_e32 v7, 31, v6
	v_lshl_add_u64 v[6:7], v[6:7], 2, v[0:1]
	global_store_dword v[6:7], v24, off nt
	v_add_u32_e32 v6, 0x1880, v4
	v_ashrrev_i32_e32 v7, 31, v6
	v_lshl_add_u64 v[6:7], v[6:7], 2, v[0:1]
	global_store_dword v[6:7], v25, off nt
	v_add_u32_e32 v6, 0x1900, v4
	v_ashrrev_i32_e32 v7, 31, v6
	v_lshl_add_u64 v[6:7], v[6:7], 2, v[0:1]
	global_store_dword v[6:7], v26, off nt
	v_add_u32_e32 v6, 0x1980, v4
	v_ashrrev_i32_e32 v7, 31, v6
	v_lshl_add_u64 v[6:7], v[6:7], 2, v[0:1]
	global_store_dword v[6:7], v27, off nt
	v_add_u32_e32 v6, 0x2000, v4
	v_ashrrev_i32_e32 v7, 31, v6
	v_lshl_add_u64 v[6:7], v[6:7], 2, v[0:1]
	global_store_dword v[6:7], v36, off nt
	v_add_u32_e32 v6, 0x2080, v4
	v_ashrrev_i32_e32 v7, 31, v6
	v_lshl_add_u64 v[6:7], v[6:7], 2, v[0:1]
	global_store_dword v[6:7], v37, off nt
	v_add_u32_e32 v6, 0x2100, v4
	v_ashrrev_i32_e32 v7, 31, v6
	v_lshl_add_u64 v[6:7], v[6:7], 2, v[0:1]
	global_store_dword v[6:7], v38, off nt
	v_add_u32_e32 v6, 0x2180, v4
	v_ashrrev_i32_e32 v7, 31, v6
	v_lshl_add_u64 v[6:7], v[6:7], 2, v[0:1]
	global_store_dword v[6:7], v39, off nt
	v_add_u32_e32 v6, 0x2800, v4
	v_ashrrev_i32_e32 v7, 31, v6
	v_lshl_add_u64 v[6:7], v[6:7], 2, v[0:1]
	global_store_dword v[6:7], v28, off nt
	v_add_u32_e32 v6, 0x2880, v4
	v_ashrrev_i32_e32 v7, 31, v6
	v_lshl_add_u64 v[6:7], v[6:7], 2, v[0:1]
	global_store_dword v[6:7], v29, off nt
	v_add_u32_e32 v6, 0x2900, v4
	v_ashrrev_i32_e32 v7, 31, v6
	v_lshl_add_u64 v[6:7], v[6:7], 2, v[0:1]
	global_store_dword v[6:7], v30, off nt
	v_add_u32_e32 v6, 0x2980, v4
	v_ashrrev_i32_e32 v7, 31, v6
	v_lshl_add_u64 v[6:7], v[6:7], 2, v[0:1]
	global_store_dword v[6:7], v31, off nt
	v_add_u32_e32 v6, 0x3000, v4
	v_ashrrev_i32_e32 v7, 31, v6
	v_lshl_add_u64 v[6:7], v[6:7], 2, v[0:1]
	global_store_dword v[6:7], v32, off nt
	v_add_u32_e32 v6, 0x3080, v4
	v_ashrrev_i32_e32 v7, 31, v6
	v_lshl_add_u64 v[6:7], v[6:7], 2, v[0:1]
	global_store_dword v[6:7], v33, off nt
	v_add_u32_e32 v6, 0x3100, v4
	v_ashrrev_i32_e32 v7, 31, v6
	v_lshl_add_u64 v[6:7], v[6:7], 2, v[0:1]
	global_store_dword v[6:7], v34, off nt
	v_add_u32_e32 v6, 0x3180, v4
	v_ashrrev_i32_e32 v7, 31, v6
	v_lshl_add_u64 v[6:7], v[6:7], 2, v[0:1]
	global_store_dword v[6:7], v35, off nt
	v_add_u32_e32 v6, 0x3800, v4
	v_ashrrev_i32_e32 v7, 31, v6
	v_lshl_add_u64 v[6:7], v[6:7], 2, v[0:1]
	global_store_dword v[6:7], v40, off nt
	v_add_u32_e32 v6, 0x3880, v4
	v_ashrrev_i32_e32 v7, 31, v6
	v_lshl_add_u64 v[6:7], v[6:7], 2, v[0:1]
	global_store_dword v[6:7], v41, off nt
	v_add_u32_e32 v6, 0x3900, v4
	v_add_u32_e32 v4, 0x3980, v4
	v_ashrrev_i32_e32 v7, 31, v6
	v_ashrrev_i32_e32 v5, 31, v4
	v_lshl_add_u64 v[6:7], v[6:7], 2, v[0:1]
	v_lshl_add_u64 v[0:1], v[4:5], 2, v[0:1]
	global_store_dword v[6:7], v42, off nt
	global_store_dword v[0:1], v43, off nt

; template <int TYPE>
; __device__ __forceinline__ void mix_sg_unit(Frame& F, int b, int h, int mode  , const float* rot) {
;     ...
;     if (!prompt) {
;         const float* Sin = (TYPE == 0 ? F.in[2] : F.in[5]) + (size_t)(b * 4 + h) * 16384;
; #pragma unroll
;         for (int mt = 0; mt < 8; ++mt)
; #pragma unroll
;             for (int r = 0; r < 4; ++r) S[mt][r] = __builtin_nontemporal_load(Sin + (16 * mt + 4 * q + r) * 128 + 16 * w + r16);
;         if (TYPE == 0) {
; #pragma unroll
;             for (int r = 0; r < 4; ++r) nacc[r] = F.in[3][(size_t)(b * 4 + h) * 128 + 16 * w + 4 * q + r];
;             m0 = F.in[4][b * 4 + h];
;         }
;     }
.LBB0_742:
	s_and_b64 vcc, exec, s[28:29]
	s_cbranch_vccnz .LBB0_744
	s_lshl_b32 s76, s56, 9
	v_lshl_add_u64 v[0:1], v[68:69], 0, s[76:77]
	s_lshl_b32 s34, s56, 2
	v_readlane_b32 s4, v251, 5
	global_load_dwordx4 v[4:7], v[0:1], off
	v_mov_b32_e32 v0, s34
	v_readlane_b32 s12, v251, 13
	v_readlane_b32 s13, v251, 14
	v_readlane_b32 s5, v251, 6
	v_readlane_b32 s6, v251, 7
	v_readlane_b32 s7, v251, 8
	v_readlane_b32 s8, v251, 9
	v_readlane_b32 s9, v251, 10
	global_load_dword v0, v0, s[12:13]
	v_readlane_b32 s10, v251, 11
	v_readlane_b32 s11, v251, 12
	v_readlane_b32 s14, v251, 15
	v_readlane_b32 s15, v251, 16
	v_readlane_b32 s16, v251, 17
	v_readlane_b32 s17, v251, 18
	v_readlane_b32 s18, v251, 19
	v_readlane_b32 s19, v251, 20
	s_waitcnt vmcnt(1)
	v_cvt_pk_bf16_f32 v16, v4, v5
	v_cvt_pk_bf16_f32 v17, v6, v7
	s_branch .LBB0_745

; template <int TYPE>
; __device__ __forceinline__ void mix_sg_unit(Frame& F, int b, int h, int mode  , const float* rot) {
;     ...
;         const float* Sin = (TYPE == 0 ? F.in[2] : F.in[5]) + (size_t)(b * 4 + h) * 16384;
; #pragma unroll
;         for (int mt = 0; mt < 8; ++mt)
; #pragma unroll
;             for (int r = 0; r < 4; ++r) S[mt][r] = __builtin_nontemporal_load(Sin + (16 * mt + 4 * q + r) * 128 + 16 * w + r16);
.LBB0_749:
	s_cmpk_lt_i32 s43, 0x400
	s_cbranch_scc0 .Lsum_noload
	s_lshl_b32 s98, s56, 16
	s_mov_b32 s99, 0
	v_lshl_add_u64 v[126:127], v[74:75], 0, s[98:99]
	s_mov_b32 s98, 0x2000
	global_load_dword v82, v[126:127], off nt
	global_load_dword v83, v[126:127], off offset:512 nt
	global_load_dword v84, v[126:127], off offset:1024 nt
	global_load_dword v85, v[126:127], off offset:1536 nt
	v_lshl_add_u64 v[126:127], v[126:127], 0, s[98:99]
	global_load_dword v78, v[126:127], off nt
	global_load_dword v79, v[126:127], off offset:512 nt
	global_load_dword v80, v[126:127], off offset:1024 nt
	global_load_dword v81, v[126:127], off offset:1536 nt
	v_lshl_add_u64 v[126:127], v[126:127], 0, s[98:99]
	global_load_dword v62, v[126:127], off nt
	global_load_dword v63, v[126:127], off offset:512 nt
	global_load_dword v76, v[126:127], off offset:1024 nt
	global_load_dword v77, v[126:127], off offset:1536 nt
	v_lshl_add_u64 v[126:127], v[126:127], 0, s[98:99]
	global_load_dword v58, v[126:127], off nt
	global_load_dword v59, v[126:127], off offset:512 nt
	global_load_dword v60, v[126:127], off offset:1024 nt
	global_load_dword v61, v[126:127], off offset:1536 nt
	v_lshl_add_u64 v[126:127], v[126:127], 0, s[98:99]
	global_load_dword v38, v[126:127], off nt
	global_load_dword v39, v[126:127], off offset:512 nt
	global_load_dword v56, v[126:127], off offset:1024 nt
	global_load_dword v57, v[126:127], off offset:1536 nt
	v_lshl_add_u64 v[126:127], v[126:127], 0, s[98:99]
	global_load_dword v52, v[126:127], off nt
	global_load_dword v53, v[126:127], off offset:512 nt
	global_load_dword v54, v[126:127], off offset:1024 nt
	global_load_dword v55, v[126:127], off offset:1536 nt
	v_lshl_add_u64 v[126:127], v[126:127], 0, s[98:99]
	global_load_dword v40, v[126:127], off nt
	global_load_dword v41, v[126:127], off offset:512 nt
	global_load_dword v42, v[126:127], off offset:1024 nt
	global_load_dword v43, v[126:127], off offset:1536 nt
	v_lshl_add_u64 v[126:127], v[126:127], 0, s[98:99]
	global_load_dword v44, v[126:127], off nt
	global_load_dword v45, v[126:127], off offset:512 nt
	global_load_dword v46, v[126:127], off offset:1024 nt
	global_load_dword v47, v[126:127], off offset:1536 nt
	s_branch .Lsum_loaded

; #define LAS __attribute__((address_space(3)))
; __device__ __forceinline__ float logsigmoidf_(float x) { return fminf(x, 0.f) - __logf(1.f + __expf(-fabsf(x))); }
; template <int TYPE>
; __device__ __forceinline__ void mix_sg_unit(Frame& F, int b, int h, int mode  , const float* rot) {
;     ...
;             *(LAS u32x4*)(L + MX_V + tk * MX_PITCH + 32 * p) = pa[4]; *(LAS u32x4*)(L + MX_V + tk * MX_PITCH + 32 * p + 16) = pa[5];
;             {
;                 const int c0 = (MX_POS4(16 * p)) * 2;
; #pragma unroll
;                 for (int g = 0; g < 4; ++g) {
;                     *(LAS u32x2*)(L + MX_Q + tk * MX_PITCH + c0 + 16 * g) = (u32x2){pa[g >> 1][2 * (g & 1)], pa[g >> 1][2 * (g & 1) + 1]};
;                     *(LAS u32x2*)(L + MX_K + tk * MX_PITCH + c0 + 16 * g) = (u32x2){pa[2 + (g >> 1)][2 * (g & 1)], pa[2 + (g >> 1)][2 * (g & 1) + 1]};
;                 }
;             }
;         }
;         if (w == 0) {
;             const bool valid = lane < ntok;
;             float li = -1e30f, lf = 0.f;
;             if (TYPE == 0) { if (valid) { li = pli + bias_i; lf = logsigmoidf_(plf + bias_f); } } else { if (valid) { li = 0.f; lf = lgam; } }
;             const float bb = row_prefix_sum(lf);
;             const float y = li - bb;
;             const float am = row_prefix_max(y);
;             const float a = bb + am;
;             const float B0 = rdlane(bb, 15), B1 = rdlane(bb, 31), B2 = rdlane(bb, 47), B3 = rdlane(bb, 63);
;             float M1 = 0.f, M2 = 0.f, M3 = 0.f, M4 = 0.f;
;             if (TYPE == 0) { const float A0 = rdlane(a, 15), A1 = rdlane(a, 31), A2 = rdlane(a, 47), A3 = rdlane(a, 63);
;                 M1 = fmaxf(B0 + m0, A0); M2 = fmaxf(B1 + M1, A1); M3 = fmaxf(B2 + M2, A2); M4 = fmaxf(B3 + M3, A3); }
;             const float m0q = q == 0 ? m0 : q == 1 ? M1 : q == 2 ? M2 : M3;
;             const float mnq = q == 0 ? M1 : q == 1 ? M2 : q == 2 ? M3 : M4;
;             const float b15 = q == 0 ? B0 : q == 1 ? B1 : q == 2 ? B2 : B3;
;             const float m = (TYPE == 0) ? fmaxf(bb + m0q, a) : 0.f;
;             SC[lane] = bb - m; SC[64 + lane] = y + LNKS; SC[128 + lane] = __expf(bb + m0q - m);
;             SC[192 + lane] = __expf(y + LNKS + b15 - mnq); SC[256 + lane] = __expf(-m);
;             if (r16 == 0) SC[320 + q] = __expf(b15 + m0q - mnq);
;             m0 = (nmc == 4) ? M4 : M1;
;         }
.Lsum_loaded:
	v_add_u32_e32 v37, v91, v66
	s_waitcnt vmcnt(33)
	ds_write_b128 v37, v[26:29] offset:52224
	s_waitcnt vmcnt(32)
	ds_write_b128 v37, v[30:33] offset:52240
	v_add_u32_e32 v26, v91, v92
	ds_write2_b64 v26, v[18:19], v[20:21] offset1:2
	v_add_u32_e32 v18, 0x4000, v26
	s_and_b64 vcc, exec, s[0:1]
	v_mov_b32_e32 v116, v0
	ds_write2_b64 v18, v[22:23], v[24:25] offset0:128 offset1:130
	ds_write2_b64 v26, v[8:9], v[10:11] offset0:4 offset1:6
	ds_write2_b64 v18, v[12:13], v[14:15] offset0:132 offset1:134
	s_cbranch_vccnz .LBB0_753
	v_add_f32_e32 v8, v35, v36
	s_mov_b32 s0, 0xbfb8aa3b
	v_mul_f32_e64 v9, |v8|, s0
	v_exp_f32_e32 v9, v9
	s_mov_b32 s0, 0x3f317217
	v_min_f32_e32 v8, 0, v8
	v_add_f32_e32 v2, v34, v2
	v_add_f32_e32 v9, 1.0, v9
	v_cmp_gt_f32_e32 vcc, s81, v9
	s_nop 1
	v_cndmask_b32_e64 v10, 0, 32, vcc
	v_ldexp_f32 v9, v9, v10
	v_log_f32_e32 v9, v9
	v_cndmask_b32_e32 v10, 0, v220, vcc
	v_mul_f32_e32 v11, 0x3f317217, v9
	v_fma_f32 v11, v9, s0, -v11
	v_fmac_f32_e32 v11, 0x3377d1cf, v9
	s_mov_b32 s0, 0x7f800000
	v_fmac_f32_e32 v11, 0x3f317217, v9
	v_cmp_lt_f32_e64 vcc, |v9|, s0
	s_nop 1
	v_cndmask_b32_e32 v9, v9, v11, vcc
	v_sub_f32_e32 v9, v9, v10
	v_sub_f32_e32 v8, v8, v9
	v_cmp_gt_u32_e32 vcc, s59, v190
	s_nop 1
	v_cndmask_b32_e32 v8, 0, v8, vcc
	v_cndmask_b32_e32 v2, v219, v2, vcc
	s_nop 0
	v_add_f32_dpp v8, v8, v8 row_shr:1 row_mask:0xf bank_mask:0xf bound_ctrl:1
	s_nop 1
	v_add_f32_dpp v8, v8, v8 row_shr:2 row_mask:0xf bank_mask:0xf bound_ctrl:1
	s_nop 1
	v_add_f32_dpp v8, v8, v8 row_shr:4 row_mask:0xf bank_mask:0xf bound_ctrl:1
	s_nop 1
	v_add_f32_dpp v9, v8, v8 row_shr:8 row_mask:0xf bank_mask:0xf bound_ctrl:1
	v_sub_f32_e32 v10, v2, v9
	v_mov_b32_e32 v2, 0xff61b1e6
	v_mov_b32_e32 v8, 0xff61b1e6
	v_readlane_b32 s0, v9, 15
	v_mov_b32_dpp v2, v10 row_shr:1 row_mask:0xf bank_mask:0xf
	v_max_f32_e32 v2, v2, v2
	v_max_f32_e32 v2, v10, v2
	v_readlane_b32 s1, v9, 31
	v_readlane_b32 s34, v9, 47
	v_mov_b32_dpp v8, v2 row_shr:2 row_mask:0xf bank_mask:0xf
	v_max_f32_e32 v8, v8, v8
	v_max_f32_e32 v2, v2, v8
	v_mov_b32_e32 v8, 0xff61b1e6
	v_readlane_b32 s35, v9, 63
	v_add_f32_e32 v10, 0xc01b43d5, v10
	v_mov_b32_dpp v8, v2 row_shr:4 row_mask:0xf bank_mask:0xf
	v_max_f32_e32 v8, v8, v8
	v_max_f32_e32 v2, v2, v8
	v_mov_b32_e32 v8, 0xff61b1e6
	s_nop 1
	v_mov_b32_dpp v8, v2 row_shr:8 row_mask:0xf bank_mask:0xf
	v_max_f32_e32 v8, v8, v8
	v_max_f32_e32 v2, v2, v8
	v_add_f32_e32 v11, v9, v2
	v_add_f32_e32 v2, s0, v0
	v_readlane_b32 s60, v11, 15
	v_readlane_b32 s61, v11, 31
	v_readlane_b32 s62, v11, 47
	v_max_f32_e64 v8, s60, s60
	v_max_f32_e32 v116, v2, v8
	v_add_f32_e32 v2, s1, v116
	v_max_f32_e64 v8, s61, s61
	v_max_f32_e32 v2, v2, v8
	v_add_f32_e32 v8, s34, v2
	v_max_f32_e64 v12, s62, s62
	v_readlane_b32 s63, v11, 63
	v_max_f32_e32 v8, v8, v12
	v_add_f32_e32 v12, s35, v8
	v_max_f32_e64 v13, s63, s63
	v_max_f32_e32 v12, v12, v13
	v_cndmask_b32_e64 v13, v8, v2, s[84:85]
	v_cndmask_b32_e64 v8, v12, v8, s[84:85]
	v_cndmask_b32_e64 v2, v8, v2, s[96:97]
	v_mov_b32_e32 v8, s35
	v_mov_b32_e32 v12, s34
	v_cndmask_b32_e64 v13, v13, v116, s[96:97]
	v_cndmask_b32_e64 v8, v8, v12, s[84:85]
	v_mov_b32_e32 v12, s1
	v_cndmask_b32_e64 v0, v13, v0, s[20:21]
	v_cndmask_b32_e64 v8, v8, v12, s[96:97]
	v_mov_b32_e32 v12, s0
	v_cndmask_b32_e64 v8, v8, v12, s[20:21]
	v_add_f32_e32 v12, v9, v0
	v_cndmask_b32_e64 v2, v2, v116, s[20:21]
	v_max_f32_e32 v11, v12, v11
	v_add_f32_e32 v13, v10, v8
	v_sub_f32_e32 v12, v12, v11
	v_sub_f32_e32 v13, v13, v2
	v_mul_f32_e32 v12, 0x3fb8aa3b, v12
	v_mul_f32_e32 v13, 0x3fb8aa3b, v13
	v_exp_f32_e32 v12, v12
	v_exp_f32_e32 v13, v13
	v_mul_f32_e32 v14, 0xbfb8aa3b, v11
	v_exp_f32_e32 v14, v14
	v_sub_f32_e32 v9, v9, v11
	ds_write2st64_b32 v104, v9, v10 offset1:1
	ds_write2st64_b32 v104, v12, v13 offset0:2 offset1:3
	ds_write_b32 v104, v14 offset:1024
	s_and_saveexec_b64 s[0:1], s[72:73]
	s_cbranch_execz .LBB0_752
	v_add_f32_e32 v0, v8, v0
	v_sub_f32_e32 v0, v0, v2
	v_mul_f32_e32 v0, 0x3fb8aa3b, v0
	v_exp_f32_e32 v0, v0
	ds_write_b32 v105, v0 offset:1280

; template <int TYPE, int NMC>
; __device__ __forceinline__ void sg_chain(LAS unsigned char* L, LAS float* SC, f32x4 (&S)[8], f32x4& nacc, int w, int r16, int q) {
;     ...
;         {
;             const LAS unsigned char* Qb = L + MX_Q + 16 * mc * MX_PITCH; const LAS unsigned char* Kb = L + MX_K + 16 * mc * MX_PITCH; const LAS unsigned char* Vb = L + MX_V + 16 * mc * MX_PITCH;
;             f32x4 g0 = {0.f, 0.f, 0.f, 0.f}, g1 = {0.f, 0.f, 0.f, 0.f};
; #pragma unroll
;             for (int ks = 0; ks < 4; ++ks) {
;                 const bf16x8 kf = ld8(Kb + r16 * MX_PITCH + (32 * ks + 8 * q) * 2), qf = ld8(Qb + r16 * MX_PITCH + (32 * ks + 8 * q) * 2);
;                 if (ks & 1) g1 = MFMA16(kf, qf, g1); else g0 = MFMA16(kf, qf, g0);
;             }
;             const f32x4 g = g0 + g1;
;             const float xi = SC[mc * 16 + r16]; const f32x4 y4 = *(const LAS f32x4*)(SC + 64 + mc * 16 + 4 * q);
;             f32x4 P;
; #pragma unroll
;             for (int r = 0; r < 4; ++r) P[r] = (4 * q + r <= r16) ? g[r] * __expf(xi + y4[r]) : 0.f;
;             if (TYPE == 0) { float ps = (P[0] + P[1]) + (P[2] + P[3]); ps += __shfl_xor(ps, 16); ps += __shfl_xor(ps, 32); if (w == 0 && q == 0) DI[16 * mc + r16] = ps; }
;             const u32x2 vt = tr16(Vb + (4 * q + (r16 >> 2)) * MX_PITCH + (16 * w + 4 * (r16 & 3)) * 2);
;             oo[mc] = mfma16k16((u32x2){pkbf(P[0], P[1]), pkbf(P[2], P[3])}, vt, oo[mc]);
;         }
;         if (mc == 1 || TYPE == 1) __builtin_amdgcn_sched_barrier(0);
;     }
; #pragma unroll
;     for (int mc = 0; mc < NMC; ++mc) {
;         {
;             const LAS unsigned char* Qb = L + MX_Q + 16 * mc * MX_PITCH; const LAS unsigned char* Kb = L + MX_K + 16 * mc * MX_PITCH;
;             const u32x2 vt = tr16(L + MX_V + 16 * mc * MX_PITCH + (4 * q + (r16 >> 2)) * MX_PITCH + (16 * w + 4 * (r16 & 3)) * 2);
;             f32x4 o2a = {0.f, 0.f, 0.f, 0.f}, o2b = {0.f, 0.f, 0.f, 0.f};
; #pragma unroll
;             for (int ks = 0; ks < 4; ++ks) {
;                 const bf16x8 qf = ld8(Qb + r16 * MX_PITCH + (32 * ks + 8 * q) * 2);
;                 const bf16x8 SB = mk8(pkbf(S[2 * ks][0], S[2 * ks][1]), pkbf(S[2 * ks][2], S[2 * ks][3]), pkbf(S[2 * ks + 1][0], S[2 * ks + 1][1]), pkbf(S[2 * ks + 1][2], S[2 * ks + 1][3]));
;                 if (ks & 1) o2b = MFMA16(qf, SB, o2b); else o2a = MFMA16(qf, SB, o2a);
;             }
.LBB0_755:
	s_or_b64 exec, exec, s[0:1]
	v_add_u32_e32 v0, v97, v98
	s_waitcnt vmcnt(2)
	v_cvt_pk_bf16_f32 v48, v82, v83
	v_cvt_pk_bf16_f32 v49, v84, v85
	v_cvt_pk_bf16_f32 v50, v78, v79
	v_cvt_pk_bf16_f32 v51, v80, v81
	s_waitcnt lgkmcnt(0)
	ds_read_b64_tr_b16 v[0:1], v0 offset:52224
	v_cvt_pk_bf16_f32 v34, v2, v34
	v_cvt_pk_bf16_f32 v35, v35, v36
	v_mfma_f32_16x16x32_bf16 v[26:29], v[26:29], v[48:51], 0
	v_mov_b32_e32 v36, v3
	v_mov_b32_e32 v37, v3
	v_cvt_pk_bf16_f32 v48, v62, v63
	v_cvt_pk_bf16_f32 v49, v76, v77
	v_cvt_pk_bf16_f32 v50, v58, v59
	v_cvt_pk_bf16_f32 v51, v60, v61
	v_mov_b32_e32 v2, v3
	v_add_u32_e32 v86, v96, v99
	v_mfma_f32_16x16x32_bf16 v[18:21], v[18:21], v[48:51], 0
	v_cvt_pk_bf16_f32 v48, v38, v39
	v_cvt_pk_bf16_f32 v49, v56, v57
	v_cvt_pk_bf16_f32 v50, v52, v53
	v_cvt_pk_bf16_f32 v51, v54, v55
	s_nop 1
	v_mfma_f32_16x16x32_bf16 v[26:29], v[30:33], v[48:51], v[26:29]
	v_mov_b32_e32 v30, s62
	ds_read_b64_tr_b16 v[88:89], v86 offset:52224
	ds_read_b32 v86, v30
	v_cvt_pk_bf16_f32 v48, v40, v41
	s_waitcnt lgkmcnt(2)
	v_mfma_f32_16x16x32_bf16 v[30:33], v[34:37], v[0:3], 0
	ds_read_b64 v[0:1], v114
	v_cvt_pk_bf16_f32 v49, v42, v43
	v_cvt_pk_bf16_f32 v50, v44, v45
	v_cvt_pk_bf16_f32 v51, v46, v47
	s_nop 1
	v_mfma_f32_16x16x32_bf16 v[34:37], v[22:25], v[48:51], v[18:21]
	s_nop 2
	ds_read_b128 v[20:23], v109
	ds_read_b128 v[48:51], v108
	v_mov_b32_e32 v18, v3
	v_mov_b32_e32 v19, v3
	s_waitcnt lgkmcnt(2)
	s_nop 0
	v_mfma_f32_16x16x32_bf16 v[16:19], v[0:3], v[16:19], 0
	s_and_saveexec_b64 s[0:1], s[72:73]
	s_nop 6
	ds_write_b128 v113, v[16:19]
	s_or_b64 exec, exec, s[0:1]
	v_pk_add_f32 v[16:17], v[26:27], v[34:35]
	v_pk_add_f32 v[0:1], v[28:29], v[36:37]
	s_waitcnt lgkmcnt(1)
	v_fma_f32 v2, v16, v20, v30
	v_add_u32_e32 v16, v101, v102
	v_fma_f32 v17, v17, v21, v31
	v_fma_f32 v0, v0, v22, v32
	v_fmac_f32_e32 v33, v1, v23
	v_add_u32_e32 v1, 0x400, v16
	ds_write2_b32 v16, v2, v17 offset1:132
	ds_write2_b32 v1, v0, v33 offset0:8 offset1:140
	v_lshlrev_b32_e32 v0, 16, v88
	v_and_b32_e32 v1, 0xffff0000, v88
	v_add_u32_e32 v88, v96, v100
	v_mov_b32_e32 v22, v3
	v_mov_b32_e32 v23, v3
	ds_read_b64_tr_b16 v[20:21], v88 offset:17408
	ds_read_b64_tr_b16 v[24:25], v88 offset:17416
	v_mov_b32_e32 v26, v3
	v_mov_b32_e32 v27, v3
	v_lshlrev_b32_e32 v16, 16, v89
	v_and_b32_e32 v17, 0xffff0000, v89
	s_waitcnt lgkmcnt(4)
	v_pk_mul_f32 v[0:1], v[48:49], v[0:1]
	v_pk_mul_f32 v[16:17], v[50:51], v[16:17]
	v_cvt_pk_bf16_f32 v0, v0, v1
	v_cvt_pk_bf16_f32 v1, v16, v17
	v_mov_b32_e32 v2, v3
	v_pk_mul_f32 v[18:19], v[84:85], v[86:87] op_sel_hi:[1,0]
	v_pk_mul_f32 v[16:17], v[82:83], v[86:87] op_sel_hi:[1,0]
	v_pk_mul_f32 v[30:31], v[76:77], v[86:87] op_sel_hi:[1,0]
	v_pk_mul_f32 v[28:29], v[62:63], v[86:87] op_sel_hi:[1,0]
	s_waitcnt lgkmcnt(1)
	v_mfma_f32_16x16x32_bf16 v[20:23], v[20:23], v[0:3], v[16:19]
	v_mul_f32_e64 v34, v60, v86
	v_mul_f32_e64 v35, v61, v86
	v_pk_mul_f32 v[32:33], v[58:59], v[86:87] op_sel_hi:[1,0]
	v_pk_mul_f32 v[58:59], v[56:57], v[86:87] op_sel_hi:[1,0]
	v_pk_mul_f32 v[18:19], v[80:81], v[86:87] op_sel_hi:[1,0]
	v_pk_mul_f32 v[16:17], v[78:79], v[86:87] op_sel_hi:[1,0]
	v_pk_mul_f32 v[56:57], v[38:39], v[86:87] op_sel_hi:[1,0]
	v_pk_mul_f32 v[54:55], v[54:55], v[86:87] op_sel_hi:[1,0]
	s_waitcnt lgkmcnt(0)
	v_mfma_f32_16x16x32_bf16 v[16:19], v[24:27], v[0:3], v[16:19]
	ds_read_b64_tr_b16 v[24:25], v88 offset:17472
	v_pk_mul_f32 v[52:53], v[52:53], v[86:87] op_sel_hi:[1,0]
	v_pk_mul_f32 v[42:43], v[42:43], v[86:87] op_sel_hi:[1,0]
	s_waitcnt lgkmcnt(0)
	v_mfma_f32_16x16x32_bf16 v[24:27], v[24:27], v[0:3], v[28:31]
	s_nop 2
	ds_read_b64_tr_b16 v[28:29], v88 offset:17480
	v_mov_b32_e32 v30, v3
	v_mov_b32_e32 v31, v3
	v_pk_mul_f32 v[40:41], v[40:41], v[86:87] op_sel_hi:[1,0]
	v_pk_mul_f32 v[46:47], v[46:47], v[86:87] op_sel_hi:[1,0]
	s_waitcnt lgkmcnt(0)
	v_mfma_f32_16x16x32_bf16 v[28:31], v[28:31], v[0:3], v[32:35]
	s_nop 2
	ds_read_b64_tr_b16 v[32:33], v88 offset:17536
	v_mov_b32_e32 v34, v3
	v_mov_b32_e32 v35, v3
	v_pk_mul_f32 v[44:45], v[44:45], v[86:87] op_sel_hi:[1,0]
	v_pk_mul_f32 v[6:7], v[6:7], v[86:87] op_sel_hi:[1,0]
	s_waitcnt lgkmcnt(0)
	v_mfma_f32_16x16x32_bf16 v[36:39], v[32:35], v[0:3], v[56:59]
	ds_read_b64_tr_b16 v[32:33], v88 offset:17544
	v_pk_mul_f32 v[4:5], v[4:5], v[86:87] op_sel_hi:[1,0]
	v_cvt_pk_bf16_f32 v48, v48, v49
	s_waitcnt lgkmcnt(0)
	v_mfma_f32_16x16x32_bf16 v[32:35], v[32:35], v[0:3], v[52:55]
	s_nop 2
	ds_read_b64_tr_b16 v[52:53], v88 offset:17600
	v_mov_b32_e32 v54, v3
	v_mov_b32_e32 v55, v3
	v_cvt_pk_bf16_f32 v49, v50, v51
	v_mov_b32_e32 v50, v3
	s_waitcnt lgkmcnt(0)
	v_mfma_f32_16x16x32_bf16 v[40:43], v[52:55], v[0:3], v[40:43]
	ds_read_b64_tr_b16 v[52:53], v88 offset:17608
	v_mov_b32_e32 v51, v3
	s_waitcnt lgkmcnt(0)
	v_mfma_f32_16x16x32_bf16 v[44:47], v[52:55], v[0:3], v[44:47]
	ds_read_b64_tr_b16 v[0:1], v115 offset:17408
	s_waitcnt lgkmcnt(0)
	s_barrier
	s_waitcnt vmcnt(0)
	v_mfma_f32_16x16x32_bf16 v[4:7], v[0:3], v[48:51], v[4:7]
	ds_read_b128 v[60:63], v93
	ds_read_b128 v[52:55], v93 offset:16
	ds_read_b128 v[56:59], v93 offset:32
	ds_read_b128 v[48:51], v93 offset:48
	s_and_saveexec_b64 s[0:1], s[24:25]
	s_cbranch_execz .LBB0_759
	s_waitcnt lgkmcnt(2)
	v_mov_b32_e32 v52, 0
	v_mov_b32_e32 v53, v52
	v_mov_b32_e32 v54, v52
	v_mov_b32_e32 v55, v52
	v_mov_b32_e32 v60, v52
	v_mov_b32_e32 v61, v52
	v_mov_b32_e32 v62, v52
	v_mov_b32_e32 v63, v52
	s_waitcnt lgkmcnt(1)
	v_mov_b32_e32 v56, v52
	v_mov_b32_e32 v57, v52
	v_mov_b32_e32 v58, v52
	v_mov_b32_e32 v59, v52
	s_waitcnt lgkmcnt(0)
	v_mov_b32_e32 v48, v52
	v_mov_b32_e32 v49, v52
	v_mov_b32_e32 v50, v52
	v_mov_b32_e32 v51, v52

; template <int TYPE>
; __device__ __forceinline__ void mix_sg_unit(Frame& F, int b, int h, int mode  , const float* rot) {
;     ...
;     __syncthreads();
;     if (mode != 2) {
;         int l2 = F.lane; asm volatile("" : "+v"(l2)); const int r16 = l2 & 15, q = l2 >> 4;
;         float* So = F.out + (TYPE == 0 ? (prompt ? O_CP : O_CS) : (prompt ? O_RP : O_RS)) + (size_t)(b * 4 + h) * 16384;
; #pragma unroll
;         for (int mt = 0; mt < 8; ++mt)
; #pragma unroll
;             for (int r = 0; r < 4; ++r) __builtin_nontemporal_store(S[mt][r], So + (16 * mt + 4 * q + r) * 128 + 16 * w + r16);
;         if (TYPE == 0) {
;             if (r16 == 0) { float* No = F.out + (prompt ? O_NP : O_NS) + (size_t)(b * 4 + h) * 128;
; #pragma unroll
;                 for (int r = 0; r < 4; ++r) No[16 * w + 4 * q + r] = nacc[r]; }
;             if (w == 0 && lane == 0) F.out[(prompt ? O_MP : O_MS) + b * 4 + h] = m0;
.LBB0_761:
	s_or_b64 exec, exec, s[0:1]
	s_and_b64 vcc, exec, s[28:29]
	s_barrier
	s_cbranch_vccnz .LBB0_719
	v_mov_b32_e32 v0, v190
	s_lshl_b32 s0, s56, 16
	v_ashrrev_i32_e32 v14, 2, v0
	v_and_b32_e32 v1, 15, v0
	v_and_b32_e32 v0, -4, v14
	s_add_u32 s0, s45, s0
	s_addc_u32 s1, s49, 0
	v_lshlrev_b32_e32 v2, 2, v1
	v_lshlrev_b32_e32 v10, 7, v0
	v_lshl_add_u64 v[8:9], s[0:1], 0, v[2:3]
	v_ashrrev_i32_e32 v11, 31, v10
	v_lshl_add_u64 v[12:13], v[10:11], 2, v[8:9]
	global_store_dword v[12:13], v20, off nt
	global_store_dword v[12:13], v21, off offset:512 nt
	global_store_dword v[12:13], v22, off offset:1024 nt
	v_lshl_or_b32 v12, v14, 7, v221
	v_ashrrev_i32_e32 v13, 31, v12
	v_lshl_add_u64 v[12:13], v[12:13], 2, v[8:9]
	global_store_dword v[12:13], v23, off nt
	v_add_u32_e32 v12, 0x800, v10
	v_ashrrev_i32_e32 v13, 31, v12
	v_lshl_add_u64 v[12:13], v[12:13], 2, v[8:9]
	global_store_dword v[12:13], v16, off nt
	v_add_u32_e32 v12, 0x880, v10
	v_ashrrev_i32_e32 v13, 31, v12
	v_lshl_add_u64 v[12:13], v[12:13], 2, v[8:9]
	global_store_dword v[12:13], v17, off nt
	v_add_u32_e32 v12, 0x900, v10
	v_ashrrev_i32_e32 v13, 31, v12
	v_lshl_add_u64 v[12:13], v[12:13], 2, v[8:9]
	global_store_dword v[12:13], v18, off nt
	v_add_u32_e32 v12, 0x980, v10
	v_ashrrev_i32_e32 v13, 31, v12
	v_lshl_add_u64 v[12:13], v[12:13], 2, v[8:9]
	global_store_dword v[12:13], v19, off nt
	v_add_u32_e32 v12, 0x1000, v10
	v_ashrrev_i32_e32 v13, 31, v12
	v_lshl_add_u64 v[12:13], v[12:13], 2, v[8:9]
	global_store_dword v[12:13], v24, off nt
	v_add_u32_e32 v12, 0x1080, v10
	v_ashrrev_i32_e32 v13, 31, v12
	v_lshl_add_u64 v[12:13], v[12:13], 2, v[8:9]
	global_store_dword v[12:13], v25, off nt
	v_add_u32_e32 v12, 0x1100, v10
	v_ashrrev_i32_e32 v13, 31, v12
	v_lshl_add_u64 v[12:13], v[12:13], 2, v[8:9]
	global_store_dword v[12:13], v26, off nt
	v_add_u32_e32 v12, 0x1180, v10
	v_ashrrev_i32_e32 v13, 31, v12
	v_lshl_add_u64 v[12:13], v[12:13], 2, v[8:9]
	global_store_dword v[12:13], v27, off nt
	v_add_u32_e32 v12, 0x1800, v10
	v_ashrrev_i32_e32 v13, 31, v12
	v_lshl_add_u64 v[12:13], v[12:13], 2, v[8:9]
	global_store_dword v[12:13], v28, off nt
	v_add_u32_e32 v12, 0x1880, v10
	v_ashrrev_i32_e32 v13, 31, v12
	v_lshl_add_u64 v[12:13], v[12:13], 2, v[8:9]
	global_store_dword v[12:13], v29, off nt
	v_add_u32_e32 v12, 0x1900, v10
	v_ashrrev_i32_e32 v13, 31, v12
	v_lshl_add_u64 v[12:13], v[12:13], 2, v[8:9]
	global_store_dword v[12:13], v30, off nt
	v_add_u32_e32 v12, 0x1980, v10
	v_ashrrev_i32_e32 v13, 31, v12
	v_lshl_add_u64 v[12:13], v[12:13], 2, v[8:9]
	global_store_dword v[12:13], v31, off nt
	v_add_u32_e32 v12, 0x2000, v10
	v_ashrrev_i32_e32 v13, 31, v12
	v_lshl_add_u64 v[12:13], v[12:13], 2, v[8:9]
	global_store_dword v[12:13], v36, off nt
	v_add_u32_e32 v12, 0x2080, v10
	v_ashrrev_i32_e32 v13, 31, v12
	v_lshl_add_u64 v[12:13], v[12:13], 2, v[8:9]
	global_store_dword v[12:13], v37, off nt
	v_add_u32_e32 v12, 0x2100, v10
	v_ashrrev_i32_e32 v13, 31, v12
	v_lshl_add_u64 v[12:13], v[12:13], 2, v[8:9]
	global_store_dword v[12:13], v38, off nt
	v_add_u32_e32 v12, 0x2180, v10
	v_ashrrev_i32_e32 v13, 31, v12
	v_lshl_add_u64 v[12:13], v[12:13], 2, v[8:9]
	global_store_dword v[12:13], v39, off nt
	v_add_u32_e32 v12, 0x2800, v10
	v_ashrrev_i32_e32 v13, 31, v12
	v_lshl_add_u64 v[12:13], v[12:13], 2, v[8:9]
	global_store_dword v[12:13], v32, off nt
	v_add_u32_e32 v12, 0x2880, v10
	v_ashrrev_i32_e32 v13, 31, v12
	v_lshl_add_u64 v[12:13], v[12:13], 2, v[8:9]
	global_store_dword v[12:13], v33, off nt
	v_add_u32_e32 v12, 0x2900, v10
	v_ashrrev_i32_e32 v13, 31, v12
	v_lshl_add_u64 v[12:13], v[12:13], 2, v[8:9]
	global_store_dword v[12:13], v34, off nt
	v_add_u32_e32 v12, 0x2980, v10
	v_ashrrev_i32_e32 v13, 31, v12
	v_lshl_add_u64 v[12:13], v[12:13], 2, v[8:9]
	global_store_dword v[12:13], v35, off nt
	v_add_u32_e32 v12, 0x3000, v10
	v_ashrrev_i32_e32 v13, 31, v12
	v_lshl_add_u64 v[12:13], v[12:13], 2, v[8:9]
	global_store_dword v[12:13], v40, off nt
	v_add_u32_e32 v12, 0x3080, v10
	v_ashrrev_i32_e32 v13, 31, v12
	v_lshl_add_u64 v[12:13], v[12:13], 2, v[8:9]
	global_store_dword v[12:13], v41, off nt
	v_add_u32_e32 v12, 0x3100, v10
	v_ashrrev_i32_e32 v13, 31, v12
	v_lshl_add_u64 v[12:13], v[12:13], 2, v[8:9]
	global_store_dword v[12:13], v42, off nt
	v_add_u32_e32 v12, 0x3180, v10
	v_ashrrev_i32_e32 v13, 31, v12
	v_lshl_add_u64 v[12:13], v[12:13], 2, v[8:9]
	global_store_dword v[12:13], v43, off nt
	v_add_u32_e32 v12, 0x3800, v10
	v_ashrrev_i32_e32 v13, 31, v12
	v_lshl_add_u64 v[12:13], v[12:13], 2, v[8:9]
	global_store_dword v[12:13], v44, off nt
	v_add_u32_e32 v12, 0x3880, v10
	v_ashrrev_i32_e32 v13, 31, v12
	v_lshl_add_u64 v[12:13], v[12:13], 2, v[8:9]
	global_store_dword v[12:13], v45, off nt
	v_add_u32_e32 v12, 0x3900, v10
	v_add_u32_e32 v10, 0x3980, v10
	v_ashrrev_i32_e32 v13, 31, v12
	v_ashrrev_i32_e32 v11, 31, v10
	v_lshl_add_u64 v[12:13], v[12:13], 2, v[8:9]
	v_lshl_add_u64 v[8:9], v[10:11], 2, v[8:9]
	v_cmp_eq_u32_e32 vcc, 0, v1
	global_store_dword v[12:13], v46, off nt
	global_store_dword v[8:9], v47, off nt
	s_and_saveexec_b64 s[0:1], vcc
	s_cbranch_execz .LBB0_764
	s_lshl_b32 s28, s56, 9
	v_readlane_b32 s4, v253, 3
	s_add_u32 s28, s4, s28
	v_readlane_b32 s4, v253, 4
	v_add_u32_e32 v0, s40, v0
	s_addc_u32 s29, s4, 0
	v_ashrrev_i32_e32 v1, 31, v0
	v_lshl_add_u64 v[0:1], v[0:1], 2, s[28:29]
	global_store_dwordx4 v[0:1], v[4:7], off

; #define LAS __attribute__((address_space(3)))
; #define ZROW(F, row, layer) (((row) < ROW_S ? F_Z(F) : F_ZS1(F, layer)) + (size_t)(row) * 4096)
; __device__ __forceinline__ u32x2 tr16(const LAS unsigned char* p) { return __builtin_bit_cast(u32x2, __builtin_amdgcn_ds_read_tr16_b64_v4i16((LAS v4i16_t*)p)); }
; #define MFMA16(a, b, c) __builtin_amdgcn_mfma_f32_16x16x32_bf16((a), (b), (c), 0, 0, 0)
; #define Z_LD(rs, off) __builtin_amdgcn_raw_buffer_load_b128(rs, (off), 0, 0)
; template <int TYPE, int NMC>
; __device__ __forceinline__ void sg_chain(LAS unsigned char* L, LAS float* SC, f32x4 (&S)[8], f32x4& nacc, int w, int r16, int q) {
;     ...
;     for (int mc = 0; mc < NMC; ++mc) {
;         oo[mc] = (f32x4){0.f, 0.f, 0.f, 0.f};
;         {
;             const LAS unsigned char* Qb = L + MX_Q + 16 * mc * MX_PITCH; const LAS unsigned char* Kb = L + MX_K + 16 * mc * MX_PITCH; const LAS unsigned char* Vb = L + MX_V + 16 * mc * MX_PITCH;
;             f32x4 g0 = {0.f, 0.f, 0.f, 0.f}, g1 = {0.f, 0.f, 0.f, 0.f};
; #pragma unroll
;             for (int ks = 0; ks < 4; ++ks) {
;                 const bf16x8 kf = ld8(Kb + r16 * MX_PITCH + (32 * ks + 8 * q) * 2), qf = ld8(Qb + r16 * MX_PITCH + (32 * ks + 8 * q) * 2);
;                 if (ks & 1) g1 = MFMA16(kf, qf, g1); else g0 = MFMA16(kf, qf, g0);
;             }
;             const f32x4 g = g0 + g1;
;             const float xi = SC[mc * 16 + r16]; const f32x4 y4 = *(const LAS f32x4*)(SC + 64 + mc * 16 + 4 * q);
;             f32x4 P;
; #pragma unroll
;             for (int r = 0; r < 4; ++r) P[r] = (4 * q + r <= r16) ? g[r] * __expf(xi + y4[r]) : 0.f;
;             if (TYPE == 0) { float ps = (P[0] + P[1]) + (P[2] + P[3]); ps += __shfl_xor(ps, 16); ps += __shfl_xor(ps, 32); if (w == 0 && q == 0) DI[16 * mc + r16] = ps; }
;             const u32x2 vt = tr16(Vb + (4 * q + (r16 >> 2)) * MX_PITCH + (16 * w + 4 * (r16 & 3)) * 2);
;             oo[mc] = mfma16k16((u32x2){pkbf(P[0], P[1]), pkbf(P[2], P[3])}, vt, oo[mc]);
;         }
;         if (mc == 1 || TYPE == 1) __builtin_amdgcn_sched_barrier(0);
; template <int TYPE>
; __device__ __forceinline__ void mix_sg_unit(Frame& F, int b, int h, int mode  , const float* rot) {
;     ...
;         if (sc + 1 < nsc) SG_LOAD(sc + 1);
;         { const __amdgpu_buffer_rsrc_t rz = Z_RSRC(ZROW(F, row0, 0), ntok); pg[0] = Z_LD(rz, zvo + 3072); pg[1] = Z_LD(rz, zvo + 3088); }
.LBB0_783:
	s_and_b64 s[26:27], s[24:25], exec
	s_cselect_b32 s26, 0x4400, s54
	s_cmpk_lt_i32 s26, 0x4000
	s_mov_b32 s27, 0x9700000
	s_cselect_b32 s27, 0x5900000, s27
	s_add_u32 s36, s94, s27
	s_addc_u32 s37, s95, 0
	s_ashr_i32 s27, s26, 31
	s_lshl_b64 s[34:35], s[26:27], 13
	s_add_u32 s68, s36, s34
	s_addc_u32 s27, s37, s35
	s_lshl_b32 s70, s55, 13
	s_and_b32 s69, s27, 0xffff
	buffer_load_dwordx4 v[32:35], v141, s[68:71], 0 offen
	buffer_load_dwordx4 v[28:31], v142, s[68:71], 0 offen
	v_lshl_add_u32 v52, v132, 2, s49
	ds_read_b32 v157, v52
	s_mov_b64 s[34:35], -1
	s_andn2_b64 vcc, exec, s[28:29]
	v_lshl_add_u32 v156, v144, 2, s49
	v_cvt_pk_bf16_f32 v48, v126, v127
	v_cvt_pk_bf16_f32 v49, v128, v129
	v_cvt_pk_bf16_f32 v50, v122, v123
	v_cvt_pk_bf16_f32 v51, v124, v125
	v_cvt_pk_bf16_f32 v36, v118, v119
	v_cvt_pk_bf16_f32 v37, v120, v121
	v_cvt_pk_bf16_f32 v38, v114, v115
	v_cvt_pk_bf16_f32 v39, v116, v117
	v_cvt_pk_bf16_f32 v40, v110, v111
	v_cvt_pk_bf16_f32 v41, v112, v113
	v_cvt_pk_bf16_f32 v42, v106, v107
	v_cvt_pk_bf16_f32 v43, v108, v109
	v_cvt_pk_bf16_f32 v44, v102, v103
	v_cvt_pk_bf16_f32 v45, v104, v105
	v_cvt_pk_bf16_f32 v46, v98, v99
	v_cvt_pk_bf16_f32 v47, v100, v101
	v_add_u32_e32 v155, 0x400, v154
	v_add_u32_e32 v97, v146, v147
	s_cbranch_vccnz .LBB0_785
	ds_read_b128 v[68:71], v151
	ds_read_b128 v[72:75], v151 offset:17408
	ds_read_b128 v[76:79], v151 offset:64
	ds_read_b128 v[80:83], v151 offset:17472
	ds_read_b128 v[84:87], v151 offset:128
	ds_read_b128 v[88:91], v151 offset:17536
	ds_read_b128 v[160:163], v151 offset:192
	ds_read_b128 v[164:167], v151 offset:17600
	ds_read_b32 v176, v52
	ds_read_b128 v[178:181], v156 offset:256
	ds_read_b64_tr_b16 v[182:183], v152 offset:52224
	v_mov_b32_e32 v158, s49
	v_mov_b32_e32 v184, 0
	v_mov_b32_e32 v185, 0
	v_mov_b32_e32 v194, 0
	v_mov_b32_e32 v195, 0
	v_mov_b32_e32 v198, 0
	v_mov_b32_e32 v199, 0
	s_waitcnt lgkmcnt(9)
	v_mfma_f32_16x16x32_bf16 v[168:171], v[72:75], v[68:71], 0
	s_waitcnt lgkmcnt(7)
	v_mfma_f32_16x16x32_bf16 v[172:175], v[80:83], v[76:79], 0
	s_waitcnt lgkmcnt(5)
	v_mfma_f32_16x16x32_bf16 v[168:171], v[88:91], v[84:87], v[168:171]
	s_waitcnt lgkmcnt(3)
	v_mfma_f32_16x16x32_bf16 v[172:175], v[164:167], v[160:163], v[172:175]
	ds_read_b128 v[68:71], v151 offset:4352
	ds_read_b128 v[72:75], v151 offset:21760
	ds_read_b128 v[76:79], v151 offset:4416
	ds_read_b128 v[80:83], v151 offset:21824
	ds_read_b128 v[84:87], v151 offset:4480
	ds_read_b128 v[88:91], v151 offset:21888
	ds_read_b128 v[160:163], v151 offset:4544
	ds_read_b128 v[164:167], v151 offset:21952
	ds_read_b32 v177, v52 offset:64
	ds_read_b128 v[186:189], v156 offset:320
	ds_read_b64_tr_b16 v[192:193], v152 offset:56576
	s_waitcnt lgkmcnt(11)
	v_pk_add_f32 v[200:201], v[168:169], v[172:173]
	v_pk_add_f32 v[202:203], v[170:171], v[174:175]
	v_add_f32_e32 v0, v176, v178
	v_add_f32_e32 v1, v176, v179
	v_add_f32_e32 v2, v176, v180
	v_add_f32_e32 v204, v176, v181
	v_mul_f32_e32 v0, 0x3fb8aa3b, v0
	v_mul_f32_e32 v1, 0x3fb8aa3b, v1
	v_mul_f32_e32 v2, 0x3fb8aa3b, v2
	v_mul_f32_e32 v204, 0x3fb8aa3b, v204
	v_exp_f32_e32 v0, v0
	v_exp_f32_e32 v1, v1
	v_exp_f32_e32 v2, v2
	v_exp_f32_e32 v204, v204
	v_mul_f32_e32 v0, v200, v0
	v_mul_f32_e32 v1, v201, v1
	v_mul_f32_e32 v2, v202, v2
	v_mul_f32_e32 v204, v203, v204
	v_cndmask_b32_e64 v0, v0, 0, s[12:13]
	v_cndmask_b32_e64 v1, 0, v1, s[14:15]
	v_cndmask_b32_e64 v2, v2, 0, s[16:17]
	v_cndmask_b32_e64 v204, v204, 0, s[18:19]
	v_cvt_pk_bf16_f32 v196, v0, v1
	v_cvt_pk_bf16_f32 v197, v2, v204
	s_nop 1
	v_mfma_f32_16x16x32_bf16 v[64:67], v[196:199], v[182:185], 0
	s_waitcnt lgkmcnt(9)
	v_mfma_f32_16x16x32_bf16 v[168:171], v[72:75], v[68:71], 0
	s_waitcnt lgkmcnt(7)
	v_mfma_f32_16x16x32_bf16 v[172:175], v[80:83], v[76:79], 0
	s_waitcnt lgkmcnt(5)
	v_mfma_f32_16x16x32_bf16 v[168:171], v[88:91], v[84:87], v[168:171]
	s_waitcnt lgkmcnt(3)
	v_mfma_f32_16x16x32_bf16 v[172:175], v[164:167], v[160:163], v[172:175]
	ds_read_b128 v[68:71], v151 offset:8704
	ds_read_b128 v[72:75], v151 offset:26112
	ds_read_b128 v[76:79], v151 offset:8768
	ds_read_b128 v[80:83], v151 offset:26176
	ds_read_b128 v[84:87], v151 offset:8832
	ds_read_b128 v[88:91], v151 offset:26240
	ds_read_b128 v[160:163], v151 offset:8896
	ds_read_b128 v[164:167], v151 offset:26304
	ds_read_b32 v176, v52 offset:128
	ds_read_b128 v[178:181], v156 offset:384
	ds_read_b64_tr_b16 v[182:183], v152 offset:60928
	s_waitcnt lgkmcnt(11)
	v_pk_add_f32 v[200:201], v[168:169], v[172:173]
	v_pk_add_f32 v[202:203], v[170:171], v[174:175]
	v_add_f32_e32 v0, v177, v186
	v_add_f32_e32 v1, v177, v187
	v_add_f32_e32 v2, v177, v188
	v_add_f32_e32 v204, v177, v189
	v_mul_f32_e32 v0, 0x3fb8aa3b, v0
	v_mul_f32_e32 v1, 0x3fb8aa3b, v1
	v_mul_f32_e32 v2, 0x3fb8aa3b, v2
	v_mul_f32_e32 v204, 0x3fb8aa3b, v204
	v_exp_f32_e32 v0, v0
	v_exp_f32_e32 v1, v1
	v_exp_f32_e32 v2, v2
	v_exp_f32_e32 v204, v204
	v_mul_f32_e32 v0, v200, v0
	v_mul_f32_e32 v1, v201, v1
	v_mul_f32_e32 v2, v202, v2
	v_mul_f32_e32 v204, v203, v204
	v_cndmask_b32_e64 v0, v0, 0, s[12:13]
	v_cndmask_b32_e64 v1, 0, v1, s[14:15]
	v_cndmask_b32_e64 v2, v2, 0, s[16:17]
	v_cndmask_b32_e64 v204, v204, 0, s[18:19]
	v_cvt_pk_bf16_f32 v196, v0, v1
	v_cvt_pk_bf16_f32 v197, v2, v204
	s_nop 1
	v_mfma_f32_16x16x32_bf16 v[60:63], v[196:199], v[192:195], 0
	s_waitcnt lgkmcnt(9)
	v_mfma_f32_16x16x32_bf16 v[168:171], v[72:75], v[68:71], 0
	s_waitcnt lgkmcnt(7)
	v_mfma_f32_16x16x32_bf16 v[172:175], v[80:83], v[76:79], 0
	s_waitcnt lgkmcnt(5)
	v_mfma_f32_16x16x32_bf16 v[168:171], v[88:91], v[84:87], v[168:171]
	s_waitcnt lgkmcnt(3)
; template <int TYPE, int NMC>
; __device__ __forceinline__ void sg_chain(LAS unsigned char* L, LAS float* SC, f32x4 (&S)[8], f32x4& nacc, int w, int r16, int q) {
;     ...
;     for (int mc = 0; mc < NMC; ++mc) {
;         oo[mc] = (f32x4){0.f, 0.f, 0.f, 0.f};
;         {
;             const LAS unsigned char* Qb = L + MX_Q + 16 * mc * MX_PITCH; const LAS unsigned char* Kb = L + MX_K + 16 * mc * MX_PITCH; const LAS unsigned char* Vb = L + MX_V + 16 * mc * MX_PITCH;
;             f32x4 g0 = {0.f, 0.f, 0.f, 0.f}, g1 = {0.f, 0.f, 0.f, 0.f};
; #pragma unroll
;             for (int ks = 0; ks < 4; ++ks) {
;                 const bf16x8 kf = ld8(Kb + r16 * MX_PITCH + (32 * ks + 8 * q) * 2), qf = ld8(Qb + r16 * MX_PITCH + (32 * ks + 8 * q) * 2);
;                 if (ks & 1) g1 = MFMA16(kf, qf, g1); else g0 = MFMA16(kf, qf, g0);
;             }
;             const f32x4 g = g0 + g1;
;             const float xi = SC[mc * 16 + r16]; const f32x4 y4 = *(const LAS f32x4*)(SC + 64 + mc * 16 + 4 * q);
;             f32x4 P;
; #pragma unroll
;             for (int r = 0; r < 4; ++r) P[r] = (4 * q + r <= r16) ? g[r] * __expf(xi + y4[r]) : 0.f;
;             if (TYPE == 0) { float ps = (P[0] + P[1]) + (P[2] + P[3]); ps += __shfl_xor(ps, 16); ps += __shfl_xor(ps, 32); if (w == 0 && q == 0) DI[16 * mc + r16] = ps; }
;             const u32x2 vt = tr16(Vb + (4 * q + (r16 >> 2)) * MX_PITCH + (16 * w + 4 * (r16 & 3)) * 2);
;             oo[mc] = mfma16k16((u32x2){pkbf(P[0], P[1]), pkbf(P[2], P[3])}, vt, oo[mc]);
;         }
;         if (mc == 1 || TYPE == 1) __builtin_amdgcn_sched_barrier(0);
;     }
; #pragma unroll
;     for (int mc = 0; mc < NMC; ++mc) {
;         {
;             const LAS unsigned char* Qb = L + MX_Q + 16 * mc * MX_PITCH; const LAS unsigned char* Kb = L + MX_K + 16 * mc * MX_PITCH;
;             const u32x2 vt = tr16(L + MX_V + 16 * mc * MX_PITCH + (4 * q + (r16 >> 2)) * MX_PITCH + (16 * w + 4 * (r16 & 3)) * 2);
;             f32x4 o2a = {0.f, 0.f, 0.f, 0.f}, o2b = {0.f, 0.f, 0.f, 0.f};
; #pragma unroll
;             for (int ks = 0; ks < 4; ++ks) {
;                 const bf16x8 qf = ld8(Qb + r16 * MX_PITCH + (32 * ks + 8 * q) * 2);
;                 const bf16x8 SB = mk8(pkbf(S[2 * ks][0], S[2 * ks][1]), pkbf(S[2 * ks][2], S[2 * ks][3]), pkbf(S[2 * ks + 1][0], S[2 * ks + 1][1]), pkbf(S[2 * ks + 1][2], S[2 * ks + 1][3]));
	v_mfma_f32_16x16x32_bf16 v[172:175], v[164:167], v[160:163], v[172:175]
	ds_read_b128 v[68:71], v151 offset:13056
	ds_read_b128 v[72:75], v151 offset:30464
	ds_read_b128 v[76:79], v151 offset:13120
	ds_read_b128 v[80:83], v151 offset:30528
	ds_read_b128 v[84:87], v151 offset:13184
	ds_read_b128 v[88:91], v151 offset:30592
	ds_read_b128 v[160:163], v151 offset:13248
	ds_read_b128 v[164:167], v151 offset:30656
	ds_read_b32 v177, v52 offset:192
	ds_read_b128 v[186:189], v156 offset:448
	ds_read_b64_tr_b16 v[192:193], v152 offset:65280
	s_waitcnt lgkmcnt(11)
	v_pk_add_f32 v[200:201], v[168:169], v[172:173]
	v_pk_add_f32 v[202:203], v[170:171], v[174:175]
	v_add_f32_e32 v0, v176, v178
	v_add_f32_e32 v1, v176, v179
	v_add_f32_e32 v2, v176, v180
	v_add_f32_e32 v204, v176, v181
	v_mul_f32_e32 v0, 0x3fb8aa3b, v0
	v_mul_f32_e32 v1, 0x3fb8aa3b, v1
	v_mul_f32_e32 v2, 0x3fb8aa3b, v2
	v_mul_f32_e32 v204, 0x3fb8aa3b, v204
	v_exp_f32_e32 v0, v0
	v_exp_f32_e32 v1, v1
	v_exp_f32_e32 v2, v2
	v_exp_f32_e32 v204, v204
	v_mul_f32_e32 v0, v200, v0
	v_mul_f32_e32 v1, v201, v1
	v_mul_f32_e32 v2, v202, v2
	v_mul_f32_e32 v204, v203, v204
	v_cndmask_b32_e64 v0, v0, 0, s[12:13]
	v_cndmask_b32_e64 v1, 0, v1, s[14:15]
	v_cndmask_b32_e64 v2, v2, 0, s[16:17]
	v_cndmask_b32_e64 v204, v204, 0, s[18:19]
	v_cvt_pk_bf16_f32 v196, v0, v1
	v_cvt_pk_bf16_f32 v197, v2, v204
	s_nop 1
	v_mfma_f32_16x16x32_bf16 v[56:59], v[196:199], v[182:185], 0
	s_waitcnt lgkmcnt(9)
	v_mfma_f32_16x16x32_bf16 v[168:171], v[72:75], v[68:71], 0
	s_waitcnt lgkmcnt(7)
	v_mfma_f32_16x16x32_bf16 v[172:175], v[80:83], v[76:79], 0
	s_waitcnt lgkmcnt(5)
	v_mfma_f32_16x16x32_bf16 v[168:171], v[88:91], v[84:87], v[168:171]
	s_waitcnt lgkmcnt(3)
	v_mfma_f32_16x16x32_bf16 v[172:175], v[164:167], v[160:163], v[172:175]
	s_waitcnt lgkmcnt(0)
	s_nop 7
	v_pk_add_f32 v[200:201], v[168:169], v[172:173]
	v_pk_add_f32 v[202:203], v[170:171], v[174:175]
	v_add_f32_e32 v0, v177, v186
	v_add_f32_e32 v1, v177, v187
	v_add_f32_e32 v2, v177, v188
	v_add_f32_e32 v204, v177, v189
	v_mul_f32_e32 v0, 0x3fb8aa3b, v0
	v_mul_f32_e32 v1, 0x3fb8aa3b, v1
	v_mul_f32_e32 v2, 0x3fb8aa3b, v2
	v_mul_f32_e32 v204, 0x3fb8aa3b, v204
	v_exp_f32_e32 v0, v0
	v_exp_f32_e32 v1, v1
	v_exp_f32_e32 v2, v2
	v_exp_f32_e32 v204, v204
	v_mul_f32_e32 v0, v200, v0
	v_mul_f32_e32 v1, v201, v1
	v_mul_f32_e32 v2, v202, v2
	v_mul_f32_e32 v204, v203, v204
	v_cndmask_b32_e64 v0, v0, 0, s[12:13]
	v_cndmask_b32_e64 v1, 0, v1, s[14:15]
	v_cndmask_b32_e64 v2, v2, 0, s[16:17]
	v_cndmask_b32_e64 v204, v204, 0, s[18:19]
	v_cvt_pk_bf16_f32 v196, v0, v1
	v_cvt_pk_bf16_f32 v197, v2, v204
	s_nop 1
	v_mfma_f32_16x16x32_bf16 v[52:55], v[196:199], v[192:195], 0
	v_mov_b32_e32 v2, v3
	ds_read_b64_tr_b16 v[0:1], v153 offset:52224
	ds_read_b128 v[68:71], v151
	ds_read_b128 v[72:75], v151 offset:64
	ds_read_b128 v[76:79], v151 offset:128
	s_waitcnt lgkmcnt(2)
	v_mfma_f32_16x16x32_bf16 v[68:71], v[68:71], v[48:51], 0
	s_waitcnt lgkmcnt(0)
	v_mfma_f32_16x16x32_bf16 v[68:71], v[76:79], v[40:43], v[68:71]
	ds_read_b128 v[76:79], v151 offset:192
	v_mfma_f32_16x16x32_bf16 v[72:75], v[72:75], v[36:39], 0
	s_waitcnt lgkmcnt(0)
	v_mfma_f32_16x16x32_bf16 v[72:75], v[76:79], v[44:47], v[72:75]
	ds_read_b128 v[76:79], v156 offset:512
	s_nop 6
	v_pk_add_f32 v[70:71], v[70:71], v[74:75]
	v_pk_add_f32 v[68:69], v[68:69], v[72:73]
	s_waitcnt lgkmcnt(0)
	v_pk_fma_f32 v[70:71], v[70:71], v[78:79], v[66:67]
	v_pk_fma_f32 v[68:69], v[68:69], v[76:77], v[64:65]
	ds_read_b128 v[64:67], v156 offset:768
	ds_read_b32 v92, v158 offset:1280
	ds_write2_b32 v154, v68, v69 offset1:132
	ds_write2_b32 v155, v70, v71 offset0:8 offset1:140
	v_lshlrev_b32_e32 v68, 16, v0
	v_and_b32_e32 v69, 0xffff0000, v0
	v_mov_b32_e32 v70, v3
	v_mov_b32_e32 v71, v3
	s_waitcnt lgkmcnt(3)
	v_pk_mul_f32 v[64:65], v[64:65], v[68:69]
	ds_read_b64_tr_b16 v[68:69], v97 offset:17408
	ds_read_b64_tr_b16 v[72:73], v97 offset:17416
	v_cvt_pk_bf16_f32 v0, v64, v65
	v_lshlrev_b32_e32 v64, 16, v1
	v_and_b32_e32 v65, 0xffff0000, v1
	v_pk_mul_f32 v[64:65], v[66:67], v[64:65]
	s_waitcnt lgkmcnt(4)
	v_pk_mul_f32 v[66:67], v[128:129], v[92:93] op_sel_hi:[1,0]
	v_cvt_pk_bf16_f32 v1, v64, v65
	v_pk_mul_f32 v[64:65], v[126:127], v[92:93] op_sel_hi:[1,0]
	v_mov_b32_e32 v74, v3
	v_mov_b32_e32 v75, v3
	s_waitcnt lgkmcnt(1)
	v_mfma_f32_16x16x32_bf16 v[84:87], v[68:71], v[0:3], v[64:67]
	ds_read_b64_tr_b16 v[68:69], v97 offset:17472
	v_pk_mul_f32 v[78:79], v[116:117], v[92:93] op_sel_hi:[1,0]
	v_pk_mul_f32 v[76:77], v[114:115], v[92:93] op_sel_hi:[1,0]
	v_pk_mul_f32 v[66:67], v[124:125], v[92:93] op_sel_hi:[1,0]
	v_pk_mul_f32 v[64:65], v[122:123], v[92:93] op_sel_hi:[1,0]
	v_pk_mul_f32 v[162:163], v[104:105], v[92:93] op_sel_hi:[1,0]
	v_pk_mul_f32 v[160:161], v[102:103], v[92:93] op_sel_hi:[1,0]
	s_waitcnt lgkmcnt(1)
	v_mfma_f32_16x16x32_bf16 v[64:67], v[72:75], v[0:3], v[64:67]
	v_mul_f32_e64 v74, v120, v92
	v_mul_f32_e64 v75, v121, v92
	v_pk_mul_f32 v[72:73], v[118:119], v[92:93] op_sel_hi:[1,0]
	v_pk_mul_f32 v[94:95], v[100:101], v[92:93] op_sel_hi:[1,0]
	s_waitcnt lgkmcnt(0)
	v_mfma_f32_16x16x32_bf16 v[68:71], v[68:71], v[0:3], v[72:75]
	s_nop 2
	ds_read_b64_tr_b16 v[72:73], v97 offset:17480
	v_mov_b32_e32 v74, v3
	v_mov_b32_e32 v75, v3
	s_waitcnt lgkmcnt(0)
	s_nop 0
	v_mfma_f32_16x16x32_bf16 v[88:91], v[72:75], v[0:3], v[76:79]
	ds_read_b64_tr_b16 v[72:73], v97 offset:17536
	s_nop 1
	v_pk_mul_f32 v[78:79], v[112:113], v[92:93] op_sel_hi:[1,0]
	v_pk_mul_f32 v[76:77], v[110:111], v[92:93] op_sel_hi:[1,0]
	s_waitcnt lgkmcnt(0)
; template <int TYPE, int NMC>
; __device__ __forceinline__ void sg_chain(LAS unsigned char* L, LAS float* SC, f32x4 (&S)[8], f32x4& nacc, int w, int r16, int q) {
;     ...
;     for (int mc = 0; mc < NMC; ++mc) {
;         {
;             const LAS unsigned char* Qb = L + MX_Q + 16 * mc * MX_PITCH; const LAS unsigned char* Kb = L + MX_K + 16 * mc * MX_PITCH;
;             const u32x2 vt = tr16(L + MX_V + 16 * mc * MX_PITCH + (4 * q + (r16 >> 2)) * MX_PITCH + (16 * w + 4 * (r16 & 3)) * 2);
;             f32x4 o2a = {0.f, 0.f, 0.f, 0.f}, o2b = {0.f, 0.f, 0.f, 0.f};
; #pragma unroll
;             for (int ks = 0; ks < 4; ++ks) {
;                 const bf16x8 qf = ld8(Qb + r16 * MX_PITCH + (32 * ks + 8 * q) * 2);
;                 const bf16x8 SB = mk8(pkbf(S[2 * ks][0], S[2 * ks][1]), pkbf(S[2 * ks][2], S[2 * ks][3]), pkbf(S[2 * ks + 1][0], S[2 * ks + 1][1]), pkbf(S[2 * ks + 1][2], S[2 * ks + 1][3]));
;                 if (ks & 1) o2b = MFMA16(qf, SB, o2b); else o2a = MFMA16(qf, SB, o2a);
;             }
;             const f32x4 in4 = *(const LAS f32x4*)(SC + 128 + mc * 16 + 4 * q);
;             oo[mc] = oo[mc] + in4 * (o2a + o2b);
;             const f32x4 w4 = *(const LAS f32x4*)(SC + 192 + mc * 16 + 4 * q); const float carry = SC[320 + mc];
;             if (TYPE == 0) {
;                 const u32x2 qn = *(const LAS u32x2*)(Qb + r16 * MX_PITCH + MX_POS4(16 * w + 4 * q) * 2);
;                 f32x4 rr = {0.f, 0.f, 0.f, 0.f}; rr = mfma16k16(qn, (u32x2){pkbf(nacc[0], nacc[1]), pkbf(nacc[2], nacc[3])}, rr);
;                 if (r16 == 0) {
; #pragma unroll
;                     for (int r = 0; r < 4; ++r) RP[w * 64 + 16 * mc + 4 * q + r] = rr[r]; }
;             }
; #pragma unroll
;             for (int r = 0; r < 4; ++r) OB[(16 * mc + 4 * q + r) * MX_OP + 16 * w + r16] = oo[mc][r];
;             const u32x2 VH = {pkbf(bflo(vt.x) * w4[0], bfhi(vt.x) * w4[1]), pkbf(bflo(vt.y) * w4[2], bfhi(vt.y) * w4[3])};
; #pragma unroll
;             for (int mt = 0; mt < 8; ++mt) {
;                 const u32x2 kt = tr16(Kb + (4 * q + (r16 >> 2)) * MX_PITCH + MX_POS4(16 * mt + 4 * (r16 & 3)) * 2);
;                 S[mt] = S[mt] * carry; S[mt] = mfma16k16(kt, VH, S[mt]);
;             }
;             if (TYPE == 0) {
;                 const u32x2 kt = tr16(Kb + (4 * q + (r16 >> 2)) * MX_PITCH + MX_POS4(16 * w + 4 * (r16 & 3)) * 2);
	s_nop 0
	v_mfma_f32_16x16x32_bf16 v[80:83], v[72:75], v[0:3], v[76:79]
	ds_read_b64_tr_b16 v[72:73], v97 offset:17544
	s_nop 1
	v_pk_mul_f32 v[78:79], v[108:109], v[92:93] op_sel_hi:[1,0]
	v_pk_mul_f32 v[76:77], v[106:107], v[92:93] op_sel_hi:[1,0]
	v_pk_mul_f32 v[92:93], v[98:99], v[92:93] op_sel_hi:[1,0]
	s_waitcnt lgkmcnt(0)
	v_mfma_f32_16x16x32_bf16 v[72:75], v[72:75], v[0:3], v[76:79]
	s_nop 2
	ds_read_b64_tr_b16 v[76:77], v97 offset:17600
	v_mov_b32_e32 v78, v3
	v_mov_b32_e32 v79, v3
	s_waitcnt lgkmcnt(0)
	s_nop 0
	v_mfma_f32_16x16x32_bf16 v[76:79], v[76:79], v[0:3], v[160:163]
	s_nop 2
	ds_read_b64_tr_b16 v[160:161], v97 offset:17608
	v_mov_b32_e32 v162, v3
	v_mov_b32_e32 v163, v3
	s_waitcnt lgkmcnt(0)
	s_nop 0
	v_mfma_f32_16x16x32_bf16 v[92:95], v[160:163], v[0:3], v[92:95]
	ds_read_b128 v[164:167], v151 offset:4352
	ds_read_b128 v[168:171], v151 offset:4416
	ds_read_b64_tr_b16 v[0:1], v153 offset:56576
	ds_read_b128 v[172:175], v151 offset:4480
	v_cvt_pk_bf16_f32 v160, v84, v85
	v_cvt_pk_bf16_f32 v161, v86, v87
	v_cvt_pk_bf16_f32 v162, v64, v65
	v_cvt_pk_bf16_f32 v163, v66, v67
	v_add_u32_e32 v2, 0x2000, v154
	s_waitcnt lgkmcnt(3)
	v_mfma_f32_16x16x32_bf16 v[160:163], v[164:167], v[160:163], 0
	v_cvt_pk_bf16_f32 v164, v68, v69
	v_cvt_pk_bf16_f32 v165, v70, v71
	v_cvt_pk_bf16_f32 v166, v88, v89
	v_cvt_pk_bf16_f32 v167, v90, v91
	s_waitcnt lgkmcnt(2)
	s_nop 0
	v_mfma_f32_16x16x32_bf16 v[164:167], v[168:171], v[164:167], 0
	v_cvt_pk_bf16_f32 v168, v80, v81
	v_cvt_pk_bf16_f32 v169, v82, v83
	v_cvt_pk_bf16_f32 v170, v72, v73
	v_cvt_pk_bf16_f32 v171, v74, v75
	s_waitcnt lgkmcnt(0)
	s_nop 0
	v_mfma_f32_16x16x32_bf16 v[160:163], v[172:175], v[168:171], v[160:163]
	ds_read_b128 v[172:175], v151 offset:4544
	v_cvt_pk_bf16_f32 v168, v76, v77
	v_cvt_pk_bf16_f32 v169, v78, v79
	v_cvt_pk_bf16_f32 v170, v92, v93
	v_cvt_pk_bf16_f32 v171, v94, v95
	s_waitcnt lgkmcnt(0)
	s_nop 0
	v_mfma_f32_16x16x32_bf16 v[164:167], v[172:175], v[168:171], v[164:167]
	ds_read_b128 v[168:171], v156 offset:576
	s_nop 6
	v_pk_add_f32 v[162:163], v[162:163], v[166:167]
	v_pk_add_f32 v[160:161], v[160:161], v[164:165]
	s_waitcnt lgkmcnt(0)
	v_pk_fma_f32 v[162:163], v[162:163], v[170:171], v[62:63]
	v_pk_fma_f32 v[160:161], v[160:161], v[168:169], v[60:61]
	ds_read_b128 v[60:63], v156 offset:832
	ds_read_b32 v130, v158 offset:1284
	ds_write2_b32 v2, v160, v161 offset0:64 offset1:196
	v_lshlrev_b32_e32 v160, 16, v0
	v_and_b32_e32 v161, 0xffff0000, v0
	s_waitcnt lgkmcnt(2)
	v_pk_mul_f32 v[60:61], v[60:61], v[160:161]
	v_add_u32_e32 v2, 0x2400, v154
	v_cvt_pk_bf16_f32 v0, v60, v61
	v_lshlrev_b32_e32 v60, 16, v1
	v_and_b32_e32 v61, 0xffff0000, v1
	ds_write2_b32 v2, v162, v163 offset0:72 offset1:204
	v_pk_mul_f32 v[60:61], v[62:63], v[60:61]
	s_waitcnt lgkmcnt(2)
	v_pk_mul_f32 v[62:63], v[86:87], v[130:131] op_sel_hi:[1,0]
	v_mov_b32_e32 v86, v3
	v_mov_b32_e32 v87, v3
	v_cvt_pk_bf16_f32 v1, v60, v61
	v_pk_mul_f32 v[60:61], v[84:85], v[130:131] op_sel_hi:[1,0]
	ds_read_b64_tr_b16 v[84:85], v97 offset:21760
	ds_read_b64_tr_b16 v[160:161], v97 offset:21768
	v_mov_b32_e32 v2, v3
	v_pk_mul_f32 v[70:71], v[70:71], v[130:131] op_sel_hi:[1,0]
	v_pk_mul_f32 v[68:69], v[68:69], v[130:131] op_sel_hi:[1,0]
	s_waitcnt lgkmcnt(1)
	v_mfma_f32_16x16x32_bf16 v[84:87], v[84:87], v[0:3], v[60:63]
	v_mul_f32_e64 v90, v90, v130
	v_mul_f32_e64 v91, v91, v130
	v_pk_mul_f32 v[88:89], v[88:89], v[130:131] op_sel_hi:[1,0]
	v_pk_mul_f32 v[82:83], v[82:83], v[130:131] op_sel_hi:[1,0]
	v_pk_mul_f32 v[60:61], v[64:65], v[130:131] op_sel_hi:[1,0]
	ds_read_b64_tr_b16 v[64:65], v97 offset:21824
	v_pk_mul_f32 v[62:63], v[66:67], v[130:131] op_sel_hi:[1,0]
	v_mov_b32_e32 v66, v3
	v_mov_b32_e32 v67, v3
	v_pk_mul_f32 v[80:81], v[80:81], v[130:131] op_sel_hi:[1,0]
	v_pk_mul_f32 v[74:75], v[74:75], v[130:131] op_sel_hi:[1,0]
	s_waitcnt lgkmcnt(0)
	v_mfma_f32_16x16x32_bf16 v[64:67], v[64:67], v[0:3], v[68:71]
	s_nop 2
	ds_read_b64_tr_b16 v[68:69], v97 offset:21832
	v_mov_b32_e32 v70, v3
	v_mov_b32_e32 v71, v3
	v_pk_mul_f32 v[72:73], v[72:73], v[130:131] op_sel_hi:[1,0]
	v_pk_mul_f32 v[78:79], v[78:79], v[130:131] op_sel_hi:[1,0]
	s_waitcnt lgkmcnt(0)
	v_mfma_f32_16x16x32_bf16 v[88:91], v[68:71], v[0:3], v[88:91]
	ds_read_b64_tr_b16 v[68:69], v97 offset:21888
	v_pk_mul_f32 v[76:77], v[76:77], v[130:131] op_sel_hi:[1,0]
	v_mov_b32_e32 v162, v3
	s_waitcnt lgkmcnt(0)
	v_mfma_f32_16x16x32_bf16 v[80:83], v[68:71], v[0:3], v[80:83]
	ds_read_b64_tr_b16 v[68:69], v97 offset:21896
	v_mov_b32_e32 v163, v3
	v_pk_mul_f32 v[94:95], v[94:95], v[130:131] op_sel_hi:[1,0]
	s_waitcnt lgkmcnt(0)
	v_mfma_f32_16x16x32_bf16 v[68:71], v[68:71], v[0:3], v[72:75]
	s_nop 2
	ds_read_b64_tr_b16 v[72:73], v97 offset:21952
	v_mov_b32_e32 v74, v3
	v_mov_b32_e32 v75, v3
	v_mfma_f32_16x16x32_bf16 v[60:63], v[160:163], v[0:3], v[60:63]
	v_mul_f32_e64 v92, v92, v130
	v_mul_f32_e64 v93, v93, v130
	s_waitcnt lgkmcnt(0)
	v_mfma_f32_16x16x32_bf16 v[72:75], v[72:75], v[0:3], v[76:79]
	s_nop 2
	ds_read_b64_tr_b16 v[76:77], v97 offset:21960
	v_mov_b32_e32 v78, v3
	v_mov_b32_e32 v79, v3
	s_waitcnt lgkmcnt(0)
	s_nop 0
	v_mfma_f32_16x16x32_bf16 v[92:95], v[76:79], v[0:3], v[92:95]
	ds_read_b128 v[160:163], v151 offset:8704
	ds_read_b128 v[164:167], v151 offset:8768
	ds_read_b64_tr_b16 v[0:1], v153 offset:60928
	ds_read_b128 v[168:171], v151 offset:8832
	v_cvt_pk_bf16_f32 v76, v84, v85
	v_cvt_pk_bf16_f32 v77, v86, v87
	v_cvt_pk_bf16_f32 v78, v60, v61
	v_cvt_pk_bf16_f32 v79, v62, v63
	v_add_u32_e32 v2, 0x4200, v154
	s_waitcnt lgkmcnt(3)
	v_mfma_f32_16x16x32_bf16 v[76:79], v[160:163], v[76:79], 0
	v_cvt_pk_bf16_f32 v160, v64, v65
	v_cvt_pk_bf16_f32 v161, v66, v67
	v_cvt_pk_bf16_f32 v162, v88, v89
	v_cvt_pk_bf16_f32 v163, v90, v91
	s_waitcnt lgkmcnt(2)
; #define LAS __attribute__((address_space(3)))
; #define MFMA16(a, b, c) __builtin_amdgcn_mfma_f32_16x16x32_bf16((a), (b), (c), 0, 0, 0)
; template <int TYPE, int NMC>
; __device__ __forceinline__ void sg_chain(LAS unsigned char* L, LAS float* SC, f32x4 (&S)[8], f32x4& nacc, int w, int r16, int q) {
;     ...
;     for (int mc = 0; mc < NMC; ++mc) {
;         {
;             const LAS unsigned char* Qb = L + MX_Q + 16 * mc * MX_PITCH; const LAS unsigned char* Kb = L + MX_K + 16 * mc * MX_PITCH;
;             const u32x2 vt = tr16(L + MX_V + 16 * mc * MX_PITCH + (4 * q + (r16 >> 2)) * MX_PITCH + (16 * w + 4 * (r16 & 3)) * 2);
;             f32x4 o2a = {0.f, 0.f, 0.f, 0.f}, o2b = {0.f, 0.f, 0.f, 0.f};
; #pragma unroll
;             for (int ks = 0; ks < 4; ++ks) {
;                 const bf16x8 qf = ld8(Qb + r16 * MX_PITCH + (32 * ks + 8 * q) * 2);
;                 const bf16x8 SB = mk8(pkbf(S[2 * ks][0], S[2 * ks][1]), pkbf(S[2 * ks][2], S[2 * ks][3]), pkbf(S[2 * ks + 1][0], S[2 * ks + 1][1]), pkbf(S[2 * ks + 1][2], S[2 * ks + 1][3]));
;                 if (ks & 1) o2b = MFMA16(qf, SB, o2b); else o2a = MFMA16(qf, SB, o2a);
;             }
;             const f32x4 in4 = *(const LAS f32x4*)(SC + 128 + mc * 16 + 4 * q);
;             oo[mc] = oo[mc] + in4 * (o2a + o2b);
;             const f32x4 w4 = *(const LAS f32x4*)(SC + 192 + mc * 16 + 4 * q); const float carry = SC[320 + mc];
;             if (TYPE == 0) {
;                 const u32x2 qn = *(const LAS u32x2*)(Qb + r16 * MX_PITCH + MX_POS4(16 * w + 4 * q) * 2);
;                 f32x4 rr = {0.f, 0.f, 0.f, 0.f}; rr = mfma16k16(qn, (u32x2){pkbf(nacc[0], nacc[1]), pkbf(nacc[2], nacc[3])}, rr);
;                 if (r16 == 0) {
; #pragma unroll
;                     for (int r = 0; r < 4; ++r) RP[w * 64 + 16 * mc + 4 * q + r] = rr[r]; }
;             }
; #pragma unroll
;             for (int r = 0; r < 4; ++r) OB[(16 * mc + 4 * q + r) * MX_OP + 16 * w + r16] = oo[mc][r];
;             const u32x2 VH = {pkbf(bflo(vt.x) * w4[0], bfhi(vt.x) * w4[1]), pkbf(bflo(vt.y) * w4[2], bfhi(vt.y) * w4[3])};
; #pragma unroll
;             for (int mt = 0; mt < 8; ++mt) {
;                 const u32x2 kt = tr16(Kb + (4 * q + (r16 >> 2)) * MX_PITCH + MX_POS4(16 * mt + 4 * (r16 & 3)) * 2);
;                 S[mt] = S[mt] * carry; S[mt] = mfma16k16(kt, VH, S[mt]);
	s_nop 0
	v_mfma_f32_16x16x32_bf16 v[160:163], v[164:167], v[160:163], 0
	v_cvt_pk_bf16_f32 v164, v80, v81
	v_cvt_pk_bf16_f32 v165, v82, v83
	v_cvt_pk_bf16_f32 v166, v68, v69
	v_cvt_pk_bf16_f32 v167, v70, v71
	s_waitcnt lgkmcnt(0)
	s_nop 0
	v_mfma_f32_16x16x32_bf16 v[76:79], v[168:171], v[164:167], v[76:79]
	ds_read_b128 v[168:171], v151 offset:8896
	v_cvt_pk_bf16_f32 v164, v72, v73
	v_cvt_pk_bf16_f32 v165, v74, v75
	v_cvt_pk_bf16_f32 v166, v92, v93
	v_cvt_pk_bf16_f32 v167, v94, v95
	s_waitcnt lgkmcnt(0)
	s_nop 0
	v_mfma_f32_16x16x32_bf16 v[160:163], v[168:171], v[164:167], v[160:163]
	ds_read_b128 v[164:167], v156 offset:640
	s_nop 6
	v_pk_add_f32 v[78:79], v[78:79], v[162:163]
	v_pk_add_f32 v[76:77], v[76:77], v[160:161]
	s_waitcnt lgkmcnt(0)
	v_pk_fma_f32 v[78:79], v[78:79], v[166:167], v[58:59]
	v_pk_fma_f32 v[76:77], v[76:77], v[164:165], v[56:57]
	ds_read_b128 v[56:59], v156 offset:896
	ds_read_b32 v130, v158 offset:1288
	ds_write2_b32 v2, v76, v77 offset1:132
	v_lshlrev_b32_e32 v76, 16, v0
	v_and_b32_e32 v77, 0xffff0000, v0
	s_waitcnt lgkmcnt(2)
	v_pk_mul_f32 v[56:57], v[56:57], v[76:77]
	v_add_u32_e32 v2, 0x4600, v154
	v_cvt_pk_bf16_f32 v0, v56, v57
	v_lshlrev_b32_e32 v56, 16, v1
	v_and_b32_e32 v57, 0xffff0000, v1
	ds_write2_b32 v2, v78, v79 offset0:8 offset1:140
	v_pk_mul_f32 v[56:57], v[58:59], v[56:57]
	v_mov_b32_e32 v78, v3
	v_mov_b32_e32 v79, v3
	v_cvt_pk_bf16_f32 v1, v56, v57
	s_waitcnt lgkmcnt(2)
	v_pk_mul_f32 v[56:57], v[84:85], v[130:131] op_sel_hi:[1,0]
	ds_read_b64_tr_b16 v[76:77], v97 offset:26112
	ds_read_b64_tr_b16 v[84:85], v97 offset:26120
	v_mov_b32_e32 v2, v3
	v_pk_mul_f32 v[58:59], v[86:87], v[130:131] op_sel_hi:[1,0]
	v_pk_mul_f32 v[66:67], v[66:67], v[130:131] op_sel_hi:[1,0]
	v_pk_mul_f32 v[64:65], v[64:65], v[130:131] op_sel_hi:[1,0]
	s_waitcnt lgkmcnt(1)
	v_mfma_f32_16x16x32_bf16 v[56:59], v[76:79], v[0:3], v[56:59]
	ds_read_b64_tr_b16 v[76:77], v97 offset:26176
	v_mov_b32_e32 v86, v3
	v_mov_b32_e32 v87, v3
	s_waitcnt lgkmcnt(0)
	v_mfma_f32_16x16x32_bf16 v[64:67], v[76:79], v[0:3], v[64:67]
	ds_read_b64_tr_b16 v[76:77], v97 offset:26184
	v_pk_mul_f32 v[62:63], v[62:63], v[130:131] op_sel_hi:[1,0]
	v_pk_mul_f32 v[60:61], v[60:61], v[130:131] op_sel_hi:[1,0]
	v_pk_mul_f32 v[82:83], v[82:83], v[130:131] op_sel_hi:[1,0]
	v_pk_mul_f32 v[80:81], v[80:81], v[130:131] op_sel_hi:[1,0]
	v_mfma_f32_16x16x32_bf16 v[60:63], v[84:87], v[0:3], v[60:63]
	v_mul_f32_e64 v86, v90, v130
	v_mul_f32_e64 v87, v91, v130
	v_pk_mul_f32 v[84:85], v[88:89], v[130:131] op_sel_hi:[1,0]
	v_pk_mul_f32 v[70:71], v[70:71], v[130:131] op_sel_hi:[1,0]
	v_pk_mul_f32 v[68:69], v[68:69], v[130:131] op_sel_hi:[1,0]
	s_waitcnt lgkmcnt(0)
	v_mfma_f32_16x16x32_bf16 v[88:91], v[76:79], v[0:3], v[84:87]
	ds_read_b64_tr_b16 v[76:77], v97 offset:26240
	v_pk_mul_f32 v[74:75], v[74:75], v[130:131] op_sel_hi:[1,0]
	v_pk_mul_f32 v[72:73], v[72:73], v[130:131] op_sel_hi:[1,0]
	s_waitcnt lgkmcnt(0)
	v_mfma_f32_16x16x32_bf16 v[84:87], v[76:79], v[0:3], v[80:83]
	ds_read_b64_tr_b16 v[76:77], v97 offset:26248
	s_waitcnt lgkmcnt(0)
	v_mfma_f32_16x16x32_bf16 v[76:79], v[76:79], v[0:3], v[68:71]
	s_nop 2
	ds_read_b64_tr_b16 v[68:69], v97 offset:26304
	v_mov_b32_e32 v70, v3
	v_mov_b32_e32 v71, v3
	s_waitcnt lgkmcnt(0)
	s_nop 0
	v_mfma_f32_16x16x32_bf16 v[80:83], v[68:71], v[0:3], v[72:75]
	ds_read_b64_tr_b16 v[68:69], v97 offset:26312
	s_nop 1
	v_pk_mul_f32 v[74:75], v[94:95], v[130:131] op_sel_hi:[1,0]
	v_pk_mul_f32 v[72:73], v[92:93], v[130:131] op_sel_hi:[1,0]
	s_waitcnt lgkmcnt(0)
	s_nop 0
	v_mfma_f32_16x16x32_bf16 v[92:95], v[68:71], v[0:3], v[72:75]
	s_nop 2
	ds_read_b128 v[72:75], v151 offset:13056
	ds_read_b128 v[160:163], v151 offset:13120
	ds_read_b64_tr_b16 v[0:1], v153 offset:65280
	ds_read_b128 v[164:167], v151 offset:13184
	v_cvt_pk_bf16_f32 v68, v56, v57
	v_cvt_pk_bf16_f32 v69, v58, v59
	v_cvt_pk_bf16_f32 v70, v60, v61
	v_cvt_pk_bf16_f32 v71, v62, v63
	v_add_u32_e32 v2, 0x6200, v154
	s_mov_b64 s[34:35], 0
	s_waitcnt lgkmcnt(3)
; #define LAS __attribute__((address_space(3)))
; #define MFMA16(a, b, c) __builtin_amdgcn_mfma_f32_16x16x32_bf16((a), (b), (c), 0, 0, 0)
; template <int TYPE, int NMC>
; __device__ __forceinline__ void sg_chain(LAS unsigned char* L, LAS float* SC, f32x4 (&S)[8], f32x4& nacc, int w, int r16, int q) {
;     ...
;     for (int mc = 0; mc < NMC; ++mc) {
;         {
;             const LAS unsigned char* Qb = L + MX_Q + 16 * mc * MX_PITCH; const LAS unsigned char* Kb = L + MX_K + 16 * mc * MX_PITCH;
;             const u32x2 vt = tr16(L + MX_V + 16 * mc * MX_PITCH + (4 * q + (r16 >> 2)) * MX_PITCH + (16 * w + 4 * (r16 & 3)) * 2);
;             f32x4 o2a = {0.f, 0.f, 0.f, 0.f}, o2b = {0.f, 0.f, 0.f, 0.f};
; #pragma unroll
;             for (int ks = 0; ks < 4; ++ks) {
;                 const bf16x8 qf = ld8(Qb + r16 * MX_PITCH + (32 * ks + 8 * q) * 2);
;                 const bf16x8 SB = mk8(pkbf(S[2 * ks][0], S[2 * ks][1]), pkbf(S[2 * ks][2], S[2 * ks][3]), pkbf(S[2 * ks + 1][0], S[2 * ks + 1][1]), pkbf(S[2 * ks + 1][2], S[2 * ks + 1][3]));
;                 if (ks & 1) o2b = MFMA16(qf, SB, o2b); else o2a = MFMA16(qf, SB, o2a);
;             }
;             const f32x4 in4 = *(const LAS f32x4*)(SC + 128 + mc * 16 + 4 * q);
;             oo[mc] = oo[mc] + in4 * (o2a + o2b);
;             const f32x4 w4 = *(const LAS f32x4*)(SC + 192 + mc * 16 + 4 * q); const float carry = SC[320 + mc];
;             if (TYPE == 0) {
;                 const u32x2 qn = *(const LAS u32x2*)(Qb + r16 * MX_PITCH + MX_POS4(16 * w + 4 * q) * 2);
;                 f32x4 rr = {0.f, 0.f, 0.f, 0.f}; rr = mfma16k16(qn, (u32x2){pkbf(nacc[0], nacc[1]), pkbf(nacc[2], nacc[3])}, rr);
;                 if (r16 == 0) {
; #pragma unroll
;                     for (int r = 0; r < 4; ++r) RP[w * 64 + 16 * mc + 4 * q + r] = rr[r]; }
;             }
; #pragma unroll
;             for (int r = 0; r < 4; ++r) OB[(16 * mc + 4 * q + r) * MX_OP + 16 * w + r16] = oo[mc][r];
;             const u32x2 VH = {pkbf(bflo(vt.x) * w4[0], bfhi(vt.x) * w4[1]), pkbf(bflo(vt.y) * w4[2], bfhi(vt.y) * w4[3])};
; #pragma unroll
;             for (int mt = 0; mt < 8; ++mt) {
;                 const u32x2 kt = tr16(Kb + (4 * q + (r16 >> 2)) * MX_PITCH + MX_POS4(16 * mt + 4 * (r16 & 3)) * 2);
;                 S[mt] = S[mt] * carry; S[mt] = mfma16k16(kt, VH, S[mt]);
	v_mfma_f32_16x16x32_bf16 v[68:71], v[72:75], v[68:71], 0
	v_cvt_pk_bf16_f32 v72, v64, v65
	v_cvt_pk_bf16_f32 v73, v66, v67
	v_cvt_pk_bf16_f32 v74, v88, v89
	v_cvt_pk_bf16_f32 v75, v90, v91
	s_waitcnt lgkmcnt(2)
	s_nop 0
	v_mfma_f32_16x16x32_bf16 v[72:75], v[160:163], v[72:75], 0
	v_cvt_pk_bf16_f32 v160, v84, v85
	v_cvt_pk_bf16_f32 v161, v86, v87
	v_cvt_pk_bf16_f32 v162, v76, v77
	v_cvt_pk_bf16_f32 v163, v78, v79
	s_waitcnt lgkmcnt(0)
	s_nop 0
	v_mfma_f32_16x16x32_bf16 v[68:71], v[164:167], v[160:163], v[68:71]
	ds_read_b128 v[164:167], v151 offset:13248
	v_cvt_pk_bf16_f32 v160, v80, v81
	v_cvt_pk_bf16_f32 v161, v82, v83
	v_cvt_pk_bf16_f32 v162, v92, v93
	v_cvt_pk_bf16_f32 v163, v94, v95
	s_waitcnt lgkmcnt(0)
	s_nop 0
	v_mfma_f32_16x16x32_bf16 v[72:75], v[164:167], v[160:163], v[72:75]
	ds_read_b128 v[160:163], v156 offset:704
	s_nop 6
	v_pk_add_f32 v[70:71], v[70:71], v[74:75]
	v_pk_add_f32 v[68:69], v[68:69], v[72:73]
	s_waitcnt lgkmcnt(0)
	v_pk_fma_f32 v[70:71], v[70:71], v[162:163], v[54:55]
	v_pk_fma_f32 v[68:69], v[68:69], v[160:161], v[52:53]
	ds_read_b128 v[52:55], v156 offset:960
	ds_read_b32 v130, v158 offset:1292
	ds_write2_b32 v2, v68, v69 offset0:64 offset1:196
	v_lshlrev_b32_e32 v68, 16, v0
	v_and_b32_e32 v69, 0xffff0000, v0
	s_waitcnt lgkmcnt(2)
	v_pk_mul_f32 v[52:53], v[52:53], v[68:69]
	v_add_u32_e32 v2, 0x6600, v154
	v_cvt_pk_bf16_f32 v0, v52, v53
	v_lshlrev_b32_e32 v52, 16, v1
	v_and_b32_e32 v53, 0xffff0000, v1
	ds_write2_b32 v2, v70, v71 offset0:72 offset1:204
	v_pk_mul_f32 v[52:53], v[54:55], v[52:53]
	s_waitcnt lgkmcnt(2)
	v_pk_mul_f32 v[54:55], v[58:59], v[130:131] op_sel_hi:[1,0]
	v_mov_b32_e32 v58, v3
	v_mov_b32_e32 v59, v3
	v_cvt_pk_bf16_f32 v1, v52, v53
	v_pk_mul_f32 v[52:53], v[56:57], v[130:131] op_sel_hi:[1,0]
	ds_read_b64_tr_b16 v[56:57], v97 offset:30464
	ds_read_b64_tr_b16 v[68:69], v97 offset:30472
	v_mov_b32_e32 v2, v3
	v_pk_mul_f32 v[66:67], v[66:67], v[130:131] op_sel_hi:[1,0]
	v_pk_mul_f32 v[64:65], v[64:65], v[130:131] op_sel_hi:[1,0]
	s_waitcnt lgkmcnt(1)
	v_mfma_f32_16x16x32_bf16 v[56:59], v[56:59], v[0:3], v[52:55]
	v_mov_b32_e32 v70, v3
	v_mov_b32_e32 v71, v3
	v_pk_mul_f32 v[74:75], v[86:87], v[130:131] op_sel_hi:[1,0]
	v_pk_mul_f32 v[52:53], v[60:61], v[130:131] op_sel_hi:[1,0]
	ds_read_b64_tr_b16 v[60:61], v97 offset:30528
	v_pk_mul_f32 v[54:55], v[62:63], v[130:131] op_sel_hi:[1,0]
	v_mov_b32_e32 v62, v3
	v_mov_b32_e32 v63, v3
	s_waitcnt lgkmcnt(1)
	v_mfma_f32_16x16x32_bf16 v[52:55], v[68:71], v[0:3], v[52:55]
	v_mul_f32_e64 v70, v90, v130
	v_mul_f32_e64 v71, v91, v130
	v_pk_mul_f32 v[68:69], v[88:89], v[130:131] op_sel_hi:[1,0]
	v_pk_mul_f32 v[72:73], v[84:85], v[130:131] op_sel_hi:[1,0]
	s_waitcnt lgkmcnt(0)
	v_mfma_f32_16x16x32_bf16 v[60:63], v[60:63], v[0:3], v[64:67]
	v_mul_f32_e64 v78, v78, v130
	v_mul_f32_e64 v79, v79, v130
	v_pk_mul_f32 v[76:77], v[76:77], v[130:131] op_sel_hi:[1,0]
	ds_read_b64_tr_b16 v[64:65], v97 offset:30536
	v_mov_b32_e32 v66, v3
	v_mov_b32_e32 v67, v3
	v_pk_mul_f32 v[82:83], v[82:83], v[130:131] op_sel_hi:[1,0]
	v_pk_mul_f32 v[80:81], v[80:81], v[130:131] op_sel_hi:[1,0]
	s_waitcnt lgkmcnt(0)
	v_mfma_f32_16x16x32_bf16 v[64:67], v[64:67], v[0:3], v[68:71]
	s_nop 2
	ds_read_b64_tr_b16 v[68:69], v97 offset:30592
	v_mov_b32_e32 v70, v3
	v_mov_b32_e32 v71, v3
	v_pk_mul_f32 v[86:87], v[94:95], v[130:131] op_sel_hi:[1,0]
	v_pk_mul_f32 v[84:85], v[92:93], v[130:131] op_sel_hi:[1,0]
	s_waitcnt lgkmcnt(0)
	v_mfma_f32_16x16x32_bf16 v[68:71], v[68:71], v[0:3], v[72:75]
	s_nop 2
	ds_read_b64_tr_b16 v[72:73], v97 offset:30600
	v_mov_b32_e32 v74, v3
	v_mov_b32_e32 v75, v3
	s_waitcnt lgkmcnt(0)
	s_nop 0
	v_mfma_f32_16x16x32_bf16 v[72:75], v[72:75], v[0:3], v[76:79]
	s_nop 2
	ds_read_b64_tr_b16 v[76:77], v97 offset:30656
	v_mov_b32_e32 v78, v3
	v_mov_b32_e32 v79, v3
	s_waitcnt lgkmcnt(0)
	s_nop 0
	v_mfma_f32_16x16x32_bf16 v[76:79], v[76:79], v[0:3], v[80:83]
	s_nop 2
	ds_read_b64_tr_b16 v[80:81], v97 offset:30664
	v_mov_b32_e32 v82, v3
	v_mov_b32_e32 v83, v3
	s_waitcnt lgkmcnt(0)
	s_nop 0
	v_mfma_f32_16x16x32_bf16 v[80:83], v[80:83], v[0:3], v[84:87]

; #define LAS __attribute__((address_space(3)))
; __device__ __forceinline__ u32x2 tr16(const LAS unsigned char* p) { return __builtin_bit_cast(u32x2, __builtin_amdgcn_ds_read_tr16_b64_v4i16((LAS v4i16_t*)p)); }
; __device__ __forceinline__ unsigned pkbf(float lo, float hi) { const f32x2_t v = {lo, hi}; const bf16x2_t b = __builtin_convertvector(v, bf16x2_t); return __builtin_bit_cast(unsigned, b); }
; #define MFMA16(a, b, c) __builtin_amdgcn_mfma_f32_16x16x32_bf16((a), (b), (c), 0, 0, 0)
; __device__ __forceinline__ f32x4 mfma16k16(u32x2 a, u32x2 b, f32x4 c) { const u32x4 a4 = {a.x, a.y, 0u, 0u}, b4 = {b.x, b.y, 0u, 0u}; return __builtin_amdgcn_mfma_f32_16x16x32_bf16(__builtin_bit_cast(bf16x8, a4), __builtin_bit_cast(bf16x8, b4), c, 0, 0, 0); }
; template <int TYPE, int NMC>
; __device__ __forceinline__ void sg_chain(LAS unsigned char* L, LAS float* SC, f32x4 (&S)[8], f32x4& nacc, int w, int r16, int q) {
;     ...
;     for (int mc = 0; mc < NMC; ++mc) {
;         oo[mc] = (f32x4){0.f, 0.f, 0.f, 0.f};
;         {
;             const LAS unsigned char* Qb = L + MX_Q + 16 * mc * MX_PITCH; const LAS unsigned char* Kb = L + MX_K + 16 * mc * MX_PITCH; const LAS unsigned char* Vb = L + MX_V + 16 * mc * MX_PITCH;
;             f32x4 g0 = {0.f, 0.f, 0.f, 0.f}, g1 = {0.f, 0.f, 0.f, 0.f};
; #pragma unroll
;             for (int ks = 0; ks < 4; ++ks) {
;                 const bf16x8 kf = ld8(Kb + r16 * MX_PITCH + (32 * ks + 8 * q) * 2), qf = ld8(Qb + r16 * MX_PITCH + (32 * ks + 8 * q) * 2);
;                 if (ks & 1) g1 = MFMA16(kf, qf, g1); else g0 = MFMA16(kf, qf, g0);
;             }
;             const f32x4 g = g0 + g1;
;             const float xi = SC[mc * 16 + r16]; const f32x4 y4 = *(const LAS f32x4*)(SC + 64 + mc * 16 + 4 * q);
;             f32x4 P;
; #pragma unroll
;             for (int r = 0; r < 4; ++r) P[r] = (4 * q + r <= r16) ? g[r] * __expf(xi + y4[r]) : 0.f;
;             if (TYPE == 0) { float ps = (P[0] + P[1]) + (P[2] + P[3]); ps += __shfl_xor(ps, 16); ps += __shfl_xor(ps, 32); if (w == 0 && q == 0) DI[16 * mc + r16] = ps; }
;             const u32x2 vt = tr16(Vb + (4 * q + (r16 >> 2)) * MX_PITCH + (16 * w + 4 * (r16 & 3)) * 2);
;             oo[mc] = mfma16k16((u32x2){pkbf(P[0], P[1]), pkbf(P[2], P[3])}, vt, oo[mc]);
;         }
;         if (mc == 1 || TYPE == 1) __builtin_amdgcn_sched_barrier(0);
.LBB0_811:
	s_and_b64 s[0:1], s[22:23], exec
	s_cselect_b32 s24, 0x4400, s51
	s_cmpk_lt_i32 s24, 0x4000
	s_mov_b32 s0, 0x9700000
	s_cselect_b32 s0, 0x5900000, s0
	s_add_u32 s36, s94, s0
	s_addc_u32 s37, s95, 0
	s_ashr_i32 s25, s24, 31
	s_lshl_b64 s[0:1], s[24:25], 13
	s_add_u32 s68, s36, s0
	s_addc_u32 s0, s37, s1
	s_lshl_b32 s70, s54, 13
	s_and_b32 s69, s0, 0xffff
	buffer_load_dwordx4 v[32:35], v162, s[68:71], 0 offen
	buffer_load_dwordx4 v[28:31], v163, s[68:71], 0 offen
	s_mov_b64 s[0:1], -1
	s_andn2_b64 vcc, exec, s[44:45]
	v_lshl_add_u32 v187, v168, 2, s55
	v_lshl_add_u32 v188, v160, 2, s55
	s_cbranch_vccnz .LBB0_829
	v_add_u32_e32 v230, v170, v171
	ds_read_b128 v[56:59], v186
	ds_read_b128 v[60:63], v186 offset:17408
	ds_read_b128 v[64:67], v186 offset:64
	ds_read_b128 v[68:71], v186 offset:17472
	ds_read_b128 v[72:75], v186 offset:128
	ds_read_b128 v[76:79], v186 offset:17536
	ds_read_b128 v[80:83], v186 offset:192
	ds_read_b128 v[88:91], v186 offset:17600
	ds_read_b32 v100, v188
	ds_read_b128 v[102:105], v187 offset:256
	ds_read_b64_tr_b16 v[240:241], v230 offset:52224
	v_mov_b32_e32 v242, 0
	v_mov_b32_e32 v243, 0
	v_mov_b32_e32 v202, 0
	v_mov_b32_e32 v203, 0
	v_mov_b32_e32 v234, 0
	v_mov_b32_e32 v235, 0
	v_xor_b32_e32 v236, 16, v215
	v_xor_b32_e32 v237, 32, v215
	v_lshlrev_b32_e32 v236, 2, v236
	v_lshlrev_b32_e32 v237, 2, v237
	s_waitcnt lgkmcnt(9)
	v_mfma_f32_16x16x32_bf16 v[92:95], v[60:63], v[56:59], 0
	s_waitcnt lgkmcnt(7)
	v_mfma_f32_16x16x32_bf16 v[96:99], v[68:71], v[64:67], 0
	s_waitcnt lgkmcnt(5)
	v_mfma_f32_16x16x32_bf16 v[92:95], v[76:79], v[72:75], v[92:95]
	s_waitcnt lgkmcnt(3)
	v_mfma_f32_16x16x32_bf16 v[96:99], v[88:91], v[80:83], v[96:99]
	ds_read_b128 v[56:59], v186 offset:4352
	ds_read_b128 v[60:63], v186 offset:21760
	ds_read_b128 v[64:67], v186 offset:4416
	ds_read_b128 v[68:71], v186 offset:21824
	ds_read_b128 v[72:75], v186 offset:4480
	ds_read_b128 v[76:79], v186 offset:21888
	ds_read_b128 v[80:83], v186 offset:4544
	ds_read_b128 v[88:91], v186 offset:21952
	ds_read_b32 v101, v188 offset:64
	ds_read_b128 v[196:199], v187 offset:320
	ds_read_b64_tr_b16 v[200:201], v230 offset:56576
	s_waitcnt lgkmcnt(11)
	v_pk_add_f32 v[244:245], v[92:93], v[96:97]
	v_pk_add_f32 v[246:247], v[94:95], v[98:99]
	v_add_f32_e32 v0, v100, v102
	v_add_f32_e32 v1, v100, v103
	v_add_f32_e32 v2, v100, v104
	v_add_f32_e32 v189, v100, v105
	v_mul_f32_e32 v0, 0x3fb8aa3b, v0
	v_mul_f32_e32 v1, 0x3fb8aa3b, v1
	v_mul_f32_e32 v2, 0x3fb8aa3b, v2
	v_mul_f32_e32 v189, 0x3fb8aa3b, v189
	v_exp_f32_e32 v0, v0
	v_exp_f32_e32 v1, v1
	v_exp_f32_e32 v2, v2
	v_exp_f32_e32 v189, v189
	v_mul_f32_e32 v0, v244, v0
	v_mul_f32_e32 v1, v245, v1
	v_mul_f32_e32 v2, v246, v2
	v_mul_f32_e32 v189, v247, v189
	v_cndmask_b32_e64 v0, v0, 0, s[14:15]
	v_cndmask_b32_e64 v1, 0, v1, s[16:17]
	v_cndmask_b32_e64 v2, v2, 0, s[18:19]
	v_cndmask_b32_e64 v189, v189, 0, s[20:21]
	v_add_f32_e32 v204, v0, v1
	v_add_f32_e32 v205, v2, v189
	v_cvt_pk_bf16_f32 v232, v0, v1
	v_cvt_pk_bf16_f32 v233, v2, v189
	v_add_f32_e32 v248, v204, v205
	s_nop 0
	v_mfma_f32_16x16x32_bf16 v[52:55], v[232:235], v[240:243], 0
	s_waitcnt lgkmcnt(9)
	v_mfma_f32_16x16x32_bf16 v[92:95], v[60:63], v[56:59], 0
	s_waitcnt lgkmcnt(7)
	v_mfma_f32_16x16x32_bf16 v[96:99], v[68:71], v[64:67], 0
	s_waitcnt lgkmcnt(5)
	v_mfma_f32_16x16x32_bf16 v[92:95], v[76:79], v[72:75], v[92:95]
	s_waitcnt lgkmcnt(3)
	v_mfma_f32_16x16x32_bf16 v[96:99], v[88:91], v[80:83], v[96:99]
	ds_read_b128 v[56:59], v186 offset:8704
	ds_read_b128 v[60:63], v186 offset:26112
	ds_read_b128 v[64:67], v186 offset:8768
	ds_read_b128 v[68:71], v186 offset:26176
	ds_read_b128 v[72:75], v186 offset:8832
	ds_read_b128 v[76:79], v186 offset:26240
	ds_read_b128 v[80:83], v186 offset:8896
	ds_read_b128 v[88:91], v186 offset:26304
	ds_read_b32 v100, v188 offset:128
	ds_read_b128 v[102:105], v187 offset:384
	ds_read_b64_tr_b16 v[240:241], v230 offset:60928
	s_waitcnt lgkmcnt(11)
	v_pk_add_f32 v[244:245], v[92:93], v[96:97]
	v_pk_add_f32 v[246:247], v[94:95], v[98:99]
	v_add_f32_e32 v0, v101, v196
	v_add_f32_e32 v1, v101, v197
	v_add_f32_e32 v2, v101, v198
	v_add_f32_e32 v189, v101, v199
	v_mul_f32_e32 v0, 0x3fb8aa3b, v0
	v_mul_f32_e32 v1, 0x3fb8aa3b, v1
	v_mul_f32_e32 v2, 0x3fb8aa3b, v2
	v_mul_f32_e32 v189, 0x3fb8aa3b, v189
	v_exp_f32_e32 v0, v0
	v_exp_f32_e32 v1, v1
	v_exp_f32_e32 v2, v2
	v_exp_f32_e32 v189, v189
	v_mul_f32_e32 v0, v244, v0
	v_mul_f32_e32 v1, v245, v1
	v_mul_f32_e32 v2, v246, v2
	v_mul_f32_e32 v189, v247, v189
	v_cndmask_b32_e64 v0, v0, 0, s[14:15]
	v_cndmask_b32_e64 v1, 0, v1, s[16:17]
	v_cndmask_b32_e64 v2, v2, 0, s[18:19]
	v_cndmask_b32_e64 v189, v189, 0, s[20:21]
	v_add_f32_e32 v204, v0, v1
	v_add_f32_e32 v205, v2, v189
	v_cvt_pk_bf16_f32 v232, v0, v1
	v_cvt_pk_bf16_f32 v233, v2, v189
	v_add_f32_e32 v249, v204, v205
	s_nop 0
	v_mfma_f32_16x16x32_bf16 v[48:51], v[232:235], v[200:203], 0
	s_waitcnt lgkmcnt(9)
	v_mfma_f32_16x16x32_bf16 v[92:95], v[60:63], v[56:59], 0
	s_waitcnt lgkmcnt(7)
	v_mfma_f32_16x16x32_bf16 v[96:99], v[68:71], v[64:67], 0
	s_waitcnt lgkmcnt(5)
	v_mfma_f32_16x16x32_bf16 v[92:95], v[76:79], v[72:75], v[92:95]
	s_waitcnt lgkmcnt(3)
	v_mfma_f32_16x16x32_bf16 v[96:99], v[88:91], v[80:83], v[96:99]
	ds_read_b128 v[56:59], v186 offset:13056
	ds_read_b128 v[60:63], v186 offset:30464
	ds_read_b128 v[64:67], v186 offset:13120
	ds_read_b128 v[68:71], v186 offset:30528
	ds_read_b128 v[72:75], v186 offset:13184
	ds_read_b128 v[76:79], v186 offset:30592
	ds_read_b128 v[80:83], v186 offset:13248
	ds_read_b128 v[88:91], v186 offset:30656
	ds_read_b32 v101, v188 offset:192
	ds_read_b128 v[196:199], v187 offset:448
	ds_read_b64_tr_b16 v[200:201], v230 offset:65280
	s_waitcnt lgkmcnt(11)
; template <int TYPE, int NMC>
; __device__ __forceinline__ void sg_chain(LAS unsigned char* L, LAS float* SC, f32x4 (&S)[8], f32x4& nacc, int w, int r16, int q) {
;     ...
;     for (int mc = 0; mc < NMC; ++mc) {
;         oo[mc] = (f32x4){0.f, 0.f, 0.f, 0.f};
;         {
;             const LAS unsigned char* Qb = L + MX_Q + 16 * mc * MX_PITCH; const LAS unsigned char* Kb = L + MX_K + 16 * mc * MX_PITCH; const LAS unsigned char* Vb = L + MX_V + 16 * mc * MX_PITCH;
;             f32x4 g0 = {0.f, 0.f, 0.f, 0.f}, g1 = {0.f, 0.f, 0.f, 0.f};
; #pragma unroll
;             for (int ks = 0; ks < 4; ++ks) {
;                 const bf16x8 kf = ld8(Kb + r16 * MX_PITCH + (32 * ks + 8 * q) * 2), qf = ld8(Qb + r16 * MX_PITCH + (32 * ks + 8 * q) * 2);
;                 if (ks & 1) g1 = MFMA16(kf, qf, g1); else g0 = MFMA16(kf, qf, g0);
;             }
;             const f32x4 g = g0 + g1;
;             const float xi = SC[mc * 16 + r16]; const f32x4 y4 = *(const LAS f32x4*)(SC + 64 + mc * 16 + 4 * q);
;             f32x4 P;
; #pragma unroll
;             for (int r = 0; r < 4; ++r) P[r] = (4 * q + r <= r16) ? g[r] * __expf(xi + y4[r]) : 0.f;
;             if (TYPE == 0) { float ps = (P[0] + P[1]) + (P[2] + P[3]); ps += __shfl_xor(ps, 16); ps += __shfl_xor(ps, 32); if (w == 0 && q == 0) DI[16 * mc + r16] = ps; }
;             const u32x2 vt = tr16(Vb + (4 * q + (r16 >> 2)) * MX_PITCH + (16 * w + 4 * (r16 & 3)) * 2);
;             oo[mc] = mfma16k16((u32x2){pkbf(P[0], P[1]), pkbf(P[2], P[3])}, vt, oo[mc]);
;         }
;         if (mc == 1 || TYPE == 1) __builtin_amdgcn_sched_barrier(0);
;     }
; #pragma unroll
;     for (int mc = 0; mc < NMC; ++mc) {
;         {
;             const LAS unsigned char* Qb = L + MX_Q + 16 * mc * MX_PITCH; const LAS unsigned char* Kb = L + MX_K + 16 * mc * MX_PITCH;
;             const u32x2 vt = tr16(L + MX_V + 16 * mc * MX_PITCH + (4 * q + (r16 >> 2)) * MX_PITCH + (16 * w + 4 * (r16 & 3)) * 2);
;             f32x4 o2a = {0.f, 0.f, 0.f, 0.f}, o2b = {0.f, 0.f, 0.f, 0.f};
; #pragma unroll
;             for (int ks = 0; ks < 4; ++ks) {
;                 const bf16x8 qf = ld8(Qb + r16 * MX_PITCH + (32 * ks + 8 * q) * 2);
;                 const bf16x8 SB = mk8(pkbf(S[2 * ks][0], S[2 * ks][1]), pkbf(S[2 * ks][2], S[2 * ks][3]), pkbf(S[2 * ks + 1][0], S[2 * ks + 1][1]), pkbf(S[2 * ks + 1][2], S[2 * ks + 1][3]));
	v_pk_add_f32 v[244:245], v[92:93], v[96:97]
	v_pk_add_f32 v[246:247], v[94:95], v[98:99]
	v_add_f32_e32 v0, v100, v102
	v_add_f32_e32 v1, v100, v103
	v_add_f32_e32 v2, v100, v104
	v_add_f32_e32 v189, v100, v105
	v_mul_f32_e32 v0, 0x3fb8aa3b, v0
	v_mul_f32_e32 v1, 0x3fb8aa3b, v1
	v_mul_f32_e32 v2, 0x3fb8aa3b, v2
	v_mul_f32_e32 v189, 0x3fb8aa3b, v189
	v_exp_f32_e32 v0, v0
	v_exp_f32_e32 v1, v1
	v_exp_f32_e32 v2, v2
	v_exp_f32_e32 v189, v189
	v_mul_f32_e32 v0, v244, v0
	v_mul_f32_e32 v1, v245, v1
	v_mul_f32_e32 v2, v246, v2
	v_mul_f32_e32 v189, v247, v189
	v_cndmask_b32_e64 v0, v0, 0, s[14:15]
	v_cndmask_b32_e64 v1, 0, v1, s[16:17]
	v_cndmask_b32_e64 v2, v2, 0, s[18:19]
	v_cndmask_b32_e64 v189, v189, 0, s[20:21]
	v_add_f32_e32 v204, v0, v1
	v_add_f32_e32 v205, v2, v189
	v_cvt_pk_bf16_f32 v232, v0, v1
	v_cvt_pk_bf16_f32 v233, v2, v189
	v_add_f32_e32 v222, v204, v205
	s_nop 0
	v_mfma_f32_16x16x32_bf16 v[44:47], v[232:235], v[240:243], 0
	s_waitcnt lgkmcnt(9)
	v_mfma_f32_16x16x32_bf16 v[92:95], v[60:63], v[56:59], 0
	s_waitcnt lgkmcnt(7)
	v_mfma_f32_16x16x32_bf16 v[96:99], v[68:71], v[64:67], 0
	s_waitcnt lgkmcnt(5)
	v_mfma_f32_16x16x32_bf16 v[92:95], v[76:79], v[72:75], v[92:95]
	s_waitcnt lgkmcnt(3)
	v_mfma_f32_16x16x32_bf16 v[96:99], v[88:91], v[80:83], v[96:99]
	s_waitcnt lgkmcnt(0)
	s_nop 7
	v_pk_add_f32 v[244:245], v[92:93], v[96:97]
	v_pk_add_f32 v[246:247], v[94:95], v[98:99]
	v_add_f32_e32 v0, v101, v196
	v_add_f32_e32 v1, v101, v197
	v_add_f32_e32 v2, v101, v198
	v_add_f32_e32 v189, v101, v199
	v_mul_f32_e32 v0, 0x3fb8aa3b, v0
	v_mul_f32_e32 v1, 0x3fb8aa3b, v1
	v_mul_f32_e32 v2, 0x3fb8aa3b, v2
	v_mul_f32_e32 v189, 0x3fb8aa3b, v189
	v_exp_f32_e32 v0, v0
	v_exp_f32_e32 v1, v1
	v_exp_f32_e32 v2, v2
	v_exp_f32_e32 v189, v189
	v_mul_f32_e32 v0, v244, v0
	v_mul_f32_e32 v1, v245, v1
	v_mul_f32_e32 v2, v246, v2
	v_mul_f32_e32 v189, v247, v189
	v_cndmask_b32_e64 v0, v0, 0, s[14:15]
	v_cndmask_b32_e64 v1, 0, v1, s[16:17]
	v_cndmask_b32_e64 v2, v2, 0, s[18:19]
	v_cndmask_b32_e64 v189, v189, 0, s[20:21]
	v_add_f32_e32 v204, v0, v1
	v_add_f32_e32 v205, v2, v189
	v_cvt_pk_bf16_f32 v232, v0, v1
	v_cvt_pk_bf16_f32 v233, v2, v189
	v_add_f32_e32 v223, v204, v205
	s_nop 0
	v_mfma_f32_16x16x32_bf16 v[40:43], v[232:235], v[200:203], 0
	s_cmp_lg_u32 s46, 0
	s_cbranch_scc1 .Lc1m_nodi
	ds_bpermute_b32 v0, v236, v248
	ds_bpermute_b32 v1, v236, v249
	ds_bpermute_b32 v189, v236, v222
	ds_bpermute_b32 v204, v236, v223
	s_waitcnt lgkmcnt(0)
	v_add_f32_e32 v248, v248, v0
	v_add_f32_e32 v249, v249, v1
	v_add_f32_e32 v222, v222, v189
	v_add_f32_e32 v223, v223, v204
	ds_bpermute_b32 v0, v237, v248
	ds_bpermute_b32 v1, v237, v249
	ds_bpermute_b32 v189, v237, v222
	ds_bpermute_b32 v204, v237, v223
	s_waitcnt lgkmcnt(0)
	v_add_f32_e32 v248, v248, v0
	v_add_f32_e32 v249, v249, v1
	v_add_f32_e32 v222, v222, v189
	v_add_f32_e32 v223, v223, v204
	s_and_saveexec_b64 s[0:1], s[12:13]
	ds_write_b32 v172, v248
	ds_write_b32 v180, v249
	ds_write_b32 v181, v222
	ds_write_b32 v182, v223
	s_or_b64 exec, exec, s[0:1]
.Lc1m_nodi:
	v_mov_b32_e32 v2, v3
	ds_read_b128 v[56:59], v186
	v_add_u32_e32 v191, v169, v173
	v_mov_b32_e32 v60, s55
	ds_read_b64_tr_b16 v[72:73], v191 offset:52224
	ds_read_b32 v84, v60 offset:1280
	ds_read_b128 v[64:67], v186 offset:64
	ds_read_b128 v[68:71], v186 offset:128
	v_add_u32_e32 v192, v167, v174
	ds_read_b128 v[74:77], v186 offset:192
	ds_read_b64 v[0:1], v192
	ds_read_b128 v[80:83], v187 offset:768
	v_cvt_pk_bf16_f32 v60, v140, v141
	v_cvt_pk_bf16_f32 v61, v142, v143
	v_cvt_pk_bf16_f32 v62, v132, v133
	v_cvt_pk_bf16_f32 v63, v136, v137
	s_waitcnt lgkmcnt(7)
	s_nop 0
	v_mfma_f32_16x16x32_bf16 v[56:59], v[56:59], v[60:63], 0
	v_cvt_pk_bf16_f32 v60, v134, v135
	v_cvt_pk_bf16_f32 v61, v138, v139
	v_cvt_pk_bf16_f32 v62, v126, v127
	v_cvt_pk_bf16_f32 v63, v128, v129
	s_waitcnt lgkmcnt(4)
	s_nop 0
	v_mfma_f32_16x16x32_bf16 v[64:67], v[64:67], v[60:63], 0
	v_cvt_pk_bf16_f32 v60, v124, v125
	v_cvt_pk_bf16_f32 v61, v130, v131
	v_cvt_pk_bf16_f32 v62, v118, v119
	v_cvt_pk_bf16_f32 v63, v122, v123
	s_waitcnt lgkmcnt(3)
	s_nop 0
	v_mfma_f32_16x16x32_bf16 v[60:63], v[68:71], v[60:63], v[56:59]
	v_cvt_pk_bf16_f32 v68, v116, v117
	v_cvt_pk_bf16_f32 v69, v120, v121
	v_cvt_pk_bf16_f32 v70, v112, v113
	v_cvt_pk_bf16_f32 v71, v114, v115
	ds_read_b128 v[56:59], v187 offset:512
	s_waitcnt lgkmcnt(3)
	v_mfma_f32_16x16x32_bf16 v[64:67], v[74:77], v[68:71], v[64:67]
	v_cvt_pk_bf16_f32 v68, v36, v37
	v_cvt_pk_bf16_f32 v69, v38, v39
	v_mov_b32_e32 v70, v3
	v_mov_b32_e32 v71, v3
	s_waitcnt lgkmcnt(2)
	s_nop 0
	v_mfma_f32_16x16x32_bf16 v[68:71], v[0:3], v[68:71], 0
	s_and_saveexec_b64 s[0:1], s[10:11]
	s_nop 6
	ds_write_b128 v175, v[68:71]
	s_or_b64 exec, exec, s[0:1]
	v_pk_add_f32 v[0:1], v[62:63], v[66:67]
	v_pk_add_f32 v[60:61], v[60:61], v[64:65]
	v_add_u32_e32 v193, v177, v178
	s_waitcnt lgkmcnt(0)
	v_pk_fma_f32 v[0:1], v[0:1], v[58:59], v[54:55]
	v_pk_fma_f32 v[52:53], v[60:61], v[56:57], v[52:53]
	v_add_u32_e32 v2, 0x400, v193
	ds_write2_b32 v193, v52, v53 offset1:132
	ds_write2_b32 v2, v0, v1 offset0:8 offset1:140
	v_lshlrev_b32_e32 v0, 16, v72
	v_and_b32_e32 v1, 0xffff0000, v72
	v_lshlrev_b32_e32 v52, 16, v73
	v_and_b32_e32 v53, 0xffff0000, v73
	v_pk_mul_f32 v[0:1], v[80:81], v[0:1]
	v_pk_mul_f32 v[52:53], v[82:83], v[52:53]
	v_add_u32_e32 v189, v169, v176
	v_cvt_pk_bf16_f32 v0, v0, v1
	v_cvt_pk_bf16_f32 v1, v52, v53
	ds_read_b64_tr_b16 v[52:53], v189 offset:17408
	v_mov_b32_e32 v54, v3
	v_mov_b32_e32 v55, v3
	v_mov_b32_e32 v62, v3
	v_mov_b32_e32 v63, v3
	ds_read_b64_tr_b16 v[60:61], v189 offset:17416
	ds_read_b64_tr_b16 v[64:65], v189 offset:17472
	ds_read_b64_tr_b16 v[68:69], v189 offset:17480
	v_mov_b32_e32 v2, v3
	v_pk_mul_f32 v[58:59], v[142:143], v[84:85] op_sel_hi:[1,0]
	v_pk_mul_f32 v[56:57], v[140:141], v[84:85] op_sel_hi:[1,0]
	v_mov_b32_e32 v66, v3
	v_mov_b32_e32 v67, v3
	s_waitcnt lgkmcnt(3)
; template <int TYPE, int NMC>
; __device__ __forceinline__ void sg_chain(LAS unsigned char* L, LAS float* SC, f32x4 (&S)[8], f32x4& nacc, int w, int r16, int q) {
;     ...
;     for (int mc = 0; mc < NMC; ++mc) {
;         {
;             const LAS unsigned char* Qb = L + MX_Q + 16 * mc * MX_PITCH; const LAS unsigned char* Kb = L + MX_K + 16 * mc * MX_PITCH;
;             const u32x2 vt = tr16(L + MX_V + 16 * mc * MX_PITCH + (4 * q + (r16 >> 2)) * MX_PITCH + (16 * w + 4 * (r16 & 3)) * 2);
;             f32x4 o2a = {0.f, 0.f, 0.f, 0.f}, o2b = {0.f, 0.f, 0.f, 0.f};
; #pragma unroll
;             for (int ks = 0; ks < 4; ++ks) {
;                 const bf16x8 qf = ld8(Qb + r16 * MX_PITCH + (32 * ks + 8 * q) * 2);
;                 const bf16x8 SB = mk8(pkbf(S[2 * ks][0], S[2 * ks][1]), pkbf(S[2 * ks][2], S[2 * ks][3]), pkbf(S[2 * ks + 1][0], S[2 * ks + 1][1]), pkbf(S[2 * ks + 1][2], S[2 * ks + 1][3]));
;                 if (ks & 1) o2b = MFMA16(qf, SB, o2b); else o2a = MFMA16(qf, SB, o2a);
;             }
;             const f32x4 in4 = *(const LAS f32x4*)(SC + 128 + mc * 16 + 4 * q);
;             oo[mc] = oo[mc] + in4 * (o2a + o2b);
;             const f32x4 w4 = *(const LAS f32x4*)(SC + 192 + mc * 16 + 4 * q); const float carry = SC[320 + mc];
;             if (TYPE == 0) {
;                 const u32x2 qn = *(const LAS u32x2*)(Qb + r16 * MX_PITCH + MX_POS4(16 * w + 4 * q) * 2);
;                 f32x4 rr = {0.f, 0.f, 0.f, 0.f}; rr = mfma16k16(qn, (u32x2){pkbf(nacc[0], nacc[1]), pkbf(nacc[2], nacc[3])}, rr);
;                 if (r16 == 0) {
; #pragma unroll
;                     for (int r = 0; r < 4; ++r) RP[w * 64 + 16 * mc + 4 * q + r] = rr[r]; }
;             }
; #pragma unroll
;             for (int r = 0; r < 4; ++r) OB[(16 * mc + 4 * q + r) * MX_OP + 16 * w + r16] = oo[mc][r];
;             const u32x2 VH = {pkbf(bflo(vt.x) * w4[0], bfhi(vt.x) * w4[1]), pkbf(bflo(vt.y) * w4[2], bfhi(vt.y) * w4[3])};
; #pragma unroll
;             for (int mt = 0; mt < 8; ++mt) {
;                 const u32x2 kt = tr16(Kb + (4 * q + (r16 >> 2)) * MX_PITCH + MX_POS4(16 * mt + 4 * (r16 & 3)) * 2);
;                 S[mt] = S[mt] * carry; S[mt] = mfma16k16(kt, VH, S[mt]);
;             }
;             if (TYPE == 0) {
;                 const u32x2 kt = tr16(Kb + (4 * q + (r16 >> 2)) * MX_PITCH + MX_POS4(16 * w + 4 * (r16 & 3)) * 2);
	v_mfma_f32_16x16x32_bf16 v[76:79], v[52:55], v[0:3], v[56:59]
	v_mul_f32_e64 v54, v136, v84
	v_mul_f32_e64 v55, v137, v84
	v_pk_mul_f32 v[52:53], v[132:133], v[84:85] op_sel_hi:[1,0]
	v_mov_b32_e32 v70, v3
	v_mov_b32_e32 v71, v3
	s_waitcnt lgkmcnt(2)
	v_mfma_f32_16x16x32_bf16 v[52:55], v[60:63], v[0:3], v[52:55]
	ds_read_b64_tr_b16 v[60:61], v189 offset:17536
	v_pk_mul_f32 v[58:59], v[138:139], v[84:85] op_sel_hi:[1,0]
	v_pk_mul_f32 v[56:57], v[134:135], v[84:85] op_sel_hi:[1,0]
	v_mov_b32_e32 v94, v3
	v_mov_b32_e32 v95, v3
	s_waitcnt lgkmcnt(2)
	v_mfma_f32_16x16x32_bf16 v[72:75], v[64:67], v[0:3], v[56:59]
	v_mov_b32_e32 v98, v3
	v_mov_b32_e32 v99, v3
	v_pk_mul_f32 v[66:67], v[130:131], v[84:85] op_sel_hi:[1,0]
	v_pk_mul_f32 v[58:59], v[128:129], v[84:85] op_sel_hi:[1,0]
	v_pk_mul_f32 v[56:57], v[126:127], v[84:85] op_sel_hi:[1,0]
	v_pk_mul_f32 v[64:65], v[124:125], v[84:85] op_sel_hi:[1,0]
	v_add_u32_e32 v194, v169, v179
	s_waitcnt lgkmcnt(1)
	v_mfma_f32_16x16x32_bf16 v[56:59], v[68:71], v[0:3], v[56:59]
	ds_read_b64_tr_b16 v[68:69], v189 offset:17544
	ds_read_b64_tr_b16 v[92:93], v189 offset:17600
	ds_read_b64_tr_b16 v[96:97], v189 offset:17608
	v_pk_mul_f32 v[86:87], v[38:39], v[84:85] op_sel_hi:[1,0]
	v_cvt_pk_bf16_f32 v80, v80, v81
	s_waitcnt lgkmcnt(3)
	v_mfma_f32_16x16x32_bf16 v[88:91], v[60:63], v[0:3], v[64:67]
	v_mul_f32_e64 v62, v122, v84
	v_mul_f32_e64 v63, v123, v84
	v_pk_mul_f32 v[60:61], v[118:119], v[84:85] op_sel_hi:[1,0]
	v_cvt_pk_bf16_f32 v81, v82, v83
	v_pk_mul_f32 v[66:67], v[120:121], v[84:85] op_sel_hi:[1,0]
	s_waitcnt lgkmcnt(2)
	v_mfma_f32_16x16x32_bf16 v[60:63], v[68:71], v[0:3], v[60:63]
	v_mul_f32_e64 v64, v116, v84
	v_mul_f32_e64 v65, v117, v84
	v_pk_mul_f32 v[70:71], v[114:115], v[84:85] op_sel_hi:[1,0]
	v_pk_mul_f32 v[68:69], v[112:113], v[84:85] op_sel_hi:[1,0]
	s_waitcnt lgkmcnt(1)
	v_mfma_f32_16x16x32_bf16 v[64:67], v[92:95], v[0:3], v[64:67]
	v_pk_mul_f32 v[84:85], v[36:37], v[84:85] op_sel_hi:[1,0]
	v_mov_b32_e32 v82, v3
	v_mov_b32_e32 v83, v3
	s_waitcnt lgkmcnt(0)
	v_mfma_f32_16x16x32_bf16 v[68:71], v[96:99], v[0:3], v[68:71]
	ds_read_b64_tr_b16 v[0:1], v194 offset:17408
	s_waitcnt lgkmcnt(0)
	v_mfma_f32_16x16x32_bf16 v[80:83], v[0:3], v[80:83], v[84:87]
	s_nop 2
	ds_read_b128 v[84:87], v186 offset:4352
	ds_read_b128 v[96:99], v186 offset:4416
	v_cvt_pk_bf16_f32 v92, v76, v77
	v_cvt_pk_bf16_f32 v93, v78, v79
	v_cvt_pk_bf16_f32 v94, v52, v53
	v_cvt_pk_bf16_f32 v95, v54, v55
	v_cvt_pk_bf16_f32 v100, v72, v73
	v_cvt_pk_bf16_f32 v101, v74, v75
	v_cvt_pk_bf16_f32 v102, v56, v57
	s_waitcnt lgkmcnt(1)
	v_mfma_f32_16x16x32_bf16 v[84:87], v[84:87], v[92:95], 0
	ds_read_b128 v[92:95], v186 offset:4480
	ds_read_b128 v[104:107], v186 offset:4544
	v_cvt_pk_bf16_f32 v103, v58, v59
	v_mov_b32_e32 v0, s55
	ds_read_b64_tr_b16 v[146:147], v191 offset:56576
	ds_read_b32 v144, v0 offset:1284
	ds_read_b64 v[0:1], v192 offset:4352
	s_waitcnt lgkmcnt(5)
	v_mfma_f32_16x16x32_bf16 v[96:99], v[96:99], v[100:103], 0
	v_cvt_pk_bf16_f32 v100, v88, v89
	v_cvt_pk_bf16_f32 v101, v90, v91
	v_cvt_pk_bf16_f32 v102, v60, v61
	v_cvt_pk_bf16_f32 v103, v62, v63
	s_waitcnt lgkmcnt(4)
	s_nop 0
	v_mfma_f32_16x16x32_bf16 v[84:87], v[92:95], v[100:103], v[84:87]
	v_cvt_pk_bf16_f32 v92, v64, v65
	v_cvt_pk_bf16_f32 v93, v66, v67
	v_cvt_pk_bf16_f32 v94, v68, v69
	v_cvt_pk_bf16_f32 v95, v70, v71
	s_waitcnt lgkmcnt(3)
	s_nop 0
	v_mfma_f32_16x16x32_bf16 v[100:103], v[104:107], v[92:95], v[96:99]
	s_nop 2
	ds_read_b128 v[96:99], v187 offset:576
	ds_read_b128 v[92:95], v187 offset:832
	v_cvt_pk_bf16_f32 v104, v80, v81
	v_cvt_pk_bf16_f32 v105, v82, v83
	v_mov_b32_e32 v106, v3
	v_mov_b32_e32 v107, v3
	s_waitcnt lgkmcnt(2)
	s_nop 0
	v_mfma_f32_16x16x32_bf16 v[104:107], v[0:3], v[104:107], 0
	s_and_saveexec_b64 s[0:1], s[10:11]
	s_nop 6
	ds_write_b128 v175, v[104:107] offset:64
	s_or_b64 exec, exec, s[0:1]
	v_pk_add_f32 v[84:85], v[84:85], v[100:101]
	v_pk_add_f32 v[0:1], v[86:87], v[102:103]
	s_waitcnt lgkmcnt(1)
	v_pk_fma_f32 v[48:49], v[84:85], v[96:97], v[48:49]
	v_add_u32_e32 v2, 0x2000, v193
	v_pk_fma_f32 v[0:1], v[0:1], v[98:99], v[50:51]
	ds_write2_b32 v2, v48, v49 offset0:64 offset1:196
	v_add_u32_e32 v2, 0x2400, v193
	ds_write2_b32 v2, v0, v1 offset0:72 offset1:204
	v_lshlrev_b32_e32 v0, 16, v146
	v_and_b32_e32 v1, 0xffff0000, v146
	v_lshlrev_b32_e32 v48, 16, v147
	v_and_b32_e32 v49, 0xffff0000, v147
	s_waitcnt lgkmcnt(2)
	v_pk_mul_f32 v[0:1], v[92:93], v[0:1]
	v_pk_mul_f32 v[48:49], v[94:95], v[48:49]
	v_cvt_pk_bf16_f32 v0, v0, v1
	v_cvt_pk_bf16_f32 v1, v48, v49
	ds_read_b64_tr_b16 v[48:49], v189 offset:21760
	v_mov_b32_e32 v50, v3
	v_mov_b32_e32 v51, v3
	v_mov_b32_e32 v102, v3
	v_mov_b32_e32 v103, v3
	ds_read_b64_tr_b16 v[96:97], v189 offset:21768
	ds_read_b64_tr_b16 v[100:101], v189 offset:21824
	ds_read_b64_tr_b16 v[104:105], v189 offset:21832
	v_mov_b32_e32 v2, v3
	v_pk_mul_f32 v[78:79], v[78:79], v[144:145] op_sel_hi:[1,0]
	v_pk_mul_f32 v[76:77], v[76:77], v[144:145] op_sel_hi:[1,0]
	v_mov_b32_e32 v98, v3
	v_mov_b32_e32 v99, v3
	s_waitcnt lgkmcnt(3)
	v_mfma_f32_16x16x32_bf16 v[84:87], v[48:51], v[0:3], v[76:79]
	v_mul_f32_e64 v50, v54, v144
	v_mul_f32_e64 v51, v55, v144
	v_pk_mul_f32 v[48:49], v[52:53], v[144:145] op_sel_hi:[1,0]
	v_pk_mul_f32 v[54:55], v[74:75], v[144:145] op_sel_hi:[1,0]
	v_pk_mul_f32 v[52:53], v[72:73], v[144:145] op_sel_hi:[1,0]
	v_mov_b32_e32 v106, v3
	v_mov_b32_e32 v107, v3
	s_waitcnt lgkmcnt(1)
	v_mfma_f32_16x16x32_bf16 v[76:79], v[100:103], v[0:3], v[52:55]
	s_nop 2
	v_mul_f32_e64 v52, v56, v144
	v_mul_f32_e64 v53, v57, v144
	ds_read_b64_tr_b16 v[56:57], v189 offset:21888
	v_pk_mul_f32 v[54:55], v[58:59], v[144:145] op_sel_hi:[1,0]
	v_mov_b32_e32 v58, v3
	v_mov_b32_e32 v59, v3
	v_mfma_f32_16x16x32_bf16 v[48:51], v[96:99], v[0:3], v[48:51]
	s_waitcnt lgkmcnt(1)
; template <int TYPE, int NMC>
; __device__ __forceinline__ void sg_chain(LAS unsigned char* L, LAS float* SC, f32x4 (&S)[8], f32x4& nacc, int w, int r16, int q) {
;     ...
;     for (int mc = 0; mc < NMC; ++mc) {
;         {
;             const LAS unsigned char* Qb = L + MX_Q + 16 * mc * MX_PITCH; const LAS unsigned char* Kb = L + MX_K + 16 * mc * MX_PITCH;
;             const u32x2 vt = tr16(L + MX_V + 16 * mc * MX_PITCH + (4 * q + (r16 >> 2)) * MX_PITCH + (16 * w + 4 * (r16 & 3)) * 2);
;             f32x4 o2a = {0.f, 0.f, 0.f, 0.f}, o2b = {0.f, 0.f, 0.f, 0.f};
; #pragma unroll
;             for (int ks = 0; ks < 4; ++ks) {
;                 const bf16x8 qf = ld8(Qb + r16 * MX_PITCH + (32 * ks + 8 * q) * 2);
;                 const bf16x8 SB = mk8(pkbf(S[2 * ks][0], S[2 * ks][1]), pkbf(S[2 * ks][2], S[2 * ks][3]), pkbf(S[2 * ks + 1][0], S[2 * ks + 1][1]), pkbf(S[2 * ks + 1][2], S[2 * ks + 1][3]));
;                 if (ks & 1) o2b = MFMA16(qf, SB, o2b); else o2a = MFMA16(qf, SB, o2a);
;             }
;             const f32x4 in4 = *(const LAS f32x4*)(SC + 128 + mc * 16 + 4 * q);
;             oo[mc] = oo[mc] + in4 * (o2a + o2b);
;             const f32x4 w4 = *(const LAS f32x4*)(SC + 192 + mc * 16 + 4 * q); const float carry = SC[320 + mc];
;             if (TYPE == 0) {
;                 const u32x2 qn = *(const LAS u32x2*)(Qb + r16 * MX_PITCH + MX_POS4(16 * w + 4 * q) * 2);
;                 f32x4 rr = {0.f, 0.f, 0.f, 0.f}; rr = mfma16k16(qn, (u32x2){pkbf(nacc[0], nacc[1]), pkbf(nacc[2], nacc[3])}, rr);
;                 if (r16 == 0) {
; #pragma unroll
;                     for (int r = 0; r < 4; ++r) RP[w * 64 + 16 * mc + 4 * q + r] = rr[r]; }
;             }
; #pragma unroll
;             for (int r = 0; r < 4; ++r) OB[(16 * mc + 4 * q + r) * MX_OP + 16 * w + r16] = oo[mc][r];
;             const u32x2 VH = {pkbf(bflo(vt.x) * w4[0], bfhi(vt.x) * w4[1]), pkbf(bflo(vt.y) * w4[2], bfhi(vt.y) * w4[3])};
; #pragma unroll
;             for (int mt = 0; mt < 8; ++mt) {
;                 const u32x2 kt = tr16(Kb + (4 * q + (r16 >> 2)) * MX_PITCH + MX_POS4(16 * mt + 4 * (r16 & 3)) * 2);
;                 S[mt] = S[mt] * carry; S[mt] = mfma16k16(kt, VH, S[mt]);
;             }
;             if (TYPE == 0) {
;                 const u32x2 kt = tr16(Kb + (4 * q + (r16 >> 2)) * MX_PITCH + MX_POS4(16 * w + 4 * (r16 & 3)) * 2);
	v_mfma_f32_16x16x32_bf16 v[72:75], v[104:107], v[0:3], v[52:55]
	ds_read_b64_tr_b16 v[96:97], v189 offset:21896
	ds_read_b64_tr_b16 v[100:101], v189 offset:21952
	ds_read_b64_tr_b16 v[104:105], v189 offset:21960
	v_pk_mul_f32 v[54:55], v[90:91], v[144:145] op_sel_hi:[1,0]
	v_pk_mul_f32 v[52:53], v[88:89], v[144:145] op_sel_hi:[1,0]
	s_waitcnt lgkmcnt(3)
	s_nop 0
	v_mfma_f32_16x16x32_bf16 v[88:91], v[56:59], v[0:3], v[52:55]
	v_mul_f32_e64 v58, v66, v144
	v_mul_f32_e64 v59, v67, v144
	v_pk_mul_f32 v[56:57], v[64:65], v[144:145] op_sel_hi:[1,0]
	v_pk_mul_f32 v[66:67], v[82:83], v[144:145] op_sel_hi:[1,0]
	v_pk_mul_f32 v[54:55], v[62:63], v[144:145] op_sel_hi:[1,0]
	v_pk_mul_f32 v[52:53], v[60:61], v[144:145] op_sel_hi:[1,0]
	v_pk_mul_f32 v[62:63], v[70:71], v[144:145] op_sel_hi:[1,0]
	v_pk_mul_f32 v[60:61], v[68:69], v[144:145] op_sel_hi:[1,0]
	s_waitcnt lgkmcnt(2)
	v_mfma_f32_16x16x32_bf16 v[52:55], v[96:99], v[0:3], v[52:55]
	v_mul_f32_e64 v64, v80, v144
	v_mul_f32_e64 v65, v81, v144
	v_cvt_pk_bf16_f32 v68, v92, v93
	v_cvt_pk_bf16_f32 v69, v94, v95
	s_waitcnt lgkmcnt(1)
	v_mfma_f32_16x16x32_bf16 v[56:59], v[100:103], v[0:3], v[56:59]
	v_mov_b32_e32 v70, v3
	v_mov_b32_e32 v71, v3
	s_waitcnt lgkmcnt(0)
	v_mfma_f32_16x16x32_bf16 v[60:63], v[104:107], v[0:3], v[60:63]
	ds_read_b64_tr_b16 v[0:1], v194 offset:21760
	s_waitcnt lgkmcnt(0)
	v_mfma_f32_16x16x32_bf16 v[80:83], v[0:3], v[68:71], v[64:67]
	s_nop 2
	ds_read_b128 v[64:67], v186 offset:8704
	ds_read_b128 v[92:95], v186 offset:8768
	v_cvt_pk_bf16_f32 v68, v84, v85
	v_cvt_pk_bf16_f32 v69, v86, v87
	v_cvt_pk_bf16_f32 v70, v48, v49
	v_cvt_pk_bf16_f32 v71, v50, v51
	v_cvt_pk_bf16_f32 v96, v76, v77
	v_cvt_pk_bf16_f32 v97, v78, v79
	v_cvt_pk_bf16_f32 v98, v72, v73
	s_waitcnt lgkmcnt(1)
	v_mfma_f32_16x16x32_bf16 v[64:67], v[64:67], v[68:71], 0
	ds_read_b128 v[68:71], v186 offset:8832
	ds_read_b128 v[100:103], v186 offset:8896
	v_cvt_pk_bf16_f32 v99, v74, v75
	v_mov_b32_e32 v0, s55
	ds_read_b64_tr_b16 v[106:107], v191 offset:60928
	ds_read_b32 v104, v0 offset:1288
	ds_read_b64 v[0:1], v192 offset:8704
	s_waitcnt lgkmcnt(5)
	v_mfma_f32_16x16x32_bf16 v[92:95], v[92:95], v[96:99], 0
	v_cvt_pk_bf16_f32 v96, v88, v89
	v_cvt_pk_bf16_f32 v97, v90, v91
	v_cvt_pk_bf16_f32 v98, v52, v53
	v_cvt_pk_bf16_f32 v99, v54, v55
	s_waitcnt lgkmcnt(4)
	s_nop 0
	v_mfma_f32_16x16x32_bf16 v[64:67], v[68:71], v[96:99], v[64:67]
	v_cvt_pk_bf16_f32 v68, v56, v57
	v_cvt_pk_bf16_f32 v69, v58, v59
	v_cvt_pk_bf16_f32 v70, v60, v61
	v_cvt_pk_bf16_f32 v71, v62, v63
	s_waitcnt lgkmcnt(3)
	s_nop 0
	v_mfma_f32_16x16x32_bf16 v[96:99], v[100:103], v[68:71], v[92:95]
	ds_read_b128 v[68:71], v187 offset:640
	s_nop 1
	ds_read_b128 v[92:95], v187 offset:896
	v_cvt_pk_bf16_f32 v100, v80, v81
	v_cvt_pk_bf16_f32 v101, v82, v83
	v_mov_b32_e32 v102, v3
	v_mov_b32_e32 v103, v3
	s_waitcnt lgkmcnt(2)
	s_nop 0
	v_mfma_f32_16x16x32_bf16 v[100:103], v[0:3], v[100:103], 0
	s_and_saveexec_b64 s[0:1], s[10:11]
	s_nop 6
	ds_write_b128 v175, v[100:103] offset:128
	s_or_b64 exec, exec, s[0:1]
	v_pk_add_f32 v[64:65], v[64:65], v[96:97]
	v_pk_add_f32 v[0:1], v[66:67], v[98:99]
	s_waitcnt lgkmcnt(1)
	v_pk_fma_f32 v[44:45], v[64:65], v[68:69], v[44:45]
	v_add_u32_e32 v2, 0x4200, v193
	v_pk_fma_f32 v[0:1], v[0:1], v[70:71], v[46:47]
	ds_write2_b32 v2, v44, v45 offset1:132
	v_add_u32_e32 v2, 0x4600, v193
	ds_write2_b32 v2, v0, v1 offset0:8 offset1:140
	v_lshlrev_b32_e32 v0, 16, v106
	v_and_b32_e32 v1, 0xffff0000, v106
	v_lshlrev_b32_e32 v44, 16, v107
	v_and_b32_e32 v45, 0xffff0000, v107
	s_waitcnt lgkmcnt(2)
	v_pk_mul_f32 v[0:1], v[92:93], v[0:1]
	v_pk_mul_f32 v[44:45], v[94:95], v[44:45]
	v_cvt_pk_bf16_f32 v0, v0, v1
	v_cvt_pk_bf16_f32 v1, v44, v45
	ds_read_b64_tr_b16 v[44:45], v189 offset:26112
	v_mov_b32_e32 v46, v3
	v_mov_b32_e32 v47, v3
	v_mov_b32_e32 v2, v3
	v_pk_mul_f32 v[66:67], v[86:87], v[104:105] op_sel_hi:[1,0]
	v_pk_mul_f32 v[64:65], v[84:85], v[104:105] op_sel_hi:[1,0]
	ds_read_b64_tr_b16 v[68:69], v189 offset:26120
	ds_read_b64_tr_b16 v[96:97], v189 offset:26176
	ds_read_b64_tr_b16 v[100:101], v189 offset:26184
	s_waitcnt lgkmcnt(3)
	v_mfma_f32_16x16x32_bf16 v[84:87], v[44:47], v[0:3], v[64:67]
	v_mov_b32_e32 v98, v3
	v_mov_b32_e32 v99, v3
	s_nop 0
	ds_read_b64_tr_b16 v[64:65], v189 offset:26240
	v_mov_b32_e32 v70, v3
	v_mov_b32_e32 v71, v3
	v_mov_b32_e32 v102, v3
	v_mov_b32_e32 v103, v3
	v_pk_mul_f32 v[46:47], v[50:51], v[104:105] op_sel_hi:[1,0]
	v_pk_mul_f32 v[44:45], v[48:49], v[104:105] op_sel_hi:[1,0]
	v_pk_mul_f32 v[50:51], v[78:79], v[104:105] op_sel_hi:[1,0]
	v_pk_mul_f32 v[48:49], v[76:77], v[104:105] op_sel_hi:[1,0]
	v_mov_b32_e32 v66, v3
	v_mov_b32_e32 v67, v3
	s_waitcnt lgkmcnt(2)
	v_mfma_f32_16x16x32_bf16 v[76:79], v[96:99], v[0:3], v[48:51]
	s_nop 2
	v_mul_f32_e64 v50, v74, v104
	v_mul_f32_e64 v51, v75, v104
	v_mov_b32_e32 v74, v3
	v_mov_b32_e32 v75, v3
	v_pk_mul_f32 v[48:49], v[72:73], v[104:105] op_sel_hi:[1,0]
	v_mfma_f32_16x16x32_bf16 v[44:47], v[68:71], v[0:3], v[44:47]
	s_waitcnt lgkmcnt(1)
	v_mfma_f32_16x16x32_bf16 v[68:71], v[100:103], v[0:3], v[48:51]
	ds_read_b64_tr_b16 v[72:73], v189 offset:26248
	ds_read_b64_tr_b16 v[96:97], v189 offset:26304
	ds_read_b64_tr_b16 v[100:101], v189 offset:26312
	v_pk_mul_f32 v[50:51], v[90:91], v[104:105] op_sel_hi:[1,0]
	v_pk_mul_f32 v[48:49], v[88:89], v[104:105] op_sel_hi:[1,0]
	s_waitcnt lgkmcnt(3)
	s_nop 0
	v_mfma_f32_16x16x32_bf16 v[88:91], v[64:67], v[0:3], v[48:51]
	s_nop 2
	v_mul_f32_e64 v50, v54, v104
	v_mul_f32_e64 v51, v55, v104
	v_pk_mul_f32 v[48:49], v[52:53], v[104:105] op_sel_hi:[1,0]
	v_cvt_pk_bf16_f32 v52, v92, v93
	v_cvt_pk_bf16_f32 v53, v94, v95
	s_waitcnt lgkmcnt(2)
; template <int TYPE, int NMC>
; __device__ __forceinline__ void sg_chain(LAS unsigned char* L, LAS float* SC, f32x4 (&S)[8], f32x4& nacc, int w, int r16, int q) {
;     ...
;     for (int mc = 0; mc < NMC; ++mc) {
;         {
;             const LAS unsigned char* Qb = L + MX_Q + 16 * mc * MX_PITCH; const LAS unsigned char* Kb = L + MX_K + 16 * mc * MX_PITCH;
;             const u32x2 vt = tr16(L + MX_V + 16 * mc * MX_PITCH + (4 * q + (r16 >> 2)) * MX_PITCH + (16 * w + 4 * (r16 & 3)) * 2);
;             f32x4 o2a = {0.f, 0.f, 0.f, 0.f}, o2b = {0.f, 0.f, 0.f, 0.f};
; #pragma unroll
;             for (int ks = 0; ks < 4; ++ks) {
;                 const bf16x8 qf = ld8(Qb + r16 * MX_PITCH + (32 * ks + 8 * q) * 2);
;                 const bf16x8 SB = mk8(pkbf(S[2 * ks][0], S[2 * ks][1]), pkbf(S[2 * ks][2], S[2 * ks][3]), pkbf(S[2 * ks + 1][0], S[2 * ks + 1][1]), pkbf(S[2 * ks + 1][2], S[2 * ks + 1][3]));
;                 if (ks & 1) o2b = MFMA16(qf, SB, o2b); else o2a = MFMA16(qf, SB, o2a);
;             }
;             const f32x4 in4 = *(const LAS f32x4*)(SC + 128 + mc * 16 + 4 * q);
;             oo[mc] = oo[mc] + in4 * (o2a + o2b);
;             const f32x4 w4 = *(const LAS f32x4*)(SC + 192 + mc * 16 + 4 * q); const float carry = SC[320 + mc];
;             if (TYPE == 0) {
;                 const u32x2 qn = *(const LAS u32x2*)(Qb + r16 * MX_PITCH + MX_POS4(16 * w + 4 * q) * 2);
;                 f32x4 rr = {0.f, 0.f, 0.f, 0.f}; rr = mfma16k16(qn, (u32x2){pkbf(nacc[0], nacc[1]), pkbf(nacc[2], nacc[3])}, rr);
;                 if (r16 == 0) {
; #pragma unroll
;                     for (int r = 0; r < 4; ++r) RP[w * 64 + 16 * mc + 4 * q + r] = rr[r]; }
;             }
; #pragma unroll
;             for (int r = 0; r < 4; ++r) OB[(16 * mc + 4 * q + r) * MX_OP + 16 * w + r16] = oo[mc][r];
;             const u32x2 VH = {pkbf(bflo(vt.x) * w4[0], bfhi(vt.x) * w4[1]), pkbf(bflo(vt.y) * w4[2], bfhi(vt.y) * w4[3])};
; #pragma unroll
;             for (int mt = 0; mt < 8; ++mt) {
;                 const u32x2 kt = tr16(Kb + (4 * q + (r16 >> 2)) * MX_PITCH + MX_POS4(16 * mt + 4 * (r16 & 3)) * 2);
;                 S[mt] = S[mt] * carry; S[mt] = mfma16k16(kt, VH, S[mt]);
;             }
;             if (TYPE == 0) {
;                 const u32x2 kt = tr16(Kb + (4 * q + (r16 >> 2)) * MX_PITCH + MX_POS4(16 * w + 4 * (r16 & 3)) * 2);
	v_mfma_f32_16x16x32_bf16 v[64:67], v[72:75], v[0:3], v[48:51]
	v_mov_b32_e32 v54, v3
	v_mov_b32_e32 v55, v3
	s_nop 0
	v_pk_mul_f32 v[50:51], v[58:59], v[104:105] op_sel_hi:[1,0]
	v_pk_mul_f32 v[48:49], v[56:57], v[104:105] op_sel_hi:[1,0]
	s_waitcnt lgkmcnt(1)
	s_nop 0
	v_mfma_f32_16x16x32_bf16 v[56:59], v[96:99], v[0:3], v[48:51]
	s_nop 2
	v_mul_f32_e64 v50, v62, v104
	v_mul_f32_e64 v51, v63, v104
	v_pk_mul_f32 v[48:49], v[60:61], v[104:105] op_sel_hi:[1,0]
	s_waitcnt lgkmcnt(0)
	s_nop 0
	v_mfma_f32_16x16x32_bf16 v[60:63], v[100:103], v[0:3], v[48:51]
	ds_read_b64_tr_b16 v[0:1], v194 offset:26112
	s_nop 1
	v_pk_mul_f32 v[50:51], v[82:83], v[104:105] op_sel_hi:[1,0]
	v_pk_mul_f32 v[48:49], v[80:81], v[104:105] op_sel_hi:[1,0]
	s_waitcnt lgkmcnt(0)
	s_nop 0
	v_mfma_f32_16x16x32_bf16 v[72:75], v[0:3], v[52:55], v[48:51]
	s_nop 2
	ds_read_b128 v[48:51], v186 offset:13056
	ds_read_b128 v[80:83], v186 offset:13120
	v_cvt_pk_bf16_f32 v52, v84, v85
	v_cvt_pk_bf16_f32 v53, v86, v87
	v_cvt_pk_bf16_f32 v54, v44, v45
	v_cvt_pk_bf16_f32 v55, v46, v47
	v_cvt_pk_bf16_f32 v92, v76, v77
	v_cvt_pk_bf16_f32 v93, v78, v79
	v_cvt_pk_bf16_f32 v94, v68, v69
	s_waitcnt lgkmcnt(1)
	v_mfma_f32_16x16x32_bf16 v[48:51], v[48:51], v[52:55], 0
	ds_read_b128 v[52:55], v186 offset:13184
	ds_read_b128 v[96:99], v186 offset:13248
	v_cvt_pk_bf16_f32 v95, v70, v71
	v_mov_b32_e32 v0, s55
	ds_read_b64_tr_b16 v[102:103], v191 offset:65280
	ds_read_b32 v100, v0 offset:1292
	ds_read_b64 v[0:1], v192 offset:13056
	s_waitcnt lgkmcnt(5)
	v_mfma_f32_16x16x32_bf16 v[80:83], v[80:83], v[92:95], 0
	v_cvt_pk_bf16_f32 v92, v88, v89
	v_cvt_pk_bf16_f32 v93, v90, v91
	v_cvt_pk_bf16_f32 v94, v64, v65
	v_cvt_pk_bf16_f32 v95, v66, v67
	s_waitcnt lgkmcnt(4)
	s_nop 0
	v_mfma_f32_16x16x32_bf16 v[48:51], v[52:55], v[92:95], v[48:51]
	v_cvt_pk_bf16_f32 v52, v56, v57
	v_cvt_pk_bf16_f32 v53, v58, v59
	v_cvt_pk_bf16_f32 v54, v60, v61
	v_cvt_pk_bf16_f32 v55, v62, v63
	s_waitcnt lgkmcnt(3)
	s_nop 0
	v_mfma_f32_16x16x32_bf16 v[92:95], v[96:99], v[52:55], v[80:83]
	ds_read_b128 v[52:55], v187 offset:704
	s_nop 1
	ds_read_b128 v[80:83], v187 offset:960
	v_cvt_pk_bf16_f32 v96, v72, v73
	v_cvt_pk_bf16_f32 v97, v74, v75
	v_mov_b32_e32 v98, v3
	v_mov_b32_e32 v99, v3
	s_waitcnt lgkmcnt(2)
	s_nop 0
	v_mfma_f32_16x16x32_bf16 v[96:99], v[0:3], v[96:99], 0
	s_and_saveexec_b64 s[0:1], s[10:11]
	s_nop 6
	ds_write_b128 v175, v[96:99] offset:192
	s_or_b64 exec, exec, s[0:1]
	v_pk_add_f32 v[48:49], v[48:49], v[92:93]
	v_pk_add_f32 v[0:1], v[50:51], v[94:95]
	s_waitcnt lgkmcnt(1)
	v_pk_fma_f32 v[40:41], v[48:49], v[52:53], v[40:41]
	v_add_u32_e32 v2, 0x6200, v193
	v_pk_fma_f32 v[0:1], v[0:1], v[54:55], v[42:43]
	ds_write2_b32 v2, v40, v41 offset0:64 offset1:196
	v_add_u32_e32 v2, 0x6600, v193
	ds_write2_b32 v2, v0, v1 offset0:72 offset1:204
	v_lshlrev_b32_e32 v0, 16, v102
	v_and_b32_e32 v1, 0xffff0000, v102
	v_lshlrev_b32_e32 v40, 16, v103
	v_and_b32_e32 v41, 0xffff0000, v103
	s_waitcnt lgkmcnt(2)
	v_pk_mul_f32 v[0:1], v[80:81], v[0:1]
	v_pk_mul_f32 v[40:41], v[82:83], v[40:41]
	v_cvt_pk_bf16_f32 v0, v0, v1
	v_cvt_pk_bf16_f32 v1, v40, v41
	ds_read_b64_tr_b16 v[40:41], v189 offset:30464
	v_mov_b32_e32 v42, v3
	v_mov_b32_e32 v43, v3
	v_mov_b32_e32 v54, v3
	v_mov_b32_e32 v55, v3
	v_pk_mul_f32 v[50:51], v[86:87], v[100:101] op_sel_hi:[1,0]
	v_mov_b32_e32 v86, v3
	v_mov_b32_e32 v87, v3
	v_pk_mul_f32 v[48:49], v[84:85], v[100:101] op_sel_hi:[1,0]
	ds_read_b64_tr_b16 v[52:53], v189 offset:30472
	ds_read_b64_tr_b16 v[84:85], v189 offset:30528
	ds_read_b64_tr_b16 v[92:93], v189 offset:30536
	v_mov_b32_e32 v2, v3
	v_pk_mul_f32 v[46:47], v[46:47], v[100:101] op_sel_hi:[1,0]
	v_pk_mul_f32 v[44:45], v[44:45], v[100:101] op_sel_hi:[1,0]
	s_waitcnt lgkmcnt(3)
	v_mfma_f32_16x16x32_bf16 v[40:43], v[40:43], v[0:3], v[48:51]
	v_mov_b32_e32 v94, v3
	v_mov_b32_e32 v95, v3
	v_pk_mul_f32 v[66:67], v[66:67], v[100:101] op_sel_hi:[1,0]
	s_waitcnt lgkmcnt(2)
	v_mfma_f32_16x16x32_bf16 v[48:51], v[52:55], v[0:3], v[44:47]
	v_mul_f32_e64 v64, v64, v100
	v_mul_f32_e64 v65, v65, v100
	v_pk_mul_f32 v[58:59], v[58:59], v[100:101] op_sel_hi:[1,0]
	v_pk_mul_f32 v[56:57], v[56:57], v[100:101] op_sel_hi:[1,0]
	v_pk_mul_f32 v[46:47], v[78:79], v[100:101] op_sel_hi:[1,0]
	v_pk_mul_f32 v[44:45], v[76:77], v[100:101] op_sel_hi:[1,0]
	v_pk_mul_f32 v[78:79], v[90:91], v[100:101] op_sel_hi:[1,0]
	v_pk_mul_f32 v[76:77], v[88:89], v[100:101] op_sel_hi:[1,0]
	s_waitcnt lgkmcnt(1)
	v_mfma_f32_16x16x32_bf16 v[52:55], v[84:87], v[0:3], v[44:47]
	v_mov_b32_e32 v90, v3
	v_mov_b32_e32 v91, v3
	v_pk_mul_f32 v[62:63], v[62:63], v[100:101] op_sel_hi:[1,0]
	v_pk_mul_f32 v[44:45], v[68:69], v[100:101] op_sel_hi:[1,0]
	ds_read_b64_tr_b16 v[68:69], v189 offset:30592
	v_pk_mul_f32 v[46:47], v[70:71], v[100:101] op_sel_hi:[1,0]
	v_mov_b32_e32 v70, v3
	v_mov_b32_e32 v71, v3
	s_waitcnt lgkmcnt(1)
	v_mfma_f32_16x16x32_bf16 v[44:47], v[92:95], v[0:3], v[44:47]
	ds_read_b64_tr_b16 v[84:85], v189 offset:30600
	ds_read_b64_tr_b16 v[88:89], v189 offset:30656
	ds_read_b64_tr_b16 v[92:93], v189 offset:30664
	v_pk_mul_f32 v[60:61], v[60:61], v[100:101] op_sel_hi:[1,0]
	v_pk_mul_f32 v[74:75], v[74:75], v[100:101] op_sel_hi:[1,0]
	s_waitcnt lgkmcnt(3)
	v_mfma_f32_16x16x32_bf16 v[68:71], v[68:71], v[0:3], v[76:79]
	v_mul_f32_e64 v72, v72, v100
	v_mul_f32_e64 v73, v73, v100
	s_mov_b64 s[0:1], 0
	v_cvt_pk_bf16_f32 v76, v80, v81
	s_waitcnt lgkmcnt(2)
	v_mfma_f32_16x16x32_bf16 v[64:67], v[84:87], v[0:3], v[64:67]
	v_cvt_pk_bf16_f32 v77, v82, v83
	v_mov_b32_e32 v78, v3
	v_mov_b32_e32 v79, v3
	s_waitcnt lgkmcnt(1)
	v_mfma_f32_16x16x32_bf16 v[56:59], v[88:91], v[0:3], v[56:59]
	s_waitcnt lgkmcnt(0)
	v_mfma_f32_16x16x32_bf16 v[60:63], v[92:95], v[0:3], v[60:63]
	ds_read_b64_tr_b16 v[0:1], v194 offset:30464
	s_waitcnt lgkmcnt(0)
	v_mfma_f32_16x16x32_bf16 v[72:75], v[0:3], v[76:79], v[72:75]

; #define LAS __attribute__((address_space(3)))
; __device__ __forceinline__ u32x2 tr16(const LAS unsigned char* p) { return __builtin_bit_cast(u32x2, __builtin_amdgcn_ds_read_tr16_b64_v4i16((LAS v4i16_t*)p)); }
; __device__ __forceinline__ f32x4 mfma16k16(u32x2 a, u32x2 b, f32x4 c) { const u32x4 a4 = {a.x, a.y, 0u, 0u}, b4 = {b.x, b.y, 0u, 0u}; return __builtin_amdgcn_mfma_f32_16x16x32_bf16(__builtin_bit_cast(bf16x8, a4), __builtin_bit_cast(bf16x8, b4), c, 0, 0, 0); }
; template <int NMC>
; __device__ __forceinline__ void hg_chain(LAS unsigned char* L, f32x4 (&S)[8], int w, int r16, int q) {
;     ...
;             for (int mt = 0; mt < 8; ++mt) {
;                 const f32x4 gd = *(const LAS f32x4*)(GD + mc * 128 + 16 * mt + 4 * q);
;                 const u32x2 kt = tr16(Kb + (4 * q + (r16 >> 2)) * MX_PITCH + MX_POS4(16 * mt + 4 * (r16 & 3)) * 2);
;                 S[mt] = mfma16k16(kt, vt, S[mt]); S[mt] = S[mt] * gd;
;             }
; __device__ __forceinline__ void mix_hg_unit(Frame& F, int b, int h, int mode) {
;     ...
;     __syncthreads();
;     if (mode != 2) {
;         int l2 = F.lane; asm volatile("" : "+v"(l2)); const int r16 = l2 & 15, q = l2 >> 4;
;         float* So = F.out + (prompt ? O_HP : O_HS) + (size_t)(b * 8 + h) * 16384;
; #pragma unroll
;         for (int mt = 0; mt < 8; ++mt)
; #pragma unroll
;             for (int r = 0; r < 4; ++r) __builtin_nontemporal_store(S[mt][r], So + (16 * mt + 4 * q + r) * 128 + 16 * w + r16);
.LBB0_851:
	s_or_b64 exec, exec, s[36:37]
	v_pk_mul_f32 v[14:15], v[18:19], v[14:15]
	v_mov_b32_e32 v18, v190
	s_barrier
	s_add_u32 s28, s1, s28
	v_and_b32_e32 v2, 15, v18
	s_addc_u32 s29, s38, s29
	v_lshlrev_b32_e32 v2, 2, v2
	v_pk_mul_f32 v[12:13], v[16:17], v[12:13]
	v_lshl_add_u64 v[16:17], s[28:29], 0, v[2:3]
	v_lshlrev_b32_e32 v2, 5, v18
	v_and_b32_e32 v18, 0xfffffe00, v2
	v_ashrrev_i32_e32 v19, 31, v18
	v_pk_mul_f32 v[0:1], v[26:27], v[54:55]
	v_pk_mul_f32 v[4:5], v[24:25], v[52:53]
	v_pk_mul_f32 v[26:27], v[38:39], v[62:63]
	v_lshl_add_u64 v[38:39], v[18:19], 2, v[16:17]
	global_store_dword v[38:39], v4, off nt
	global_store_dword v[38:39], v5, off offset:512 nt
	global_store_dword v[38:39], v0, off offset:1024 nt
	global_store_dword v[38:39], v1, off offset:1536 nt
	v_add_u32_e32 v0, 0x800, v18
	v_ashrrev_i32_e32 v1, 31, v0
	v_pk_mul_f32 v[8:9], v[48:49], v[44:45]
	v_lshl_add_u64 v[0:1], v[0:1], 2, v[16:17]
	global_store_dword v[0:1], v8, off nt
	v_add_u32_e32 v0, 0x880, v18
	v_ashrrev_i32_e32 v1, 31, v0
	v_lshl_add_u64 v[0:1], v[0:1], 2, v[16:17]
	global_store_dword v[0:1], v9, off nt
	v_add_u32_e32 v0, 0x900, v18
	v_ashrrev_i32_e32 v1, 31, v0
	v_pk_mul_f32 v[6:7], v[50:51], v[46:47]
	v_lshl_add_u64 v[0:1], v[0:1], 2, v[16:17]
	global_store_dword v[0:1], v6, off nt
	v_add_u32_e32 v0, 0x980, v18
	v_ashrrev_i32_e32 v1, 31, v0
	v_lshl_add_u64 v[0:1], v[0:1], 2, v[16:17]
	global_store_dword v[0:1], v7, off nt
	v_add_u32_e32 v0, 0x1000, v18
	v_ashrrev_i32_e32 v1, 31, v0
	v_pk_mul_f32 v[24:25], v[40:41], v[56:57]
	v_lshl_add_u64 v[0:1], v[0:1], 2, v[16:17]
	global_store_dword v[0:1], v24, off nt
	v_add_u32_e32 v0, 0x1080, v18
	v_ashrrev_i32_e32 v1, 31, v0
	v_lshl_add_u64 v[0:1], v[0:1], 2, v[16:17]
	global_store_dword v[0:1], v25, off nt
	v_add_u32_e32 v0, 0x1100, v18
	v_ashrrev_i32_e32 v1, 31, v0
	v_pk_mul_f32 v[10:11], v[42:43], v[58:59]
	v_lshl_add_u64 v[0:1], v[0:1], 2, v[16:17]
	global_store_dword v[0:1], v10, off nt
	v_add_u32_e32 v0, 0x1180, v18
	v_ashrrev_i32_e32 v1, 31, v0
	v_lshl_add_u64 v[0:1], v[0:1], 2, v[16:17]
	global_store_dword v[0:1], v11, off nt
	v_add_u32_e32 v0, 0x1800, v18
	v_ashrrev_i32_e32 v1, 31, v0
	v_pk_mul_f32 v[36:37], v[36:37], v[60:61]
	v_lshl_add_u64 v[0:1], v[0:1], 2, v[16:17]
	global_store_dword v[0:1], v36, off nt
	v_add_u32_e32 v0, 0x1880, v18
	v_ashrrev_i32_e32 v1, 31, v0
	v_lshl_add_u64 v[0:1], v[0:1], 2, v[16:17]
	global_store_dword v[0:1], v37, off nt
	v_add_u32_e32 v0, 0x1900, v18
	v_ashrrev_i32_e32 v1, 31, v0
	v_lshl_add_u64 v[0:1], v[0:1], 2, v[16:17]
	global_store_dword v[0:1], v26, off nt
	v_add_u32_e32 v0, 0x1980, v18
	v_ashrrev_i32_e32 v1, 31, v0
	v_lshl_add_u64 v[0:1], v[0:1], 2, v[16:17]
	global_store_dword v[0:1], v27, off nt
	v_add_u32_e32 v0, 0x2000, v18
	v_ashrrev_i32_e32 v1, 31, v0
	v_pk_mul_f32 v[32:33], v[32:33], v[64:65]
	v_lshl_add_u64 v[0:1], v[0:1], 2, v[16:17]
	global_store_dword v[0:1], v32, off nt
	v_add_u32_e32 v0, 0x2080, v18
	v_ashrrev_i32_e32 v1, 31, v0
	v_lshl_add_u64 v[0:1], v[0:1], 2, v[16:17]
	global_store_dword v[0:1], v33, off nt
	v_add_u32_e32 v0, 0x2100, v18
	v_ashrrev_i32_e32 v1, 31, v0
	v_pk_mul_f32 v[34:35], v[34:35], v[66:67]
	v_lshl_add_u64 v[0:1], v[0:1], 2, v[16:17]
	global_store_dword v[0:1], v34, off nt
	v_add_u32_e32 v0, 0x2180, v18
	v_ashrrev_i32_e32 v1, 31, v0
	v_lshl_add_u64 v[0:1], v[0:1], 2, v[16:17]
	global_store_dword v[0:1], v35, off nt
	v_add_u32_e32 v0, 0x2800, v18
	v_ashrrev_i32_e32 v1, 31, v0
	v_pk_mul_f32 v[28:29], v[28:29], v[76:77]
	v_lshl_add_u64 v[0:1], v[0:1], 2, v[16:17]
	global_store_dword v[0:1], v28, off nt
	v_add_u32_e32 v0, 0x2880, v18
	v_ashrrev_i32_e32 v1, 31, v0
	v_lshl_add_u64 v[0:1], v[0:1], 2, v[16:17]
	global_store_dword v[0:1], v29, off nt
	v_add_u32_e32 v0, 0x2900, v18
	v_ashrrev_i32_e32 v1, 31, v0
	v_pk_mul_f32 v[30:31], v[30:31], v[78:79]
	v_lshl_add_u64 v[0:1], v[0:1], 2, v[16:17]
	global_store_dword v[0:1], v30, off nt
	v_add_u32_e32 v0, 0x2980, v18
	v_ashrrev_i32_e32 v1, 31, v0
	v_lshl_add_u64 v[0:1], v[0:1], 2, v[16:17]
	global_store_dword v[0:1], v31, off nt
	v_add_u32_e32 v0, 0x3000, v18
	v_ashrrev_i32_e32 v1, 31, v0
	v_pk_mul_f32 v[20:21], v[20:21], v[84:85]
	v_lshl_add_u64 v[0:1], v[0:1], 2, v[16:17]
	global_store_dword v[0:1], v20, off nt
	v_add_u32_e32 v0, 0x3080, v18
	v_ashrrev_i32_e32 v1, 31, v0
	v_lshl_add_u64 v[0:1], v[0:1], 2, v[16:17]
	global_store_dword v[0:1], v21, off nt
	v_add_u32_e32 v0, 0x3100, v18
	v_ashrrev_i32_e32 v1, 31, v0
	v_pk_mul_f32 v[22:23], v[22:23], v[86:87]
	v_lshl_add_u64 v[0:1], v[0:1], 2, v[16:17]
	global_store_dword v[0:1], v22, off nt
	v_add_u32_e32 v0, 0x3180, v18
	v_ashrrev_i32_e32 v1, 31, v0
	v_lshl_add_u64 v[0:1], v[0:1], 2, v[16:17]
	global_store_dword v[0:1], v23, off nt
	v_add_u32_e32 v0, 0x3800, v18
	v_ashrrev_i32_e32 v1, 31, v0
	v_lshl_add_u64 v[0:1], v[0:1], 2, v[16:17]
	global_store_dword v[0:1], v12, off nt
	v_add_u32_e32 v0, 0x3880, v18
	v_ashrrev_i32_e32 v1, 31, v0
	v_lshl_add_u64 v[0:1], v[0:1], 2, v[16:17]
	global_store_dword v[0:1], v13, off nt
	v_add_u32_e32 v0, 0x3900, v18
	v_ashrrev_i32_e32 v1, 31, v0
	v_lshl_add_u64 v[0:1], v[0:1], 2, v[16:17]
	global_store_dword v[0:1], v14, off nt
	v_add_u32_e32 v0, 0x3980, v18
	v_ashrrev_i32_e32 v1, 31, v0
	v_lshl_add_u64 v[0:1], v[0:1], 2, v[16:17]
	global_store_dword v[0:1], v15, off nt

; #define LAS __attribute__((address_space(3)))
; __device__ __forceinline__ void mix_hg_unit(Frame& F, int b, int h, int mode) {
;     ...
;     if (!prompt) {
;         const float* Sin = F.in[6] + (size_t)(b * 8 + h) * 16384;
; #pragma unroll
;         for (int mt = 0; mt < 8; ++mt)
; #pragma unroll
;             for (int r = 0; r < 4; ++r) S[mt][r] = __builtin_nontemporal_load(Sin + (16 * mt + 4 * q + r) * 128 + 16 * w + r16);
;     }
;     LAS float* GN = (LAS float*)(L + MX_GN);
;     if (tid < 128) GN[tid] = F.in[18][128 * h + tid];
.LBB0_863:
	s_and_b64 vcc, exec, s[28:29]
	s_cbranch_vccz .LBB0_852
	s_ashr_i32 s25, s24, 31
	s_lshl_b64 s[28:29], s[24:25], 16
	s_add_i32 s25, s26, 0x20000
	s_and_b32 s76, s25, 0x380
	s_and_saveexec_b64 s[34:35], s[4:5]
	s_cbranch_execz .LBB0_866
	v_add_u32_e32 v0, s76, v145
	v_readlane_b32 s56, v252, 13
	v_ashrrev_i32_e32 v1, 31, v0
	v_readlane_b32 s60, v252, 17
	v_readlane_b32 s61, v252, 18
	v_readlane_b32 s62, v252, 19
	v_readlane_b32 s63, v252, 20
	v_lshl_add_u64 v[0:1], v[0:1], 2, s[60:61]
	global_load_dword v0, v[0:1], off
	v_readlane_b32 s64, v252, 21
	v_readlane_b32 s65, v252, 22
	v_readlane_b32 s66, v252, 23
	v_readlane_b32 s67, v252, 24
	v_readlane_b32 s71, v252, 28
	v_readlane_b32 s62, v253, 29
	v_readlane_b32 s64, v252, 3
	s_mov_b32 s71, s43
	v_readlane_b32 s63, v253, 30
	v_readlane_b32 s65, v252, 4
	v_readlane_b32 s66, v254, 30
	v_readlane_b32 s57, v252, 14
	v_readlane_b32 s58, v252, 15
	v_readlane_b32 s59, v252, 16
	v_readlane_b32 s68, v252, 25
	v_readlane_b32 s69, v252, 26
	v_readlane_b32 s70, v252, 27
	v_readlane_b32 s67, v254, 31
	s_waitcnt vmcnt(0)
	ds_write_b32 v104, v0

; #define LAS __attribute__((address_space(3)))
; #define MSTAMP(id) do { if (blockIdx.x == PROBE_BLOCK && tid == 0) { const unsigned long long t_now_ = __builtin_amdgcn_s_memrealtime(); volatile LAS unsigned long long* a_ = (volatile LAS unsigned long long*)(F.lds + 139264 + 128) + 48 + (id); *a_ = *a_ + (t_now_ - t_last_); t_last_ = t_now_; } } while (0)
; #define MSTAMP(id) do { } while (0)
; __device__ __forceinline__ void mix_hg_unit(Frame& F, int b, int h, int mode) {
;     ...
;         const float* Sin = F.in[6] + (size_t)(b * 8 + h) * 16384;
; #pragma unroll
;         for (int mt = 0; mt < 8; ++mt)
; #pragma unroll
;             for (int r = 0; r < 4; ++r) S[mt][r] = __builtin_nontemporal_load(Sin + (16 * mt + 4 * q + r) * 128 + 16 * w + r16);
;     ...
;         {
;             const int c0 = (MX_POS4(16 * p)) * 2;
; #pragma unroll
;             for (int g = 0; g < 4; ++g) {
;                 *(LAS u32x2*)(L + MX_Q + tk * MX_PITCH + c0 + 16 * g) = (u32x2){pa[g >> 1][2 * (g & 1)], pa[g >> 1][2 * (g & 1) + 1]};
;                 *(LAS u32x2*)(L + MX_K + tk * MX_PITCH + c0 + 16 * g) = (u32x2){pa[2 + (g >> 1)][2 * (g & 1)], pa[2 + (g >> 1)][2 * (g & 1) + 1]};
;             }
;             *(LAS u32x4*)(L + MX_V + tk * MX_PITCH + 32 * p) = pa[4]; *(LAS u32x4*)(L + MX_V + tk * MX_PITCH + 32 * p + 16) = pa[5];
;             GD[tid] = pgd;
;         }
;         MSTAMP(9);
;         __syncthreads();
.LBB0_870:
	s_or_b64 exec, exec, s[36:37]
	s_lshl_b32 s98, s24, 16
	s_mov_b32 s99, 0
	v_lshl_add_u64 v[142:143], v[100:101], 0, s[98:99]
	s_mov_b32 s98, 0x2000
	global_load_dword v40, v[142:143], off nt
	global_load_dword v41, v[142:143], off offset:512 nt
	global_load_dword v42, v[142:143], off offset:1024 nt
	global_load_dword v43, v[142:143], off offset:1536 nt
	v_lshl_add_u64 v[142:143], v[142:143], 0, s[98:99]
	global_load_dword v44, v[142:143], off nt
	global_load_dword v45, v[142:143], off offset:512 nt
	global_load_dword v46, v[142:143], off offset:1024 nt
	global_load_dword v47, v[142:143], off offset:1536 nt
	v_lshl_add_u64 v[142:143], v[142:143], 0, s[98:99]
	global_load_dword v36, v[142:143], off nt
	global_load_dword v37, v[142:143], off offset:512 nt
	global_load_dword v38, v[142:143], off offset:1024 nt
	global_load_dword v39, v[142:143], off offset:1536 nt
	v_lshl_add_u64 v[142:143], v[142:143], 0, s[98:99]
	global_load_dword v32, v[142:143], off nt
	global_load_dword v33, v[142:143], off offset:512 nt
	global_load_dword v34, v[142:143], off offset:1024 nt
	global_load_dword v35, v[142:143], off offset:1536 nt
	v_lshl_add_u64 v[142:143], v[142:143], 0, s[98:99]
	global_load_dword v28, v[142:143], off nt
	global_load_dword v29, v[142:143], off offset:512 nt
	global_load_dword v30, v[142:143], off offset:1024 nt
	global_load_dword v31, v[142:143], off offset:1536 nt
	v_lshl_add_u64 v[142:143], v[142:143], 0, s[98:99]
	global_load_dword v20, v[142:143], off nt
	global_load_dword v21, v[142:143], off offset:512 nt
	global_load_dword v22, v[142:143], off offset:1024 nt
	global_load_dword v23, v[142:143], off offset:1536 nt
	v_lshl_add_u64 v[142:143], v[142:143], 0, s[98:99]
	global_load_dword v16, v[142:143], off nt
	global_load_dword v17, v[142:143], off offset:512 nt
	global_load_dword v18, v[142:143], off offset:1024 nt
	global_load_dword v19, v[142:143], off offset:1536 nt
	v_lshl_add_u64 v[142:143], v[142:143], 0, s[98:99]
	global_load_dword v12, v[142:143], off nt
	global_load_dword v13, v[142:143], off offset:512 nt
	global_load_dword v14, v[142:143], off offset:1024 nt
	global_load_dword v15, v[142:143], off offset:1536 nt
	v_add_u32_e32 v2, v108, v107
	s_waitcnt vmcnt(37)
	ds_write2_b64 v2, v[48:49], v[50:51] offset1:2
	v_add_u32_e32 v48, 0x4000, v2
	s_mov_b64 s[56:57], s[68:69]
	s_waitcnt vmcnt(35)
	ds_write2_b64 v48, v[52:53], v[54:55] offset0:128 offset1:130
	ds_write2_b64 v2, v[4:5], v[6:7] offset0:4 offset1:6
	s_waitcnt vmcnt(34)
	ds_write2_b64 v48, v[8:9], v[10:11] offset0:132 offset1:134
	v_add_u32_e32 v2, v108, v94
	s_mov_b32 s58, s70
	s_mov_b32 s59, s71
	s_waitcnt vmcnt(33)
	ds_write_b128 v2, v[24:27] offset:52224
	s_waitcnt vmcnt(32)
	ds_write_b128 v2, v[56:59] offset:52240
	ds_write_b32 v109, v1
	s_waitcnt lgkmcnt(0)
	s_barrier
; #define LAS __attribute__((address_space(3)))
; template <int NMC>
; __device__ __forceinline__ void hg_chain(LAS unsigned char* L, f32x4 (&S)[8], int w, int r16, int q) {
;     ...
; #pragma unroll
;     for (int mc = 0; mc < NMC; ++mc) {
;         oo[mc] = (f32x4){0.f, 0.f, 0.f, 0.f};
;         {
;             const LAS unsigned char* Qb = L + MX_Q + 16 * mc * MX_PITCH; const LAS unsigned char* Kb = L + MX_K + 16 * mc * MX_PITCH; const LAS unsigned char* Vb = L + MX_V + 16 * mc * MX_PITCH;
;             f32x4 g0 = {0.f, 0.f, 0.f, 0.f}, g1 = {0.f, 0.f, 0.f, 0.f};
; #pragma unroll
;             for (int ks = 0; ks < 4; ++ks) {
;                 const bf16x8 kf = ld8(Kb + r16 * MX_PITCH + (32 * ks + 8 * q) * 2), qf = ld8(Qb + r16 * MX_PITCH + (32 * ks + 8 * q) * 2);
;                 if (ks & 1) g1 = MFMA16(kf, qf, g1); else g0 = MFMA16(kf, qf, g0);
;             }
;             const f32x4 g = g0 + g1;
;             f32x4 P;
; #pragma unroll
;             for (int r = 0; r < 4; ++r) P[r] = (4 * q + r <= r16) ? g[r] : 0.f;
;             const u32x2 vt = tr16(Vb + (4 * q + (r16 >> 2)) * MX_PITCH + (16 * w + 4 * (r16 & 3)) * 2);
;             oo[mc] = mfma16k16((u32x2){pkbf(P[0], P[1]), pkbf(P[2], P[3])}, vt, oo[mc]);
;         }
;         if (mc == 1) __builtin_amdgcn_sched_barrier(0);
;     }
; #pragma unroll
;     for (int mc = 0; mc < NMC; ++mc) {
;         {
;             const LAS unsigned char* Qb = L + MX_Q + 16 * mc * MX_PITCH; const LAS unsigned char* Kb = L + MX_K + 16 * mc * MX_PITCH;
;             const u32x2 vt = tr16(L + MX_V + 16 * mc * MX_PITCH + (4 * q + (r16 >> 2)) * MX_PITCH + (16 * w + 4 * (r16 & 3)) * 2);
;             f32x4 o2b = {0.f, 0.f, 0.f, 0.f};
; #pragma unroll
;             for (int ks = 0; ks < 4; ++ks) {
;                 const bf16x8 qf = ld8(Qb + r16 * MX_PITCH + (32 * ks + 8 * q) * 2);
;                 const bf16x8 SB = mk8(pkbf(S[2 * ks][0], S[2 * ks][1]), pkbf(S[2 * ks][2], S[2 * ks][3]), pkbf(S[2 * ks + 1][0], S[2 * ks + 1][1]), pkbf(S[2 * ks + 1][2], S[2 * ks + 1][3]));
;                 if (ks & 1) o2b = MFMA16(qf, SB, o2b); else oo[mc] = MFMA16(qf, SB, oo[mc]);
;             }
;             oo[mc] = oo[mc] + o2b;
; #pragma unroll
;             for (int mt = 0; mt < 8; ++mt) {
;                 const f32x4 gd = *(const LAS f32x4*)(GD + mc * 128 + 16 * mt + 4 * q);
	buffer_load_dwordx4 v[8:11], v0, s[56:59], 0 offen offset:2048
	buffer_load_dwordx4 v[4:7], v0, s[56:59], 0 offen offset:2064
	v_add_u32_e32 v0, v95, v112
	ds_read_b128 v[24:27], v0
	ds_read_b128 v[48:51], v0 offset:17408
	ds_read_b128 v[52:55], v0 offset:64
	ds_read_b128 v[56:59], v0 offset:17472
	ds_read_b128 v[60:63], v0 offset:128
	ds_read_b128 v[64:67], v0 offset:17536
	ds_read_b128 v[76:79], v0 offset:192
	ds_read_b128 v[68:71], v0 offset:17600
	s_waitcnt lgkmcnt(6)
	v_mfma_f32_16x16x32_bf16 v[48:51], v[48:51], v[24:27], 0
	s_mov_b32 s50, s58
	v_writelane_b32 v254, s48, 22
	s_waitcnt lgkmcnt(4)
	v_mfma_f32_16x16x32_bf16 v[56:59], v[56:59], v[52:55], 0
	v_writelane_b32 v254, s49, 23
	v_writelane_b32 v254, s50, 24
	v_writelane_b32 v254, s51, 25
	s_waitcnt lgkmcnt(2)
	v_mfma_f32_16x16x32_bf16 v[48:51], v[64:67], v[60:63], v[48:51]
	s_waitcnt lgkmcnt(0)
	v_mfma_f32_16x16x32_bf16 v[56:59], v[68:71], v[76:79], v[56:59]
	v_mov_b32_e32 v70, v3
	v_mov_b32_e32 v71, v3
	s_nop 5
	v_pk_add_f32 v[0:1], v[50:51], v[58:59]
	v_pk_add_f32 v[48:49], v[48:49], v[56:57]
	v_cndmask_b32_e64 v1, v1, 0, s[10:11]
	v_cndmask_b32_e64 v2, v48, 0, s[16:17]
	v_cndmask_b32_e64 v48, 0, v49, s[14:15]
	v_cndmask_b32_e64 v49, v0, 0, s[12:13]
	v_add_u32_e32 v0, v117, v118
	ds_read_b64_tr_b16 v[68:69], v0 offset:52224
	v_cvt_pk_bf16_f32 v0, v2, v48
	v_cvt_pk_bf16_f32 v1, v49, v1
	v_mov_b32_e32 v2, v3
	s_waitcnt vmcnt(2)
	v_cvt_pk_bf16_f32 v56, v40, v41
	v_cvt_pk_bf16_f32 v57, v42, v43
	s_waitcnt lgkmcnt(0)
	v_mfma_f32_16x16x32_bf16 v[48:51], v[0:3], v[68:71], 0
	v_cvt_pk_bf16_f32 v58, v44, v45
	v_cvt_pk_bf16_f32 v59, v46, v47
	s_nop 1
	v_mfma_f32_16x16x32_bf16 v[24:27], v[24:27], v[56:59], v[48:51]
	v_mov_b32_e32 v58, v3
	v_mov_b32_e32 v59, v3
	s_nop 0
	v_cvt_pk_bf16_f32 v48, v36, v37
	v_cvt_pk_bf16_f32 v49, v38, v39
	v_cvt_pk_bf16_f32 v50, v32, v33
	v_cvt_pk_bf16_f32 v51, v34, v35
	s_nop 1
	v_mfma_f32_16x16x32_bf16 v[48:51], v[52:55], v[48:51], 0
	v_cvt_pk_bf16_f32 v52, v28, v29
	v_cvt_pk_bf16_f32 v53, v30, v31
	v_cvt_pk_bf16_f32 v54, v20, v21
	v_cvt_pk_bf16_f32 v55, v22, v23
	s_nop 1
	v_mfma_f32_16x16x32_bf16 v[72:75], v[60:63], v[52:55], v[24:27]
	s_nop 2
	v_cvt_pk_bf16_f32 v24, v16, v17
	v_cvt_pk_bf16_f32 v25, v18, v19
	v_cvt_pk_bf16_f32 v26, v12, v13
	v_cvt_pk_bf16_f32 v27, v14, v15
	s_nop 1
	v_mfma_f32_16x16x32_bf16 v[80:83], v[76:79], v[24:27], v[48:51]
	ds_read_b128 v[24:27], v119
	ds_read_b64_tr_b16 v[0:1], v123 offset:17408
	ds_read_b64_tr_b16 v[56:57], v123 offset:17416
	ds_read_b128 v[48:51], v119 offset:64
	s_waitcnt lgkmcnt(2)
	v_mfma_f32_16x16x32_bf16 v[52:55], v[0:3], v[68:71], v[40:43]
	s_nop 2
	ds_read_b128 v[40:43], v119 offset:128
	ds_read_b64_tr_b16 v[0:1], v123 offset:17472
	s_waitcnt lgkmcnt(3)
	v_mfma_f32_16x16x32_bf16 v[44:47], v[56:59], v[68:71], v[44:47]
	s_waitcnt lgkmcnt(0)
	v_mfma_f32_16x16x32_bf16 v[56:59], v[0:3], v[68:71], v[36:39]
	s_nop 2
	ds_read_b128 v[36:39], v119 offset:192
	ds_read_b64_tr_b16 v[0:1], v123 offset:17480
	s_waitcnt lgkmcnt(0)
	v_mfma_f32_16x16x32_bf16 v[60:63], v[0:3], v[68:71], v[32:35]
	s_nop 2
	ds_read_b128 v[32:35], v119 offset:256
	ds_read_b64_tr_b16 v[0:1], v123 offset:17536
	s_waitcnt lgkmcnt(0)
	v_mfma_f32_16x16x32_bf16 v[64:67], v[0:3], v[68:71], v[28:31]
	s_nop 2
	ds_read_b128 v[28:31], v119 offset:320
	ds_read_b64_tr_b16 v[0:1], v123 offset:17544
	s_waitcnt lgkmcnt(0)
	v_mfma_f32_16x16x32_bf16 v[76:79], v[0:3], v[68:71], v[20:23]
	s_nop 2
	ds_read_b128 v[20:23], v119 offset:384
	ds_read_b64_tr_b16 v[0:1], v124 offset:17408
	s_waitcnt lgkmcnt(0)
	v_mfma_f32_16x16x32_bf16 v[84:87], v[0:3], v[68:71], v[16:19]
	s_nop 2
	ds_read_b128 v[16:19], v119 offset:448
	ds_read_b64_tr_b16 v[0:1], v125 offset:17408
	s_waitcnt lgkmcnt(0)
	v_mfma_f32_16x16x32_bf16 v[12:15], v[0:3], v[68:71], v[12:15]
	v_add_f32_e64 v68, v72, v80
	v_add_f32_e64 v69, v73, v81
	v_add_u32_e32 v2, v113, v116
	v_pk_add_f32 v[0:1], v[74:75], v[82:83]
	ds_write2_b32 v2, v68, v69 offset1:132
	v_add_u32_e32 v2, v113, v115
	ds_write_b32 v2, v0
	v_add_u32_e32 v0, v113, v114
	ds_write_b32 v0, v1
	s_waitcnt lgkmcnt(0)
	s_barrier
	s_waitcnt vmcnt(0)
	ds_read_b128 v[88:91], v110
	ds_read_b128 v[80:83], v110 offset:16
	ds_read_b128 v[72:75], v110 offset:32
	ds_read_b128 v[68:71], v110 offset:48
	s_and_saveexec_b64 s[36:37], s[20:21]
	s_cbranch_execz .LBB0_872
	s_waitcnt lgkmcnt(2)
	v_mov_b32_e32 v80, 0
	v_mov_b32_e32 v81, v80
	v_mov_b32_e32 v82, v80
	v_mov_b32_e32 v83, v80
	v_mov_b32_e32 v88, v80
	v_mov_b32_e32 v89, v80
	v_mov_b32_e32 v90, v80
	v_mov_b32_e32 v91, v80
	s_waitcnt lgkmcnt(1)
	v_mov_b32_e32 v72, v80
	v_mov_b32_e32 v73, v80
	v_mov_b32_e32 v74, v80
	v_mov_b32_e32 v75, v80
	s_waitcnt lgkmcnt(0)
	v_mov_b32_e32 v68, v80
	v_mov_b32_e32 v69, v80
	v_mov_b32_e32 v70, v80
	v_mov_b32_e32 v71, v80

; #define LAS __attribute__((address_space(3)))
; __device__ __forceinline__ u32x2 tr16(const LAS unsigned char* p) { return __builtin_bit_cast(u32x2, __builtin_amdgcn_ds_read_tr16_b64_v4i16((LAS v4i16_t*)p)); }
; __device__ __forceinline__ unsigned pkbf(float lo, float hi) { const f32x2_t v = {lo, hi}; const bf16x2_t b = __builtin_convertvector(v, bf16x2_t); return __builtin_bit_cast(unsigned, b); }
; #define MFMA16(a, b, c) __builtin_amdgcn_mfma_f32_16x16x32_bf16((a), (b), (c), 0, 0, 0)
; __device__ __forceinline__ f32x4 mfma16k16(u32x2 a, u32x2 b, f32x4 c) { const u32x4 a4 = {a.x, a.y, 0u, 0u}, b4 = {b.x, b.y, 0u, 0u}; return __builtin_amdgcn_mfma_f32_16x16x32_bf16(__builtin_bit_cast(bf16x8, a4), __builtin_bit_cast(bf16x8, b4), c, 0, 0, 0); }
; template <int NMC>
; __device__ __forceinline__ void hg_chain(LAS unsigned char* L, f32x4 (&S)[8], int w, int r16, int q) {
;     ...
; #pragma unroll
;     for (int mc = 0; mc < NMC; ++mc) {
;         oo[mc] = (f32x4){0.f, 0.f, 0.f, 0.f};
;         {
;             const LAS unsigned char* Qb = L + MX_Q + 16 * mc * MX_PITCH; const LAS unsigned char* Kb = L + MX_K + 16 * mc * MX_PITCH; const LAS unsigned char* Vb = L + MX_V + 16 * mc * MX_PITCH;
;             f32x4 g0 = {0.f, 0.f, 0.f, 0.f}, g1 = {0.f, 0.f, 0.f, 0.f};
; #pragma unroll
;             for (int ks = 0; ks < 4; ++ks) {
;                 const bf16x8 kf = ld8(Kb + r16 * MX_PITCH + (32 * ks + 8 * q) * 2), qf = ld8(Qb + r16 * MX_PITCH + (32 * ks + 8 * q) * 2);
;                 if (ks & 1) g1 = MFMA16(kf, qf, g1); else g0 = MFMA16(kf, qf, g0);
;             }
;             const f32x4 g = g0 + g1;
;             f32x4 P;
; #pragma unroll
;             for (int r = 0; r < 4; ++r) P[r] = (4 * q + r <= r16) ? g[r] : 0.f;
;             const u32x2 vt = tr16(Vb + (4 * q + (r16 >> 2)) * MX_PITCH + (16 * w + 4 * (r16 & 3)) * 2);
;             oo[mc] = mfma16k16((u32x2){pkbf(P[0], P[1]), pkbf(P[2], P[3])}, vt, oo[mc]);
;         }
;         if (mc == 1) __builtin_amdgcn_sched_barrier(0);
.LBB0_887:
	s_sub_i32 s16, s14, 64
	s_cmp_eq_u32 s1, 0
	s_cselect_b64 s[18:19], -1, 0
	s_and_b64 vcc, s[18:19], exec
	s_cselect_b32 s16, 0x4400, s16
	s_cselect_b32 s15, 16, 64
	s_cmpk_lt_i32 s16, 0x4000
	s_mov_b32 s17, 0xa200000
	s_cselect_b32 s17, 0x5900000, s17
	s_add_u32 s22, s94, s17
	s_addc_u32 s23, s95, 0
	s_ashr_i32 s17, s16, 31
	s_lshl_b64 s[20:21], s[16:17], 13
	s_add_u32 s68, s22, s20
	s_addc_u32 s17, s23, s21
	s_lshl_b32 s70, s15, 13
	s_and_b32 s69, s17, 0xffff
	buffer_load_dwordx4 v[32:35], v198, s[68:71], 0 offen
	buffer_load_dwordx4 v[28:31], v199, s[68:71], 0 offen
	ds_read_b128 v[68:71], v235
	ds_read_b128 v[72:75], v235 offset:64
	ds_read_b128 v[100:103], v235 offset:17408
	ds_read_b128 v[104:107], v235 offset:17472
	ds_read_b128 v[76:79], v235 offset:128
	ds_read_b128 v[80:83], v235 offset:192
	ds_read_b128 v[108:111], v235 offset:17536
	ds_read_b128 v[112:115], v235 offset:17600
	s_mov_b64 s[20:21], -1
	v_cvt_pk_bf16_f32 v84, v60, v61
	v_cvt_pk_bf16_f32 v85, v62, v63
	v_cvt_pk_bf16_f32 v86, v64, v65
	v_cvt_pk_bf16_f32 v87, v66, v67
	v_cvt_pk_bf16_f32 v88, v56, v57
	v_cvt_pk_bf16_f32 v89, v58, v59
	v_cvt_pk_bf16_f32 v90, v52, v53
	v_cvt_pk_bf16_f32 v91, v54, v55
	v_cvt_pk_bf16_f32 v92, v48, v49
	v_cvt_pk_bf16_f32 v93, v50, v51
	v_cvt_pk_bf16_f32 v94, v44, v45
	v_cvt_pk_bf16_f32 v95, v46, v47
	v_cvt_pk_bf16_f32 v96, v40, v41
	v_cvt_pk_bf16_f32 v97, v42, v43
	v_cvt_pk_bf16_f32 v98, v36, v37
	v_cvt_pk_bf16_f32 v99, v38, v39
	v_add_u32_e32 v239, v202, v204
	v_add_u32_e32 v238, v202, v205
	s_cbranch_vccnz .LBB0_889
	ds_read_b64_tr_b16 v[240:241], v236 offset:52224
	v_mov_b32_e32 v242, 0
	v_mov_b32_e32 v243, 0
	v_mov_b32_e32 v246, 0
	v_mov_b32_e32 v247, 0
	v_mov_b32_e32 v182, 0
	v_mov_b32_e32 v183, 0
	s_waitcnt lgkmcnt(6)
	v_mfma_f32_16x16x32_bf16 v[168:171], v[100:103], v[68:71], 0
	s_waitcnt lgkmcnt(5)
	v_mfma_f32_16x16x32_bf16 v[172:175], v[104:107], v[72:75], 0
	s_waitcnt lgkmcnt(2)
	v_mfma_f32_16x16x32_bf16 v[168:171], v[108:111], v[76:79], v[168:171]
	s_waitcnt lgkmcnt(1)
	v_mfma_f32_16x16x32_bf16 v[172:175], v[112:115], v[80:83], v[172:175]
	ds_read_b128 v[68:71], v235 offset:4352
	ds_read_b128 v[100:103], v235 offset:21760
	ds_read_b128 v[72:75], v235 offset:4416
	ds_read_b128 v[104:107], v235 offset:21824
	ds_read_b128 v[76:79], v235 offset:4480
	ds_read_b128 v[108:111], v235 offset:21888
	ds_read_b128 v[80:83], v235 offset:4544
	ds_read_b128 v[112:115], v235 offset:21952
	ds_read_b64_tr_b16 v[244:245], v236 offset:56576
	s_waitcnt lgkmcnt(9)
	v_pk_add_f32 v[176:177], v[168:169], v[172:173]
	v_pk_add_f32 v[178:179], v[170:171], v[174:175]
	v_cndmask_b32_e64 v0, v176, 0, s[6:7]
	v_cndmask_b32_e64 v1, 0, v177, s[8:9]
	v_cndmask_b32_e64 v2, v178, 0, s[10:11]
	v_cndmask_b32_e64 v120, v179, 0, s[12:13]
	v_cvt_pk_bf16_f32 v180, v0, v1
	v_cvt_pk_bf16_f32 v181, v2, v120
	s_nop 1
	v_mfma_f32_16x16x32_bf16 v[116:119], v[180:183], v[240:243], 0
	s_waitcnt lgkmcnt(7)
	v_mfma_f32_16x16x32_bf16 v[168:171], v[100:103], v[68:71], 0
	s_waitcnt lgkmcnt(5)
	v_mfma_f32_16x16x32_bf16 v[172:175], v[104:107], v[72:75], 0
	s_waitcnt lgkmcnt(3)
	v_mfma_f32_16x16x32_bf16 v[168:171], v[108:111], v[76:79], v[168:171]
	s_waitcnt lgkmcnt(1)
	v_mfma_f32_16x16x32_bf16 v[172:175], v[112:115], v[80:83], v[172:175]
	ds_read_b128 v[68:71], v235 offset:8704
	ds_read_b128 v[100:103], v235 offset:26112
	ds_read_b128 v[72:75], v235 offset:8768
	ds_read_b128 v[104:107], v235 offset:26176
	ds_read_b128 v[76:79], v235 offset:8832
	ds_read_b128 v[108:111], v235 offset:26240
	ds_read_b128 v[80:83], v235 offset:8896
	ds_read_b128 v[112:115], v235 offset:26304
	ds_read_b64_tr_b16 v[240:241], v236 offset:60928
	s_waitcnt lgkmcnt(9)
	v_pk_add_f32 v[176:177], v[168:169], v[172:173]
	v_pk_add_f32 v[178:179], v[170:171], v[174:175]
	v_cndmask_b32_e64 v0, v176, 0, s[6:7]
	v_cndmask_b32_e64 v1, 0, v177, s[8:9]
	v_cndmask_b32_e64 v2, v178, 0, s[10:11]
	v_cndmask_b32_e64 v120, v179, 0, s[12:13]
	v_cvt_pk_bf16_f32 v180, v0, v1
	v_cvt_pk_bf16_f32 v181, v2, v120
	s_nop 1
	v_mfma_f32_16x16x32_bf16 v[128:131], v[180:183], v[244:247], 0
	s_waitcnt lgkmcnt(7)
	v_mfma_f32_16x16x32_bf16 v[168:171], v[100:103], v[68:71], 0
	s_waitcnt lgkmcnt(5)
	v_mfma_f32_16x16x32_bf16 v[172:175], v[104:107], v[72:75], 0
	s_waitcnt lgkmcnt(3)
	v_mfma_f32_16x16x32_bf16 v[168:171], v[108:111], v[76:79], v[168:171]
	s_waitcnt lgkmcnt(1)
	v_mfma_f32_16x16x32_bf16 v[172:175], v[112:115], v[80:83], v[172:175]
	ds_read_b128 v[68:71], v235 offset:13056
	ds_read_b128 v[100:103], v235 offset:30464
	ds_read_b128 v[72:75], v235 offset:13120
	ds_read_b128 v[104:107], v235 offset:30528
	ds_read_b128 v[76:79], v235 offset:13184
	ds_read_b128 v[108:111], v235 offset:30592
	ds_read_b128 v[80:83], v235 offset:13248
	ds_read_b128 v[112:115], v235 offset:30656
	ds_read_b64_tr_b16 v[244:245], v236 offset:65280
	s_waitcnt lgkmcnt(9)
	v_pk_add_f32 v[176:177], v[168:169], v[172:173]
	v_pk_add_f32 v[178:179], v[170:171], v[174:175]
	v_cndmask_b32_e64 v0, v176, 0, s[6:7]
	v_cndmask_b32_e64 v1, 0, v177, s[8:9]
	v_cndmask_b32_e64 v2, v178, 0, s[10:11]
	v_cndmask_b32_e64 v120, v179, 0, s[12:13]
	v_cvt_pk_bf16_f32 v180, v0, v1
	v_cvt_pk_bf16_f32 v181, v2, v120
	s_nop 1
	v_mfma_f32_16x16x32_bf16 v[136:139], v[180:183], v[240:243], 0
	s_waitcnt lgkmcnt(7)
	v_mfma_f32_16x16x32_bf16 v[168:171], v[100:103], v[68:71], 0
	s_waitcnt lgkmcnt(5)
	v_mfma_f32_16x16x32_bf16 v[172:175], v[104:107], v[72:75], 0
	s_waitcnt lgkmcnt(3)
	v_mfma_f32_16x16x32_bf16 v[168:171], v[108:111], v[76:79], v[168:171]
	s_waitcnt lgkmcnt(1)
	v_mfma_f32_16x16x32_bf16 v[172:175], v[112:115], v[80:83], v[172:175]
	s_waitcnt lgkmcnt(0)
; #define LAS __attribute__((address_space(3)))
; __device__ __forceinline__ u32x2 tr16(const LAS unsigned char* p) { return __builtin_bit_cast(u32x2, __builtin_amdgcn_ds_read_tr16_b64_v4i16((LAS v4i16_t*)p)); }
; __device__ __forceinline__ unsigned pkbf(float lo, float hi) { const f32x2_t v = {lo, hi}; const bf16x2_t b = __builtin_convertvector(v, bf16x2_t); return __builtin_bit_cast(unsigned, b); }
; template <int NMC>
; __device__ __forceinline__ void hg_chain(LAS unsigned char* L, f32x4 (&S)[8], int w, int r16, int q) {
;     ...
;             for (int r = 0; r < 4; ++r) P[r] = (4 * q + r <= r16) ? g[r] : 0.f;
;             const u32x2 vt = tr16(Vb + (4 * q + (r16 >> 2)) * MX_PITCH + (16 * w + 4 * (r16 & 3)) * 2);
;             oo[mc] = mfma16k16((u32x2){pkbf(P[0], P[1]), pkbf(P[2], P[3])}, vt, oo[mc]);
;         }
;         if (mc == 1) __builtin_amdgcn_sched_barrier(0);
;     }
; #pragma unroll
;     for (int mc = 0; mc < NMC; ++mc) {
;         {
;             const LAS unsigned char* Qb = L + MX_Q + 16 * mc * MX_PITCH; const LAS unsigned char* Kb = L + MX_K + 16 * mc * MX_PITCH;
;             const u32x2 vt = tr16(L + MX_V + 16 * mc * MX_PITCH + (4 * q + (r16 >> 2)) * MX_PITCH + (16 * w + 4 * (r16 & 3)) * 2);
;             f32x4 o2b = {0.f, 0.f, 0.f, 0.f};
; #pragma unroll
;             for (int ks = 0; ks < 4; ++ks) {
;                 const bf16x8 qf = ld8(Qb + r16 * MX_PITCH + (32 * ks + 8 * q) * 2);
;                 const bf16x8 SB = mk8(pkbf(S[2 * ks][0], S[2 * ks][1]), pkbf(S[2 * ks][2], S[2 * ks][3]), pkbf(S[2 * ks + 1][0], S[2 * ks + 1][1]), pkbf(S[2 * ks + 1][2], S[2 * ks + 1][3]));
;                 if (ks & 1) o2b = MFMA16(qf, SB, o2b); else oo[mc] = MFMA16(qf, SB, oo[mc]);
;             }
;             oo[mc] = oo[mc] + o2b;
; #pragma unroll
;             for (int mt = 0; mt < 8; ++mt) {
;                 const f32x4 gd = *(const LAS f32x4*)(GD + mc * 128 + 16 * mt + 4 * q);
;                 const u32x2 kt = tr16(Kb + (4 * q + (r16 >> 2)) * MX_PITCH + MX_POS4(16 * mt + 4 * (r16 & 3)) * 2);
;                 S[mt] = mfma16k16(kt, vt, S[mt]); S[mt] = S[mt] * gd;
;             }
;         }
;         if (mc + 1 < NMC) __builtin_amdgcn_sched_barrier(0);
;     }
; #pragma unroll
;     for (int mc = 0; mc < NMC; ++mc) {
;         {
; #pragma unroll
;             for (int r = 0; r < 4; ++r) OB[(16 * mc + 4 * q + r) * MX_OP + 16 * w + r16] = oo[mc][r];
	s_nop 7
	v_pk_add_f32 v[176:177], v[168:169], v[172:173]
	v_pk_add_f32 v[178:179], v[170:171], v[174:175]
	v_cndmask_b32_e64 v0, v176, 0, s[6:7]
	v_cndmask_b32_e64 v1, 0, v177, s[8:9]
	v_cndmask_b32_e64 v2, v178, 0, s[10:11]
	v_cndmask_b32_e64 v120, v179, 0, s[12:13]
	v_cvt_pk_bf16_f32 v180, v0, v1
	v_cvt_pk_bf16_f32 v181, v2, v120
	s_nop 1
	v_mfma_f32_16x16x32_bf16 v[124:127], v[180:183], v[244:247], 0
	v_mov_b32_e32 v102, 0
	v_mov_b32_e32 v103, 0
	v_mov_b32_e32 v106, 0
	v_mov_b32_e32 v107, 0
	v_mov_b32_e32 v110, 0
	v_mov_b32_e32 v111, 0
	v_mov_b32_e32 v114, 0
	v_mov_b32_e32 v115, 0
	v_mov_b32_e32 v142, 0
	v_mov_b32_e32 v143, 0
	v_mov_b32_e32 v146, 0
	v_mov_b32_e32 v147, 0
	v_mov_b32_e32 v150, 0
	v_mov_b32_e32 v151, 0
	v_mov_b32_e32 v154, 0
	v_mov_b32_e32 v155, 0
	v_mov_b32_e32 v246, 0
	v_mov_b32_e32 v247, 0
	v_add_u32_e32 v248, v229, v230
	ds_read_b128 v[68:71], v235 offset:0
	ds_read_b128 v[72:75], v235 offset:64
	ds_read_b128 v[76:79], v235 offset:128
	ds_read_b128 v[80:83], v235 offset:192
	ds_read_b64_tr_b16 v[244:245], v236 offset:52224
	ds_read_b64_tr_b16 v[100:101], v237 offset:17408
	ds_read_b64_tr_b16 v[104:105], v237 offset:17416
	ds_read_b64_tr_b16 v[108:109], v237 offset:17472
	ds_read_b64_tr_b16 v[112:113], v237 offset:17480
	ds_read_b64_tr_b16 v[140:141], v237 offset:17536
	ds_read_b64_tr_b16 v[144:145], v237 offset:17544
	ds_read_b64_tr_b16 v[148:149], v239 offset:17408
	ds_read_b64_tr_b16 v[152:153], v238 offset:17408
	s_waitcnt lgkmcnt(12)
	v_mfma_f32_16x16x32_bf16 v[116:119], v[68:71], v[84:87], v[116:119]
	s_waitcnt lgkmcnt(11)
	v_mfma_f32_16x16x32_bf16 v[120:123], v[72:75], v[88:91], 0
	s_waitcnt lgkmcnt(10)
	v_mfma_f32_16x16x32_bf16 v[116:119], v[76:79], v[92:95], v[116:119]
	s_waitcnt lgkmcnt(9)
	v_mfma_f32_16x16x32_bf16 v[120:123], v[80:83], v[96:99], v[120:123]
	ds_read_b128 v[156:159], v203 offset:0
	ds_read_b128 v[160:163], v203 offset:64
	ds_read_b128 v[164:167], v203 offset:128
	ds_read_b128 v[168:171], v203 offset:192
	s_waitcnt lgkmcnt(11)
	v_mfma_f32_16x16x32_bf16 v[60:63], v[100:103], v[244:247], v[60:63]
	s_waitcnt lgkmcnt(10)
	v_mfma_f32_16x16x32_bf16 v[64:67], v[104:107], v[244:247], v[64:67]
	s_waitcnt lgkmcnt(9)
	v_mfma_f32_16x16x32_bf16 v[56:59], v[108:111], v[244:247], v[56:59]
	s_waitcnt lgkmcnt(8)
	v_mfma_f32_16x16x32_bf16 v[52:55], v[112:115], v[244:247], v[52:55]
	ds_read_b128 v[172:175], v203 offset:256
	ds_read_b128 v[176:179], v203 offset:320
	ds_read_b128 v[180:183], v203 offset:384
	ds_read_b128 v[240:243], v203 offset:448
	s_waitcnt lgkmcnt(11)
	v_mfma_f32_16x16x32_bf16 v[48:51], v[140:143], v[244:247], v[48:51]
	s_waitcnt lgkmcnt(10)
	v_mfma_f32_16x16x32_bf16 v[44:47], v[144:147], v[244:247], v[44:47]
	s_waitcnt lgkmcnt(9)
	v_mfma_f32_16x16x32_bf16 v[40:43], v[148:151], v[244:247], v[40:43]
	s_waitcnt lgkmcnt(8)
	v_mfma_f32_16x16x32_bf16 v[36:39], v[152:155], v[244:247], v[36:39]
	ds_read_b128 v[68:71], v235 offset:4352
	ds_read_b128 v[72:75], v235 offset:4416
	ds_read_b128 v[76:79], v235 offset:4480
	ds_read_b128 v[80:83], v235 offset:4544
	ds_read_b64_tr_b16 v[244:245], v236 offset:56576
	v_pk_add_f32 v[116:117], v[116:117], v[120:121]
	v_pk_add_f32 v[118:119], v[118:119], v[122:123]
	s_waitcnt lgkmcnt(12)
	v_pk_mul_f32 v[60:61], v[156:157], v[60:61]
	v_pk_mul_f32 v[62:63], v[158:159], v[62:63]
	s_waitcnt lgkmcnt(11)
	v_pk_mul_f32 v[64:65], v[160:161], v[64:65]
	v_pk_mul_f32 v[66:67], v[162:163], v[66:67]
	v_add_u32_e32 v222, 1056, v248
	ds_write2_b32 v248, v116, v117 offset1:132
	ds_write2_b32 v222, v118, v119 offset1:132
	s_waitcnt lgkmcnt(12)
	v_pk_mul_f32 v[56:57], v[164:165], v[56:57]
	v_pk_mul_f32 v[58:59], v[166:167], v[58:59]
	s_waitcnt lgkmcnt(11)
	v_pk_mul_f32 v[52:53], v[168:169], v[52:53]
	v_pk_mul_f32 v[54:55], v[170:171], v[54:55]
	s_waitcnt lgkmcnt(10)
	v_pk_mul_f32 v[48:49], v[172:173], v[48:49]
	v_pk_mul_f32 v[50:51], v[174:175], v[50:51]
	s_waitcnt lgkmcnt(9)
	v_pk_mul_f32 v[44:45], v[176:177], v[44:45]
	v_pk_mul_f32 v[46:47], v[178:179], v[46:47]
	s_waitcnt lgkmcnt(8)
	v_pk_mul_f32 v[40:41], v[180:181], v[40:41]
	v_pk_mul_f32 v[42:43], v[182:183], v[42:43]
	s_waitcnt lgkmcnt(7)
	v_pk_mul_f32 v[36:37], v[240:241], v[36:37]
	v_pk_mul_f32 v[38:39], v[242:243], v[38:39]
	ds_read_b64_tr_b16 v[100:101], v237 offset:21760
	ds_read_b64_tr_b16 v[104:105], v237 offset:21768
	ds_read_b64_tr_b16 v[108:109], v237 offset:21824
	ds_read_b64_tr_b16 v[112:113], v237 offset:21832
	ds_read_b64_tr_b16 v[140:141], v237 offset:21888
	ds_read_b64_tr_b16 v[144:145], v237 offset:21896
	ds_read_b64_tr_b16 v[148:149], v239 offset:21760
	ds_read_b64_tr_b16 v[152:153], v238 offset:21760
	v_cvt_pk_bf16_f32 v84, v60, v61
	v_cvt_pk_bf16_f32 v85, v62, v63
	v_cvt_pk_bf16_f32 v86, v64, v65
	v_cvt_pk_bf16_f32 v87, v66, v67
	v_cvt_pk_bf16_f32 v88, v56, v57
	v_cvt_pk_bf16_f32 v89, v58, v59
	v_cvt_pk_bf16_f32 v90, v52, v53
	v_cvt_pk_bf16_f32 v91, v54, v55
	v_cvt_pk_bf16_f32 v92, v48, v49
	v_cvt_pk_bf16_f32 v93, v50, v51
	v_cvt_pk_bf16_f32 v94, v44, v45
	v_cvt_pk_bf16_f32 v95, v46, v47
	v_cvt_pk_bf16_f32 v96, v40, v41
	v_cvt_pk_bf16_f32 v97, v42, v43
	v_cvt_pk_bf16_f32 v98, v36, v37
	v_cvt_pk_bf16_f32 v99, v38, v39
	s_waitcnt lgkmcnt(14)
	v_mfma_f32_16x16x32_bf16 v[128:131], v[68:71], v[84:87], v[128:131]
	s_waitcnt lgkmcnt(13)
	v_mfma_f32_16x16x32_bf16 v[120:123], v[72:75], v[88:91], 0
	s_waitcnt lgkmcnt(12)
	v_mfma_f32_16x16x32_bf16 v[128:131], v[76:79], v[92:95], v[128:131]
	s_waitcnt lgkmcnt(11)
	v_mfma_f32_16x16x32_bf16 v[120:123], v[80:83], v[96:99], v[120:123]
	ds_read_b128 v[156:159], v203 offset:512
	ds_read_b128 v[160:163], v203 offset:576
	ds_read_b128 v[164:167], v203 offset:640
	ds_read_b128 v[168:171], v203 offset:704
	s_waitcnt lgkmcnt(11)
; #define LAS __attribute__((address_space(3)))
; __device__ __forceinline__ u32x2 tr16(const LAS unsigned char* p) { return __builtin_bit_cast(u32x2, __builtin_amdgcn_ds_read_tr16_b64_v4i16((LAS v4i16_t*)p)); }
; __device__ __forceinline__ unsigned pkbf(float lo, float hi) { const f32x2_t v = {lo, hi}; const bf16x2_t b = __builtin_convertvector(v, bf16x2_t); return __builtin_bit_cast(unsigned, b); }
; #define MFMA16(a, b, c) __builtin_amdgcn_mfma_f32_16x16x32_bf16((a), (b), (c), 0, 0, 0)
; __device__ __forceinline__ f32x4 mfma16k16(u32x2 a, u32x2 b, f32x4 c) { const u32x4 a4 = {a.x, a.y, 0u, 0u}, b4 = {b.x, b.y, 0u, 0u}; return __builtin_amdgcn_mfma_f32_16x16x32_bf16(__builtin_bit_cast(bf16x8, a4), __builtin_bit_cast(bf16x8, b4), c, 0, 0, 0); }
; template <int NMC>
; __device__ __forceinline__ void hg_chain(LAS unsigned char* L, f32x4 (&S)[8], int w, int r16, int q) {
;     ...
;     for (int mc = 0; mc < NMC; ++mc) {
;         {
;             const LAS unsigned char* Qb = L + MX_Q + 16 * mc * MX_PITCH; const LAS unsigned char* Kb = L + MX_K + 16 * mc * MX_PITCH;
;             const u32x2 vt = tr16(L + MX_V + 16 * mc * MX_PITCH + (4 * q + (r16 >> 2)) * MX_PITCH + (16 * w + 4 * (r16 & 3)) * 2);
;             f32x4 o2b = {0.f, 0.f, 0.f, 0.f};
; #pragma unroll
;             for (int ks = 0; ks < 4; ++ks) {
;                 const bf16x8 qf = ld8(Qb + r16 * MX_PITCH + (32 * ks + 8 * q) * 2);
;                 const bf16x8 SB = mk8(pkbf(S[2 * ks][0], S[2 * ks][1]), pkbf(S[2 * ks][2], S[2 * ks][3]), pkbf(S[2 * ks + 1][0], S[2 * ks + 1][1]), pkbf(S[2 * ks + 1][2], S[2 * ks + 1][3]));
;                 if (ks & 1) o2b = MFMA16(qf, SB, o2b); else oo[mc] = MFMA16(qf, SB, oo[mc]);
;             }
;             oo[mc] = oo[mc] + o2b;
; #pragma unroll
;             for (int mt = 0; mt < 8; ++mt) {
;                 const f32x4 gd = *(const LAS f32x4*)(GD + mc * 128 + 16 * mt + 4 * q);
;                 const u32x2 kt = tr16(Kb + (4 * q + (r16 >> 2)) * MX_PITCH + MX_POS4(16 * mt + 4 * (r16 & 3)) * 2);
;                 S[mt] = mfma16k16(kt, vt, S[mt]); S[mt] = S[mt] * gd;
;             }
;         }
;         if (mc + 1 < NMC) __builtin_amdgcn_sched_barrier(0);
;     }
; #pragma unroll
;     for (int mc = 0; mc < NMC; ++mc) {
;         {
; #pragma unroll
;             for (int r = 0; r < 4; ++r) OB[(16 * mc + 4 * q + r) * MX_OP + 16 * w + r16] = oo[mc][r];
	v_mfma_f32_16x16x32_bf16 v[60:63], v[100:103], v[244:247], v[60:63]
	s_waitcnt lgkmcnt(10)
	v_mfma_f32_16x16x32_bf16 v[64:67], v[104:107], v[244:247], v[64:67]
	s_waitcnt lgkmcnt(9)
	v_mfma_f32_16x16x32_bf16 v[56:59], v[108:111], v[244:247], v[56:59]
	s_waitcnt lgkmcnt(8)
	v_mfma_f32_16x16x32_bf16 v[52:55], v[112:115], v[244:247], v[52:55]
	ds_read_b128 v[172:175], v203 offset:768
	ds_read_b128 v[176:179], v203 offset:832
	ds_read_b128 v[180:183], v203 offset:896
	ds_read_b128 v[240:243], v203 offset:960
	s_waitcnt lgkmcnt(11)
	v_mfma_f32_16x16x32_bf16 v[48:51], v[140:143], v[244:247], v[48:51]
	s_waitcnt lgkmcnt(10)
	v_mfma_f32_16x16x32_bf16 v[44:47], v[144:147], v[244:247], v[44:47]
	s_waitcnt lgkmcnt(9)
	v_mfma_f32_16x16x32_bf16 v[40:43], v[148:151], v[244:247], v[40:43]
	s_waitcnt lgkmcnt(8)
	v_mfma_f32_16x16x32_bf16 v[36:39], v[152:155], v[244:247], v[36:39]
	ds_read_b128 v[68:71], v235 offset:8704
	ds_read_b128 v[72:75], v235 offset:8768
	ds_read_b128 v[76:79], v235 offset:8832
	ds_read_b128 v[80:83], v235 offset:8896
	ds_read_b64_tr_b16 v[244:245], v236 offset:60928
	v_pk_add_f32 v[128:129], v[128:129], v[120:121]
	v_pk_add_f32 v[130:131], v[130:131], v[122:123]
	s_waitcnt lgkmcnt(12)
	v_pk_mul_f32 v[60:61], v[156:157], v[60:61]
	v_pk_mul_f32 v[62:63], v[158:159], v[62:63]
	s_waitcnt lgkmcnt(11)
	v_pk_mul_f32 v[64:65], v[160:161], v[64:65]
	v_pk_mul_f32 v[66:67], v[162:163], v[66:67]
	v_add_u32_e32 v249, 8448, v248
	v_add_u32_e32 v222, 9504, v248
	ds_write2_b32 v249, v128, v129 offset1:132
	ds_write2_b32 v222, v130, v131 offset1:132
	s_waitcnt lgkmcnt(12)
	v_pk_mul_f32 v[56:57], v[164:165], v[56:57]
	v_pk_mul_f32 v[58:59], v[166:167], v[58:59]
	s_waitcnt lgkmcnt(11)
	v_pk_mul_f32 v[52:53], v[168:169], v[52:53]
	v_pk_mul_f32 v[54:55], v[170:171], v[54:55]
	s_waitcnt lgkmcnt(10)
	v_pk_mul_f32 v[48:49], v[172:173], v[48:49]
	v_pk_mul_f32 v[50:51], v[174:175], v[50:51]
	s_waitcnt lgkmcnt(9)
	v_pk_mul_f32 v[44:45], v[176:177], v[44:45]
	v_pk_mul_f32 v[46:47], v[178:179], v[46:47]
	s_waitcnt lgkmcnt(8)
	v_pk_mul_f32 v[40:41], v[180:181], v[40:41]
	v_pk_mul_f32 v[42:43], v[182:183], v[42:43]
	s_waitcnt lgkmcnt(7)
	v_pk_mul_f32 v[36:37], v[240:241], v[36:37]
	v_pk_mul_f32 v[38:39], v[242:243], v[38:39]
	ds_read_b64_tr_b16 v[100:101], v237 offset:26112
	ds_read_b64_tr_b16 v[104:105], v237 offset:26120
	ds_read_b64_tr_b16 v[108:109], v237 offset:26176
	ds_read_b64_tr_b16 v[112:113], v237 offset:26184
	ds_read_b64_tr_b16 v[140:141], v237 offset:26240
	ds_read_b64_tr_b16 v[144:145], v237 offset:26248
	ds_read_b64_tr_b16 v[148:149], v239 offset:26112
	ds_read_b64_tr_b16 v[152:153], v238 offset:26112
	v_cvt_pk_bf16_f32 v84, v60, v61
	v_cvt_pk_bf16_f32 v85, v62, v63
	v_cvt_pk_bf16_f32 v86, v64, v65
	v_cvt_pk_bf16_f32 v87, v66, v67
	v_cvt_pk_bf16_f32 v88, v56, v57
	v_cvt_pk_bf16_f32 v89, v58, v59
	v_cvt_pk_bf16_f32 v90, v52, v53
	v_cvt_pk_bf16_f32 v91, v54, v55
	v_cvt_pk_bf16_f32 v92, v48, v49
	v_cvt_pk_bf16_f32 v93, v50, v51
	v_cvt_pk_bf16_f32 v94, v44, v45
	v_cvt_pk_bf16_f32 v95, v46, v47
	v_cvt_pk_bf16_f32 v96, v40, v41
	v_cvt_pk_bf16_f32 v97, v42, v43
	v_cvt_pk_bf16_f32 v98, v36, v37
	v_cvt_pk_bf16_f32 v99, v38, v39
	s_waitcnt lgkmcnt(14)
	v_mfma_f32_16x16x32_bf16 v[136:139], v[68:71], v[84:87], v[136:139]
	s_waitcnt lgkmcnt(13)
	v_mfma_f32_16x16x32_bf16 v[120:123], v[72:75], v[88:91], 0
	s_waitcnt lgkmcnt(12)
	v_mfma_f32_16x16x32_bf16 v[136:139], v[76:79], v[92:95], v[136:139]
	s_waitcnt lgkmcnt(11)
	v_mfma_f32_16x16x32_bf16 v[120:123], v[80:83], v[96:99], v[120:123]
	ds_read_b128 v[156:159], v203 offset:1024
	ds_read_b128 v[160:163], v203 offset:1088
	ds_read_b128 v[164:167], v203 offset:1152
	ds_read_b128 v[168:171], v203 offset:1216
	s_waitcnt lgkmcnt(11)
	v_mfma_f32_16x16x32_bf16 v[60:63], v[100:103], v[244:247], v[60:63]
	s_waitcnt lgkmcnt(10)
	v_mfma_f32_16x16x32_bf16 v[64:67], v[104:107], v[244:247], v[64:67]
	s_waitcnt lgkmcnt(9)
	v_mfma_f32_16x16x32_bf16 v[56:59], v[108:111], v[244:247], v[56:59]
	s_waitcnt lgkmcnt(8)
	v_mfma_f32_16x16x32_bf16 v[52:55], v[112:115], v[244:247], v[52:55]
	ds_read_b128 v[172:175], v203 offset:1280
	ds_read_b128 v[176:179], v203 offset:1344
	ds_read_b128 v[180:183], v203 offset:1408
	ds_read_b128 v[240:243], v203 offset:1472
	s_waitcnt lgkmcnt(11)
	v_mfma_f32_16x16x32_bf16 v[48:51], v[140:143], v[244:247], v[48:51]
	s_waitcnt lgkmcnt(10)
	v_mfma_f32_16x16x32_bf16 v[44:47], v[144:147], v[244:247], v[44:47]
	s_waitcnt lgkmcnt(9)
	v_mfma_f32_16x16x32_bf16 v[40:43], v[148:151], v[244:247], v[40:43]
	s_waitcnt lgkmcnt(8)
	v_mfma_f32_16x16x32_bf16 v[36:39], v[152:155], v[244:247], v[36:39]
	ds_read_b128 v[68:71], v235 offset:13056
	ds_read_b128 v[72:75], v235 offset:13120
	ds_read_b128 v[76:79], v235 offset:13184
	ds_read_b128 v[80:83], v235 offset:13248
	ds_read_b64_tr_b16 v[244:245], v236 offset:65280
	v_pk_add_f32 v[136:137], v[136:137], v[120:121]
	v_pk_add_f32 v[138:139], v[138:139], v[122:123]
	s_waitcnt lgkmcnt(12)
	v_pk_mul_f32 v[60:61], v[156:157], v[60:61]
	v_pk_mul_f32 v[62:63], v[158:159], v[62:63]
	s_waitcnt lgkmcnt(11)
; #define LAS __attribute__((address_space(3)))
; __device__ __forceinline__ u32x2 tr16(const LAS unsigned char* p) { return __builtin_bit_cast(u32x2, __builtin_amdgcn_ds_read_tr16_b64_v4i16((LAS v4i16_t*)p)); }
; __device__ __forceinline__ unsigned pkbf(float lo, float hi) { const f32x2_t v = {lo, hi}; const bf16x2_t b = __builtin_convertvector(v, bf16x2_t); return __builtin_bit_cast(unsigned, b); }
; #define MFMA16(a, b, c) __builtin_amdgcn_mfma_f32_16x16x32_bf16((a), (b), (c), 0, 0, 0)
; __device__ __forceinline__ f32x4 mfma16k16(u32x2 a, u32x2 b, f32x4 c) { const u32x4 a4 = {a.x, a.y, 0u, 0u}, b4 = {b.x, b.y, 0u, 0u}; return __builtin_amdgcn_mfma_f32_16x16x32_bf16(__builtin_bit_cast(bf16x8, a4), __builtin_bit_cast(bf16x8, b4), c, 0, 0, 0); }
; template <int NMC>
; __device__ __forceinline__ void hg_chain(LAS unsigned char* L, f32x4 (&S)[8], int w, int r16, int q) {
;     ...
;     for (int mc = 0; mc < NMC; ++mc) {
;         {
;             const LAS unsigned char* Qb = L + MX_Q + 16 * mc * MX_PITCH; const LAS unsigned char* Kb = L + MX_K + 16 * mc * MX_PITCH;
;             const u32x2 vt = tr16(L + MX_V + 16 * mc * MX_PITCH + (4 * q + (r16 >> 2)) * MX_PITCH + (16 * w + 4 * (r16 & 3)) * 2);
;             f32x4 o2b = {0.f, 0.f, 0.f, 0.f};
; #pragma unroll
;             for (int ks = 0; ks < 4; ++ks) {
;                 const bf16x8 qf = ld8(Qb + r16 * MX_PITCH + (32 * ks + 8 * q) * 2);
;                 const bf16x8 SB = mk8(pkbf(S[2 * ks][0], S[2 * ks][1]), pkbf(S[2 * ks][2], S[2 * ks][3]), pkbf(S[2 * ks + 1][0], S[2 * ks + 1][1]), pkbf(S[2 * ks + 1][2], S[2 * ks + 1][3]));
;                 if (ks & 1) o2b = MFMA16(qf, SB, o2b); else oo[mc] = MFMA16(qf, SB, oo[mc]);
;             }
;             oo[mc] = oo[mc] + o2b;
; #pragma unroll
;             for (int mt = 0; mt < 8; ++mt) {
;                 const f32x4 gd = *(const LAS f32x4*)(GD + mc * 128 + 16 * mt + 4 * q);
;                 const u32x2 kt = tr16(Kb + (4 * q + (r16 >> 2)) * MX_PITCH + MX_POS4(16 * mt + 4 * (r16 & 3)) * 2);
;                 S[mt] = mfma16k16(kt, vt, S[mt]); S[mt] = S[mt] * gd;
;             }
;         }
;         if (mc + 1 < NMC) __builtin_amdgcn_sched_barrier(0);
;     }
; #pragma unroll
;     for (int mc = 0; mc < NMC; ++mc) {
;         {
; #pragma unroll
;             for (int r = 0; r < 4; ++r) OB[(16 * mc + 4 * q + r) * MX_OP + 16 * w + r16] = oo[mc][r];
	v_pk_mul_f32 v[64:65], v[160:161], v[64:65]
	v_pk_mul_f32 v[66:67], v[162:163], v[66:67]
	v_add_u32_e32 v249, 16896, v248
	v_add_u32_e32 v222, 17952, v248
	ds_write2_b32 v249, v136, v137 offset1:132
	ds_write2_b32 v222, v138, v139 offset1:132
	s_waitcnt lgkmcnt(12)
	v_pk_mul_f32 v[56:57], v[164:165], v[56:57]
	v_pk_mul_f32 v[58:59], v[166:167], v[58:59]
	s_waitcnt lgkmcnt(11)
	v_pk_mul_f32 v[52:53], v[168:169], v[52:53]
	v_pk_mul_f32 v[54:55], v[170:171], v[54:55]
	s_waitcnt lgkmcnt(10)
	v_pk_mul_f32 v[48:49], v[172:173], v[48:49]
	v_pk_mul_f32 v[50:51], v[174:175], v[50:51]
	s_waitcnt lgkmcnt(9)
	v_pk_mul_f32 v[44:45], v[176:177], v[44:45]
	v_pk_mul_f32 v[46:47], v[178:179], v[46:47]
	s_waitcnt lgkmcnt(8)
	v_pk_mul_f32 v[40:41], v[180:181], v[40:41]
	v_pk_mul_f32 v[42:43], v[182:183], v[42:43]
	s_waitcnt lgkmcnt(7)
	v_pk_mul_f32 v[36:37], v[240:241], v[36:37]
	v_pk_mul_f32 v[38:39], v[242:243], v[38:39]
	ds_read_b64_tr_b16 v[100:101], v237 offset:30464
	ds_read_b64_tr_b16 v[104:105], v237 offset:30472
	ds_read_b64_tr_b16 v[108:109], v237 offset:30528
	ds_read_b64_tr_b16 v[112:113], v237 offset:30536
	ds_read_b64_tr_b16 v[140:141], v237 offset:30592
	ds_read_b64_tr_b16 v[144:145], v237 offset:30600
	ds_read_b64_tr_b16 v[148:149], v239 offset:30464
	ds_read_b64_tr_b16 v[152:153], v238 offset:30464
	v_cvt_pk_bf16_f32 v84, v60, v61
	v_cvt_pk_bf16_f32 v85, v62, v63
	v_cvt_pk_bf16_f32 v86, v64, v65
	v_cvt_pk_bf16_f32 v87, v66, v67
	v_cvt_pk_bf16_f32 v88, v56, v57
	v_cvt_pk_bf16_f32 v89, v58, v59
	v_cvt_pk_bf16_f32 v90, v52, v53
	v_cvt_pk_bf16_f32 v91, v54, v55
	v_cvt_pk_bf16_f32 v92, v48, v49
	v_cvt_pk_bf16_f32 v93, v50, v51
	v_cvt_pk_bf16_f32 v94, v44, v45
	v_cvt_pk_bf16_f32 v95, v46, v47
	v_cvt_pk_bf16_f32 v96, v40, v41
	v_cvt_pk_bf16_f32 v97, v42, v43
	v_cvt_pk_bf16_f32 v98, v36, v37
	v_cvt_pk_bf16_f32 v99, v38, v39
	s_waitcnt lgkmcnt(14)
	v_mfma_f32_16x16x32_bf16 v[124:127], v[68:71], v[84:87], v[124:127]
	s_waitcnt lgkmcnt(13)
	v_mfma_f32_16x16x32_bf16 v[120:123], v[72:75], v[88:91], 0
	s_waitcnt lgkmcnt(12)
	v_mfma_f32_16x16x32_bf16 v[124:127], v[76:79], v[92:95], v[124:127]
	s_waitcnt lgkmcnt(11)
	v_mfma_f32_16x16x32_bf16 v[120:123], v[80:83], v[96:99], v[120:123]
	ds_read_b128 v[156:159], v203 offset:1536
	ds_read_b128 v[160:163], v203 offset:1600
	ds_read_b128 v[164:167], v203 offset:1664
	ds_read_b128 v[168:171], v203 offset:1728
	s_waitcnt lgkmcnt(11)
	v_mfma_f32_16x16x32_bf16 v[60:63], v[100:103], v[244:247], v[60:63]
	s_waitcnt lgkmcnt(10)
	v_mfma_f32_16x16x32_bf16 v[64:67], v[104:107], v[244:247], v[64:67]
	s_waitcnt lgkmcnt(9)
	v_mfma_f32_16x16x32_bf16 v[56:59], v[108:111], v[244:247], v[56:59]
	s_waitcnt lgkmcnt(8)
	v_mfma_f32_16x16x32_bf16 v[52:55], v[112:115], v[244:247], v[52:55]
	ds_read_b128 v[172:175], v203 offset:1792
	ds_read_b128 v[176:179], v203 offset:1856
	ds_read_b128 v[180:183], v203 offset:1920
	ds_read_b128 v[240:243], v203 offset:1984
	s_waitcnt lgkmcnt(11)
	v_mfma_f32_16x16x32_bf16 v[48:51], v[140:143], v[244:247], v[48:51]
	s_waitcnt lgkmcnt(10)
	v_mfma_f32_16x16x32_bf16 v[44:47], v[144:147], v[244:247], v[44:47]
	s_waitcnt lgkmcnt(9)
	v_mfma_f32_16x16x32_bf16 v[40:43], v[148:151], v[244:247], v[40:43]
	s_waitcnt lgkmcnt(8)
	v_mfma_f32_16x16x32_bf16 v[36:39], v[152:155], v[244:247], v[36:39]
	v_pk_add_f32 v[124:125], v[124:125], v[120:121]
	v_pk_add_f32 v[126:127], v[126:127], v[122:123]
	s_waitcnt lgkmcnt(7)
	v_pk_mul_f32 v[60:61], v[156:157], v[60:61]
	v_pk_mul_f32 v[62:63], v[158:159], v[62:63]
	s_waitcnt lgkmcnt(6)
	v_pk_mul_f32 v[64:65], v[160:161], v[64:65]
	v_pk_mul_f32 v[66:67], v[162:163], v[66:67]
	v_add_u32_e32 v249, 25344, v248
	v_add_u32_e32 v222, 26400, v248
	ds_write2_b32 v249, v124, v125 offset1:132
	ds_write2_b32 v222, v126, v127 offset1:132
	s_waitcnt lgkmcnt(7)
	v_pk_mul_f32 v[56:57], v[164:165], v[56:57]
	v_pk_mul_f32 v[58:59], v[166:167], v[58:59]
	s_waitcnt lgkmcnt(6)
	v_pk_mul_f32 v[52:53], v[168:169], v[52:53]
	v_pk_mul_f32 v[54:55], v[170:171], v[54:55]
	s_waitcnt lgkmcnt(5)
	v_pk_mul_f32 v[48:49], v[172:173], v[48:49]
	v_pk_mul_f32 v[50:51], v[174:175], v[50:51]
	s_waitcnt lgkmcnt(4)
	v_pk_mul_f32 v[44:45], v[176:177], v[44:45]
	v_pk_mul_f32 v[46:47], v[178:179], v[46:47]
	s_waitcnt lgkmcnt(3)
	v_pk_mul_f32 v[40:41], v[180:181], v[40:41]
	v_pk_mul_f32 v[42:43], v[182:183], v[42:43]
	s_waitcnt lgkmcnt(2)
	v_pk_mul_f32 v[36:37], v[240:241], v[36:37]
	v_pk_mul_f32 v[38:39], v[242:243], v[38:39]
	v_mov_b32_e32 v150, v60
	v_mov_b32_e32 v151, v61
	v_mov_b32_e32 v148, v62
	v_mov_b32_e32 v149, v63
	v_mov_b32_e32 v146, v64
	v_mov_b32_e32 v147, v65
	v_mov_b32_e32 v144, v66
	v_mov_b32_e32 v145, v67
	v_mov_b32_e32 v174, v56
	v_mov_b32_e32 v175, v57
	v_mov_b32_e32 v172, v58
	v_mov_b32_e32 v173, v59
	v_mov_b32_e32 v170, v52
	v_mov_b32_e32 v171, v53
	v_mov_b32_e32 v168, v54
	v_mov_b32_e32 v169, v55
	v_mov_b32_e32 v166, v48
	v_mov_b32_e32 v167, v49
	v_mov_b32_e32 v164, v50
	v_mov_b32_e32 v165, v51
	v_mov_b32_e32 v162, v44
	v_mov_b32_e32 v163, v45
	v_mov_b32_e32 v160, v46
	v_mov_b32_e32 v161, v47
	v_mov_b32_e32 v154, v40
	v_mov_b32_e32 v155, v41
	v_mov_b32_e32 v152, v42
	v_mov_b32_e32 v153, v43
	v_mov_b32_e32 v156, v36
	v_mov_b32_e32 v157, v37
	v_mov_b32_e32 v0, v38
	v_mov_b32_e32 v1, v39
	s_mov_b64 s[20:21], 0
